# R3 retention outputs: prefetch gate/rnorm loads early, dual-issue decay loads; Swiglu+gate epilogues: parallel rstd butterfly
# baseline (speedup 1.0000x reference)
.LBB0_174:
	s_and_b32 s14, s81, 3
	s_lshl_b32 s74, s14, 2
	v_mov_b32_e32 v18, s74
	global_load_dword v2, v18, s[82:83]
	global_load_dword v193, v18, s[96:97]
	s_mov_b32 s84, 0x3fb8aa3b
	s_mov_b32 s2, 0xc2ce8ed0
	s_mov_b32 s93, 0x42b17218
	s_mov_b32 s16, 0x3f2aaaab
	s_mov_b32 s17, 0x3f317218
	s_mov_b32 s18, 0x33800000
	s_and_b32 s15, s3, 0xffffff80
	v_lshl_add_u64 v[20:21], v[46:47], 0, v[44:45]
	v_add_u32_e32 v24, s15, v83
	v_ashrrev_i32_e32 v25, 31, v24
	v_lshlrev_b64 v[28:29], 9, v[24:25]
	v_add_u32_e32 v188, 0x9000, v176
	s_add_i32 s81, s81, s80
	s_add_i32 s3, s3, s63
	s_waitcnt vmcnt(1)
	v_mul_f32_e32 v3, 0x3fb8aa3b, v2
	v_fma_f32 v4, v2, s84, -v3
	v_rndne_f32_e32 v5, v3
	v_fmac_f32_e32 v4, 0x32a5705f, v2
	v_sub_f32_e32 v3, v3, v5
	v_add_f32_e32 v3, v3, v4
	v_exp_f32_e32 v3, v3
	v_cvt_i32_f32_e32 v4, v5
	v_cmp_ngt_f32_e32 vcc, s2, v2
	v_ldexp_f32 v3, v3, v4
	s_nop 0
	v_cndmask_b32_e32 v3, 0, v3, vcc
	v_cmp_nlt_f32_e32 vcc, s93, v2
	s_nop 1
	v_cndmask_b32_e32 v19, v245, v3, vcc
	v_sub_f32_e32 v4, 1.0, v19
	v_add_f32_e32 v2, -1.0, v4
	v_sub_f32_e32 v3, v2, v4
	v_add_f32_e32 v3, 1.0, v3
	v_sub_f32_e64 v2, -v19, v2
	v_add_f32_e32 v5, v2, v3
	v_frexp_mant_f32_e32 v2, v4
	v_cmp_gt_f32_e32 vcc, s16, v2
	v_cvt_f64_f32_e32 v[2:3], v4
	v_frexp_exp_i32_f64_e32 v2, v[2:3]
	v_subbrev_co_u32_e32 v10, vcc, 0, v2, vcc
	v_sub_u32_e32 v2, 0, v10
	v_ldexp_f32 v3, v4, v2
	v_add_f32_e32 v4, -1.0, v3
	v_add_f32_e32 v6, 1.0, v3
	v_ldexp_f32 v2, v5, v2
	v_add_f32_e32 v5, 1.0, v4
	v_add_f32_e32 v7, -1.0, v6
	v_sub_f32_e32 v5, v3, v5
	v_sub_f32_e32 v3, v3, v7
	v_add_f32_e32 v5, v2, v5
	v_add_f32_e32 v2, v2, v3
	v_add_f32_e32 v11, v6, v2
	v_rcp_f32_e32 v13, v11
	v_sub_f32_e32 v3, v11, v6
	v_sub_f32_e32 v12, v2, v3
	v_add_f32_e32 v3, v4, v5
	v_mul_f32_e32 v15, v3, v13
	v_sub_f32_e32 v2, v3, v4
	v_mul_f32_e32 v4, v11, v15
	v_fma_f32 v6, v15, v11, -v4
	v_fmac_f32_e32 v6, v15, v12
	v_sub_f32_e32 v14, v5, v2
	v_add_f32_e32 v2, v4, v6
	v_sub_f32_e32 v5, v3, v2
	v_pk_add_f32 v[8:9], v[2:3], v[4:5] neg_lo:[0,1] neg_hi:[0,1]
	v_mov_b32_e32 v7, v2
	v_pk_add_f32 v[2:3], v[8:9], v[6:7] neg_lo:[0,1] neg_hi:[0,1]
	v_cmp_nlt_f32_e32 vcc, 1.0, v19
	v_add_f32_e32 v3, v14, v3
	v_add_f32_e32 v2, v2, v3
	v_add_f32_e32 v3, v5, v2
	v_mul_f32_e32 v14, v13, v3
	v_mul_f32_e32 v4, v11, v14
	v_fma_f32 v6, v14, v11, -v4
	v_fmac_f32_e32 v6, v14, v12
	v_sub_f32_e32 v5, v5, v3
	v_add_f32_e32 v11, v2, v5
	v_add_f32_e32 v2, v4, v6
	v_sub_f32_e32 v5, v3, v2
	v_pk_add_f32 v[8:9], v[2:3], v[4:5] neg_lo:[0,1] neg_hi:[0,1]
	v_mov_b32_e32 v7, v2
	v_pk_add_f32 v[2:3], v[8:9], v[6:7] neg_lo:[0,1] neg_hi:[0,1]
	v_cmp_lt_f32_e64 s[74:75], |v19|, s18
	v_add_f32_e32 v3, v11, v3
	v_add_f32_e32 v2, v2, v3
	v_add_f32_e32 v3, v15, v14
	v_add_f32_e32 v2, v5, v2
	v_sub_f32_e32 v4, v3, v15
	v_mul_f32_e32 v2, v13, v2
	v_sub_f32_e32 v4, v14, v4
	v_add_f32_e32 v4, v4, v2
	v_add_f32_e32 v6, v3, v4
	v_mul_f32_e32 v7, v6, v6
	v_fmamk_f32 v2, v7, 0x3e9b6dac, v237
	v_fmaak_f32 v191, v7, v2, 0x3f2aaada
	v_cvt_f32_i32_e32 v2, v10
	v_sub_f32_e32 v3, v6, v3
	v_sub_f32_e32 v3, v4, v3
	v_ldexp_f32 v8, v3, 1
	v_mul_f32_e32 v3, v6, v7
	v_ldexp_f32 v5, v6, 1
	v_pk_mul_f32 v[6:7], v[2:3], v[190:191]
	s_nop 0
	v_fma_f32 v4, v2, s17, -v6
	v_fmac_f32_e32 v4, 0xb102e308, v2
	v_pk_add_f32 v[2:3], v[6:7], v[4:5]
	s_nop 0
	v_sub_f32_e32 v5, v3, v5
	v_sub_f32_e32 v5, v7, v5
	v_add_f32_e32 v9, v8, v5
	v_mov_b32_e32 v8, v6
	v_pk_add_f32 v[6:7], v[2:3], v[6:7] neg_lo:[0,1] neg_hi:[0,1]
	v_pk_add_f32 v[10:11], v[2:3], v[8:9]
	v_mov_b32_e32 v5, v2
	v_mov_b32_e32 v7, v11
	v_pk_add_f32 v[12:13], v[4:5], v[6:7] neg_lo:[0,1] neg_hi:[0,1]
	v_pk_add_f32 v[4:5], v[4:5], v[6:7]
	v_mov_b32_e32 v16, v3
	v_pk_add_f32 v[6:7], v[4:5], v[2:3] op_sel:[1,0] op_sel_hi:[0,1] neg_lo:[0,1] neg_hi:[0,1]
	v_pk_add_f32 v[14:15], v[10:11], v[6:7] op_sel_hi:[1,0] neg_lo:[0,1] neg_hi:[0,1]
	v_mov_b32_e32 v10, v11
	v_mov_b32_e32 v11, v5
	v_mov_b32_e32 v17, v6
	v_pk_add_f32 v[6:7], v[10:11], v[16:17] neg_lo:[0,1] neg_hi:[0,1]
	v_mov_b32_e32 v8, v9
	v_mov_b32_e32 v9, v2
	v_pk_add_f32 v[2:3], v[8:9], v[6:7] neg_lo:[0,1] neg_hi:[0,1]
	v_mov_b32_e32 v14, v12
	v_pk_add_f32 v[6:7], v[14:15], v[2:3]
	v_mov_b32_e32 v13, v5
	v_pk_add_f32 v[8:9], v[6:7], v[6:7] op_sel:[0,1] op_sel_hi:[1,0]
	s_nop 0
	v_pk_add_f32 v[4:5], v[4:5], v[8:9] op_sel:[1,0] op_sel_hi:[0,1]
	v_mov_b32_e32 v7, v4
	v_pk_add_f32 v[10:11], v[6:7], v[12:13] neg_lo:[0,1] neg_hi:[0,1]
	v_mov_b32_e32 v3, v8
	v_sub_f32_e32 v5, v6, v10
	v_pk_add_f32 v[2:3], v[2:3], v[10:11] neg_lo:[0,1] neg_hi:[0,1]
	v_sub_f32_e32 v5, v12, v5
	v_add_f32_e32 v2, v2, v5
	v_add_f32_e32 v2, v2, v3
	v_add_f32_e32 v2, v4, v2
	v_cndmask_b32_e32 v2, v241, v2, vcc
	v_cmp_neq_f32_e32 vcc, 1.0, v19
	s_nop 1
	v_cndmask_b32_e32 v2, v238, v2, vcc
	v_cndmask_b32_e64 v15, v2, -v19, s[74:75]
	s_waitcnt vmcnt(0)
	v_mov_b32_e32 v2, v193
	v_mul_f32_e32 v3, 0x3fb8aa3b, v2
	v_fma_f32 v4, v2, s84, -v3
	v_rndne_f32_e32 v5, v3
	v_fmac_f32_e32 v4, 0x32a5705f, v2
	v_sub_f32_e32 v3, v3, v5
	v_add_f32_e32 v3, v3, v4
	v_exp_f32_e32 v3, v3
	v_cvt_i32_f32_e32 v4, v5
	v_cmp_ngt_f32_e32 vcc, s2, v2
	s_lshl_b32 s84, s14, 7
	s_mov_b32 s2, 0x1c804000
	v_ldexp_f32 v3, v3, v4
	v_cndmask_b32_e32 v3, 0, v3, vcc
	v_cmp_nlt_f32_e32 vcc, s93, v2
	s_nop 1
	v_cndmask_b32_e32 v14, v245, v3, vcc
	v_sub_f32_e32 v4, 1.0, v14
	v_add_f32_e32 v2, -1.0, v4
	v_sub_f32_e32 v3, v2, v4
	v_add_f32_e32 v3, 1.0, v3
	v_sub_f32_e64 v2, -v14, v2
	v_add_f32_e32 v5, v2, v3
	v_frexp_mant_f32_e32 v2, v4
	v_cmp_gt_f32_e32 vcc, s16, v2
	v_cvt_f64_f32_e32 v[2:3], v4
	v_frexp_exp_i32_f64_e32 v2, v[2:3]
	v_subbrev_co_u32_e32 v10, vcc, 0, v2, vcc
	v_sub_u32_e32 v2, 0, v10
	v_ldexp_f32 v3, v4, v2
	v_add_f32_e32 v4, -1.0, v3
	v_add_f32_e32 v6, 1.0, v3
	v_ldexp_f32 v2, v5, v2
	v_add_f32_e32 v5, 1.0, v4
	v_add_f32_e32 v7, -1.0, v6
	v_sub_f32_e32 v5, v3, v5
	v_sub_f32_e32 v3, v3, v7
	v_add_f32_e32 v5, v2, v5
	v_add_f32_e32 v2, v2, v3
	v_add_f32_e32 v11, v6, v2
	v_rcp_f32_e32 v13, v11
	v_sub_f32_e32 v3, v11, v6
	v_sub_f32_e32 v12, v2, v3
	v_add_f32_e32 v3, v4, v5
	v_mul_f32_e32 v17, v3, v13
	v_sub_f32_e32 v2, v3, v4
	v_mul_f32_e32 v4, v11, v17
	v_fma_f32 v6, v17, v11, -v4
	v_fmac_f32_e32 v6, v17, v12
	v_sub_f32_e32 v16, v5, v2
	v_add_f32_e32 v2, v4, v6
	v_sub_f32_e32 v5, v3, v2
	v_pk_add_f32 v[8:9], v[2:3], v[4:5] neg_lo:[0,1] neg_hi:[0,1]
	v_mov_b32_e32 v7, v2
	v_pk_add_f32 v[2:3], v[8:9], v[6:7] neg_lo:[0,1] neg_hi:[0,1]
	v_cmp_nlt_f32_e32 vcc, 1.0, v14
	v_add_f32_e32 v3, v16, v3
	v_add_f32_e32 v2, v2, v3
	v_add_f32_e32 v3, v5, v2
	v_mul_f32_e32 v16, v13, v3
	v_mul_f32_e32 v4, v11, v16
	v_fma_f32 v6, v16, v11, -v4
	v_fmac_f32_e32 v6, v16, v12
	v_sub_f32_e32 v5, v5, v3
	v_add_f32_e32 v11, v2, v5
	v_add_f32_e32 v2, v4, v6
	v_sub_f32_e32 v5, v3, v2
	v_pk_add_f32 v[8:9], v[2:3], v[4:5] neg_lo:[0,1] neg_hi:[0,1]
	v_mov_b32_e32 v7, v2
	v_pk_add_f32 v[2:3], v[8:9], v[6:7] neg_lo:[0,1] neg_hi:[0,1]
	v_cmp_lt_f32_e64 s[74:75], |v14|, s18
	v_add_f32_e32 v3, v11, v3
	v_add_f32_e32 v2, v2, v3
	v_add_f32_e32 v3, v17, v16
	v_add_f32_e32 v2, v5, v2
	v_sub_f32_e32 v4, v3, v17
	v_mul_f32_e32 v2, v13, v2
	v_sub_f32_e32 v4, v16, v4
	v_add_f32_e32 v4, v4, v2
	v_add_f32_e32 v6, v3, v4
	v_mul_f32_e32 v7, v6, v6
	v_fmamk_f32 v2, v7, 0x3e9b6dac, v237
	v_fmaak_f32 v191, v7, v2, 0x3f2aaada
	v_cvt_f32_i32_e32 v2, v10
	v_sub_f32_e32 v3, v6, v3
	v_sub_f32_e32 v3, v4, v3
	v_ldexp_f32 v8, v3, 1
	v_mul_f32_e32 v3, v6, v7
	v_ldexp_f32 v5, v6, 1
	v_pk_mul_f32 v[6:7], v[2:3], v[190:191]
	s_nop 0
	v_fma_f32 v4, v2, s17, -v6
	v_fmac_f32_e32 v4, 0xb102e308, v2
	v_pk_add_f32 v[2:3], v[6:7], v[4:5]
	v_readlane_b32 s16, v255, 30
	v_sub_f32_e32 v5, v3, v5
	v_sub_f32_e32 v5, v7, v5
	v_add_f32_e32 v9, v8, v5
	v_mov_b32_e32 v8, v6
	v_pk_add_f32 v[6:7], v[2:3], v[6:7] neg_lo:[0,1] neg_hi:[0,1]
	v_pk_add_f32 v[10:11], v[2:3], v[8:9]
	v_mov_b32_e32 v5, v2
	v_mov_b32_e32 v7, v11
	v_pk_add_f32 v[12:13], v[4:5], v[6:7] neg_lo:[0,1] neg_hi:[0,1]
	v_pk_add_f32 v[4:5], v[4:5], v[6:7]
	v_mov_b32_e32 v18, v3
	v_pk_add_f32 v[6:7], v[4:5], v[2:3] op_sel:[1,0] op_sel_hi:[0,1] neg_lo:[0,1] neg_hi:[0,1]
	v_pk_add_f32 v[16:17], v[10:11], v[6:7] op_sel_hi:[1,0] neg_lo:[0,1] neg_hi:[0,1]
	v_mov_b32_e32 v10, v11
	v_mov_b32_e32 v11, v5
	v_mov_b32_e32 v19, v6
	v_pk_add_f32 v[6:7], v[10:11], v[18:19] neg_lo:[0,1] neg_hi:[0,1]
	v_mov_b32_e32 v8, v9
	v_mov_b32_e32 v9, v2
	v_pk_add_f32 v[2:3], v[8:9], v[6:7] neg_lo:[0,1] neg_hi:[0,1]
	v_mov_b32_e32 v16, v12
	v_pk_add_f32 v[6:7], v[16:17], v[2:3]
	v_mov_b32_e32 v13, v5
	v_pk_add_f32 v[8:9], v[6:7], v[6:7] op_sel:[0,1] op_sel_hi:[1,0]
	v_readlane_b32 s17, v255, 31
	v_pk_add_f32 v[4:5], v[4:5], v[8:9] op_sel:[1,0] op_sel_hi:[0,1]
	v_mov_b32_e32 v7, v4
	v_pk_add_f32 v[10:11], v[6:7], v[12:13] neg_lo:[0,1] neg_hi:[0,1]
	v_mov_b32_e32 v3, v8
	v_sub_f32_e32 v5, v6, v10
	v_pk_add_f32 v[2:3], v[2:3], v[10:11] neg_lo:[0,1] neg_hi:[0,1]
	v_sub_f32_e32 v5, v12, v5
	v_add_f32_e32 v2, v2, v5
	v_add_f32_e32 v2, v2, v3
	v_add_f32_e32 v2, v4, v2
	v_cndmask_b32_e32 v2, v241, v2, vcc
	v_cmp_neq_f32_e32 vcc, 1.0, v14
	v_lshl_add_u64 v[12:13], v[30:31], 0, s[84:85]
	v_lshl_add_u64 v[10:11], v[32:33], 0, s[84:85]
	v_cndmask_b32_e32 v2, v238, v2, vcc
	v_cndmask_b32_e64 v14, v2, -v14, s[74:75]
	v_add_u32_e32 v2, s15, v82
	v_ashrrev_i32_e32 v3, 31, v2
	v_lshlrev_b64 v[6:7], 9, v[2:3]
	v_lshl_add_u64 v[2:3], v[12:13], 0, v[6:7]
	global_load_dwordx4 v[2:5], v[2:3], off
	v_lshl_add_u64 v[6:7], v[10:11], 0, v[6:7]
	global_load_dwordx4 v[6:9], v[6:7], off
	v_add_co_u32_e32 v16, vcc, s19, v20
	v_lshl_add_u64 v[12:13], v[12:13], 0, v[28:29]
	s_nop 0
	v_addc_co_u32_e32 v17, vcc, 0, v21, vcc
	v_add_co_u32_e32 v20, vcc, s2, v20
	v_lshl_add_u64 v[10:11], v[10:11], 0, v[28:29]
	s_nop 0
	v_addc_co_u32_e32 v21, vcc, 0, v21, vcc
	v_lshl_add_u64 v[28:29], v[46:47], 0, v[48:49]
	v_add_co_u32_e32 v50, vcc, s19, v28
	s_lshl_b32 s84, s14, 8
	s_nop 0
	v_addc_co_u32_e32 v51, vcc, 0, v29, vcc
	v_add_co_u32_e32 v28, vcc, s2, v28
	global_load_dwordx4 v[52:55], v[50:51], off
	s_nop 0
	v_addc_co_u32_e32 v29, vcc, 0, v29, vcc
	global_load_dwordx4 v[56:59], v[28:29], off
	v_or_b32_e32 v28, s15, v75
	v_ashrrev_i32_e32 v29, 31, v28
	v_lshlrev_b64 v[28:29], 10, v[28:29]
	v_lshl_add_u64 v[28:29], s[88:89], 0, v[28:29]
	v_lshl_add_u64 v[28:29], v[28:29], 0, s[84:85]
	global_load_dwordx4 v[16:19], v[16:17], off
	v_lshl_add_u64 v[60:61], v[36:37], 1, v[28:29]
	global_load_dwordx4 v[20:23], v[20:21], off
	v_lshl_add_u64 v[62:63], v[38:39], 1, v[28:29]
	global_load_dwordx4 v[24:27], v[12:13], off
	v_lshl_add_u64 v[64:65], v[40:41], 1, v[28:29]
	global_load_dwordx4 v[10:13], v[10:11], off
	s_waitcnt vmcnt(7)
	ds_write_b128 v84, v[2:5]
	s_waitcnt vmcnt(6)
	ds_write_b128 v84, v[6:9] offset:18432
	v_lshl_add_u64 v[28:29], v[42:43], 1, v[28:29]
	global_load_dwordx4 v[2:5], v[60:61], off
	global_load_dwordx4 v[6:9], v[62:63], off
	s_nop 0
	global_load_dwordx4 v[60:63], v[64:65], off
	s_nop 0
	global_load_dwordx4 v[64:67], v[28:29], off
	s_waitcnt vmcnt(7)
	ds_write_b128 v85, v[16:19]
	s_waitcnt vmcnt(6)
	ds_write_b128 v86, v[20:23]
	s_waitcnt vmcnt(5)
	ds_write_b128 v87, v[24:27]
	s_waitcnt vmcnt(4)
	ds_write_b128 v87, v[10:13] offset:18432
	ds_write_b128 v88, v[52:55]
	ds_write_b128 v89, v[56:59]
	s_waitcnt vmcnt(3)
	ds_write_b16 v90, v2 offset:36864
	ds_write_b16_d16_hi v90, v2 offset:37136
	ds_write_b16 v90, v3 offset:37408
	ds_write_b16_d16_hi v90, v3 offset:37680
	ds_write_b16 v90, v4 offset:37952
	ds_write_b16_d16_hi v90, v4 offset:38224
	ds_write_b16 v90, v5 offset:38496
	ds_write_b16_d16_hi v90, v5 offset:38768
	s_waitcnt vmcnt(2)
	ds_write_b16 v91, v6 offset:36864
	ds_write_b16_d16_hi v91, v6 offset:37136
	ds_write_b16 v91, v7 offset:37408
	ds_write_b16_d16_hi v91, v7 offset:37680
	ds_write_b16 v91, v8 offset:37952
	ds_write_b16_d16_hi v91, v8 offset:38224
	ds_write_b16 v91, v9 offset:38496
	ds_write_b16_d16_hi v91, v9 offset:38768
	s_waitcnt vmcnt(1)
	ds_write_b16 v92, v60 offset:36864
	ds_write_b16_d16_hi v92, v60 offset:37136
	ds_write_b16 v92, v61 offset:37408
	ds_write_b16_d16_hi v92, v61 offset:37680
	ds_write_b16 v92, v62 offset:37952
	ds_write_b16_d16_hi v92, v62 offset:38224
	ds_write_b16 v92, v63 offset:38496
	ds_write_b16_d16_hi v92, v63 offset:38768
	s_waitcnt vmcnt(0)
	ds_write_b16 v93, v64 offset:36864
	ds_write_b16_d16_hi v93, v64 offset:37136
	ds_write_b16 v93, v65 offset:37408
	ds_write_b16_d16_hi v93, v65 offset:37680
	ds_write_b16 v93, v66 offset:37952
	ds_write_b16_d16_hi v93, v66 offset:38224
	ds_write_b16 v93, v67 offset:38496
	ds_write_b16_d16_hi v93, v67 offset:38768
	v_add_u32_e32 v242, s15, v77
	v_ashrrev_i32_e32 v243, 31, v242
	v_lshlrev_b64 v[242:243], 10, v[242:243]
	v_lshl_add_u64 v[242:243], s[72:73], 0, v[242:243]
	v_lshl_add_u64 v[242:243], v[242:243], 0, s[84:85]
	v_lshl_add_u64 v[242:243], v[242:243], 0, v[0:1]
	global_load_dwordx2 v[206:207], v[242:243], off
	global_load_dwordx2 v[208:209], v[242:243], off offset:32
	global_load_dwordx2 v[210:211], v[242:243], off offset:64
	global_load_dwordx2 v[212:213], v[242:243], off offset:96
	global_load_dwordx2 v[214:215], v[242:243], off offset:128
	global_load_dwordx2 v[216:217], v[242:243], off offset:160
	global_load_dwordx2 v[218:219], v[242:243], off offset:192
	global_load_dwordx2 v[220:221], v[242:243], off offset:224
	s_waitcnt lgkmcnt(0)
	s_barrier
	ds_read_b128 v[6:9], v182
	ds_read_b128 v[2:5], v182 offset:64
	ds_read_b128 v[10:13], v183 offset:18432
	v_mul_f32_e32 v50, 0x3fb8aa3b, v15
	v_mul_f32_e32 v51, 0x3fb8aa3b, v14
	ds_read_b128 v[14:17], v183 offset:18496
	s_waitcnt lgkmcnt(1)
	v_mfma_f32_16x16x32_bf16 v[10:13], v[10:13], v[6:9], 0
	v_readlane_b32 s74, v255, 20
	v_readlane_b32 s75, v255, 21
	ds_read_b128 v[18:21], v183 offset:20800
	s_waitcnt lgkmcnt(1)
	v_mfma_f32_16x16x32_bf16 v[10:13], v[14:17], v[2:5], v[10:13]
	v_mul_f32_e32 v14, v51, v94
	v_mul_f32_e32 v15, v50, v95
	v_cndmask_b32_e64 v14, v15, v14, s[74:75]
	v_readlane_b32 s74, v255, 22
	v_mul_f32_e32 v15, v50, v97
	v_mul_f32_e32 v16, v51, v96
	v_readlane_b32 s75, v255, 23
	v_exp_f32_e32 v14, v14
	ds_read_b128 v[22:25], v183 offset:23104
	v_cndmask_b32_e64 v15, v15, v16, s[74:75]
	v_exp_f32_e32 v15, v15
	v_readlane_b32 s74, v255, 24
	v_readlane_b32 s75, v255, 25
	v_mul_f32_e32 v16, v51, v100
	v_pk_mul_f32 v[10:11], v[10:11], v[14:15]
	v_mul_f32_e32 v14, v50, v99
	v_mul_f32_e32 v15, v51, v98
	v_cndmask_b32_e64 v14, v14, v15, s[74:75]
	v_readlane_b32 s74, v255, 26
	v_mul_f32_e32 v15, v50, v101
	v_readlane_b32 s75, v255, 27
	v_exp_f32_e32 v14, v14
	ds_read_b128 v[26:29], v183 offset:25408
	v_cndmask_b32_e64 v15, v15, v16, s[74:75]
	v_exp_f32_e32 v15, v15
	v_readlane_b32 s74, v255, 28
	v_readlane_b32 s75, v255, 29
	ds_read_b128 v[52:55], v183 offset:27712
	v_pk_mul_f32 v[12:13], v[12:13], v[14:15]
	ds_read_b128 v[14:17], v183 offset:20736
	s_waitcnt lgkmcnt(0)
	v_mfma_f32_16x16x32_bf16 v[14:17], v[14:17], v[6:9], 0
	ds_read_b128 v[56:59], v183 offset:30016
	v_cvt_pk_bf16_f32 v10, v10, v11
	v_cvt_pk_bf16_f32 v11, v12, v13
	v_mfma_f32_16x16x32_bf16 v[14:17], v[18:21], v[2:5], v[14:17]
	v_mul_f32_e32 v18, v50, v103
	v_mul_f32_e32 v19, v51, v102
	v_cndmask_b32_e64 v18, v18, v19, s[74:75]
	v_mul_f32_e32 v19, v50, v105
	v_mul_f32_e32 v20, v51, v104
	v_cndmask_b32_e64 v19, v19, v20, s[16:17]
	v_exp_f32_e32 v18, v18
	v_exp_f32_e32 v19, v19
	v_readlane_b32 s16, v255, 32
	v_readlane_b32 s17, v255, 33
	v_mul_f32_e32 v20, v51, v108
	v_pk_mul_f32 v[14:15], v[18:19], v[14:15]
	v_mul_f32_e32 v18, v50, v107
	v_mul_f32_e32 v19, v51, v106
	v_cndmask_b32_e64 v18, v18, v19, s[16:17]
	v_mul_f32_e32 v19, v50, v109
	v_cndmask_b32_e64 v19, v19, v20, s[20:21]
	v_exp_f32_e32 v18, v18
	v_exp_f32_e32 v19, v19
	v_cvt_pk_bf16_f32 v12, v14, v15
	s_mov_b32 s74, 0xf800000
	v_lshl_add_u64 v[46:47], v[46:47], 0, s[76:77]
	v_pk_mul_f32 v[16:17], v[18:19], v[16:17]
	ds_read_b128 v[18:21], v183 offset:23040
	s_waitcnt lgkmcnt(0)
	v_mfma_f32_16x16x32_bf16 v[18:21], v[18:21], v[6:9], 0
	v_cvt_pk_bf16_f32 v13, v16, v17
	v_mfma_f32_16x16x32_bf16 v[18:21], v[22:25], v[2:5], v[18:21]
	v_mul_f32_e32 v22, v50, v111
	v_mul_f32_e32 v23, v51, v110
	v_cndmask_b32_e64 v22, v22, v23, s[22:23]
	v_mul_f32_e32 v23, v50, v113
	v_mul_f32_e32 v24, v51, v112
	v_cndmask_b32_e64 v23, v23, v24, s[24:25]
	v_exp_f32_e32 v22, v22
	v_exp_f32_e32 v23, v23
	v_mul_f32_e32 v24, v51, v116
	v_pk_mul_f32 v[18:19], v[22:23], v[18:19]
	v_mul_f32_e32 v22, v50, v115
	v_mul_f32_e32 v23, v51, v114
	v_cndmask_b32_e64 v22, v22, v23, s[26:27]
	v_mul_f32_e32 v23, v50, v117
	v_cndmask_b32_e64 v23, v23, v24, s[28:29]
	v_exp_f32_e32 v22, v22
	v_exp_f32_e32 v23, v23
	v_cvt_pk_bf16_f32 v14, v18, v19
	v_pk_mul_f32 v[20:21], v[22:23], v[20:21]
	ds_read_b128 v[22:25], v183 offset:25344
	s_waitcnt lgkmcnt(0)
	v_mfma_f32_16x16x32_bf16 v[22:25], v[22:25], v[6:9], 0
	v_cvt_pk_bf16_f32 v15, v20, v21
	v_mfma_f32_16x16x32_bf16 v[22:25], v[26:29], v[2:5], v[22:25]
	v_mul_f32_e32 v26, v50, v119
	v_mul_f32_e32 v27, v51, v118
	v_cndmask_b32_e64 v26, v26, v27, s[30:31]
	v_mul_f32_e32 v27, v50, v121
	v_mul_f32_e32 v28, v51, v120
	v_cndmask_b32_e64 v27, v27, v28, s[34:35]
	v_exp_f32_e32 v26, v26
	v_exp_f32_e32 v27, v27
	v_mul_f32_e32 v28, v51, v124
	v_pk_mul_f32 v[22:23], v[26:27], v[22:23]
	v_mul_f32_e32 v26, v50, v123
	v_mul_f32_e32 v27, v51, v122
	v_cndmask_b32_e64 v26, v26, v27, s[36:37]
	v_mul_f32_e32 v27, v50, v125
	v_cndmask_b32_e64 v27, v27, v28, s[38:39]
	v_exp_f32_e32 v26, v26
	v_exp_f32_e32 v27, v27
	v_cvt_pk_bf16_f32 v16, v22, v23
	v_pk_mul_f32 v[24:25], v[26:27], v[24:25]
	ds_read_b128 v[26:29], v183 offset:27648
	s_waitcnt lgkmcnt(0)
	v_mfma_f32_16x16x32_bf16 v[26:29], v[26:29], v[6:9], 0
	v_cvt_pk_bf16_f32 v17, v24, v25
	v_mfma_f32_16x16x32_bf16 v[26:29], v[52:55], v[2:5], v[26:29]
	v_mul_f32_e32 v52, v50, v127
	v_mul_f32_e32 v53, v51, v126
	v_cndmask_b32_e64 v52, v52, v53, s[40:41]
	v_mul_f32_e32 v53, v50, v129
	v_mul_f32_e32 v54, v51, v128
	v_cndmask_b32_e64 v53, v53, v54, s[42:43]
	v_exp_f32_e32 v52, v52
	v_exp_f32_e32 v53, v53
	v_mul_f32_e32 v54, v51, v132
	v_pk_mul_f32 v[26:27], v[52:53], v[26:27]
	v_mul_f32_e32 v52, v50, v131
	v_mul_f32_e32 v53, v51, v130
	v_cndmask_b32_e64 v52, v52, v53, s[44:45]
	v_mul_f32_e32 v53, v50, v133
	v_cndmask_b32_e64 v53, v53, v54, s[46:47]
	v_exp_f32_e32 v52, v52
	v_exp_f32_e32 v53, v53
	v_cvt_pk_bf16_f32 v18, v26, v27
	v_mul_f32_e32 v26, v50, v78
	v_exp_f32_e32 v74, v26
	v_pk_mul_f32 v[28:29], v[52:53], v[28:29]
	ds_read_b128 v[52:55], v183 offset:29952
	s_waitcnt lgkmcnt(0)
	v_mfma_f32_16x16x32_bf16 v[52:55], v[52:55], v[6:9], 0
	v_mul_f32_e32 v26, v51, v79
	v_cvt_pk_bf16_f32 v19, v28, v29
	v_exp_f32_e32 v76, v26
	v_mfma_f32_16x16x32_bf16 v[52:55], v[56:59], v[2:5], v[52:55]
	v_mul_f32_e32 v56, v50, v135
	v_mul_f32_e32 v57, v51, v134
	v_cndmask_b32_e64 v56, v56, v57, s[48:49]
	v_mul_f32_e32 v57, v50, v137
	v_mul_f32_e32 v58, v51, v136
	v_cndmask_b32_e64 v57, v57, v58, s[50:51]
	v_exp_f32_e32 v56, v56
	v_exp_f32_e32 v57, v57
	s_nop 0
	v_pk_mul_f32 v[60:61], v[56:57], v[52:53]
	v_mul_f32_e32 v52, v50, v139
	v_mul_f32_e32 v53, v51, v138
	v_cndmask_b32_e64 v52, v52, v53, s[52:53]
	v_mul_f32_e32 v53, v50, v141
	v_mul_f32_e32 v56, v51, v140
	v_cndmask_b32_e64 v53, v53, v56, s[54:55]
	v_exp_f32_e32 v52, v52
	v_exp_f32_e32 v53, v53
	ds_read_b128 v[56:59], v183 offset:32320
	v_cvt_pk_bf16_f32 v20, v60, v61
	v_pk_mul_f32 v[62:63], v[52:53], v[54:55]
	ds_read_b128 v[52:55], v183 offset:32256
	s_waitcnt lgkmcnt(0)
	v_mfma_f32_16x16x32_bf16 v[52:55], v[52:55], v[6:9], 0
	v_cvt_pk_bf16_f32 v21, v62, v63
	v_mfma_f32_16x16x32_bf16 v[52:55], v[56:59], v[2:5], v[52:55]
	v_mul_f32_e32 v56, v50, v143
	v_mul_f32_e32 v57, v51, v142
	v_cndmask_b32_e64 v56, v56, v57, s[6:7]
	v_mul_f32_e32 v57, v50, v145
	v_mul_f32_e32 v58, v51, v144
	v_cndmask_b32_e64 v57, v57, v58, s[8:9]
	v_exp_f32_e32 v56, v56
	v_exp_f32_e32 v57, v57
	s_nop 0
	v_pk_mul_f32 v[64:65], v[56:57], v[52:53]
	v_mul_f32_e32 v52, v50, v147
	v_mul_f32_e32 v53, v51, v146
	v_cndmask_b32_e64 v52, v52, v53, s[10:11]
	v_mul_f32_e32 v53, v50, v149
	v_mul_f32_e32 v56, v51, v148
	v_cndmask_b32_e64 v53, v53, v56, s[12:13]
	v_exp_f32_e32 v52, v52
	v_exp_f32_e32 v53, v53
	ds_read_b128 v[56:59], v183 offset:34624
	v_cvt_pk_bf16_f32 v22, v64, v65
	v_pk_mul_f32 v[66:67], v[52:53], v[54:55]
	ds_read_b128 v[52:55], v183 offset:34560
	s_waitcnt lgkmcnt(0)
	v_mfma_f32_16x16x32_bf16 v[52:55], v[52:55], v[6:9], 0
	v_cvt_pk_bf16_f32 v23, v66, v67
	v_mfma_f32_16x16x32_bf16 v[52:55], v[56:59], v[2:5], v[52:55]
	v_mul_f32_e32 v56, v50, v151
	v_mul_f32_e32 v57, v51, v150
	v_cndmask_b32_e64 v56, v56, v57, s[64:65]
	v_mul_f32_e32 v57, v50, v153
	v_mul_f32_e32 v58, v51, v152
	v_cndmask_b32_e64 v57, v57, v58, s[66:67]
	v_exp_f32_e32 v56, v56
	v_exp_f32_e32 v57, v57
	v_mul_f32_e32 v58, v51, v156
	v_pk_mul_f32 v[52:53], v[56:57], v[52:53]
	v_mul_f32_e32 v56, v50, v155
	v_mul_f32_e32 v57, v51, v154
	v_cndmask_b32_e64 v56, v56, v57, s[68:69]
	v_mul_f32_e32 v57, v50, v157
	v_cndmask_b32_e64 v57, v57, v58, s[70:71]
	v_exp_f32_e32 v56, v56
	v_exp_f32_e32 v57, v57
	v_cvt_pk_bf16_f32 v24, v52, v53
	v_pk_mul_f32 v[54:55], v[56:57], v[54:55]
	s_nop 0
	v_cvt_pk_bf16_f32 v25, v54, v55
	v_add_u32_e32 v54, 0x9000, v158
	ds_read2_b64 v[26:29], v54 offset1:4
	ds_read2_b64 v[50:53], v54 offset0:8 offset1:12
	s_waitcnt lgkmcnt(1)
	v_mfma_f32_16x16x32_bf16 v[26:29], v[26:29], v[10:13], 0
	s_waitcnt lgkmcnt(0)
	v_mfma_f32_16x16x32_bf16 v[26:29], v[50:53], v[14:17], v[26:29]
	ds_read2_b64 v[50:53], v54 offset0:16 offset1:20
	s_waitcnt lgkmcnt(0)
	v_mfma_f32_16x16x32_bf16 v[26:29], v[50:53], v[18:21], v[26:29]
	ds_read2_b64 v[50:53], v54 offset0:24 offset1:28
	s_waitcnt lgkmcnt(0)
	v_mfma_f32_16x16x32_bf16 v[26:29], v[50:53], v[22:25], v[26:29]
	ds_read_b128 v[50:53], v159
	ds_read_b128 v[54:57], v160
	ds_read_b128 v[58:61], v159 offset:64
	ds_read_b128 v[62:65], v160 offset:64
	s_waitcnt lgkmcnt(3)
	v_mfma_f32_16x16x32_bf16 v[50:53], v[50:53], v[6:9], 0
	s_waitcnt lgkmcnt(2)
	v_mfma_f32_16x16x32_bf16 v[54:57], v[54:57], v[6:9], 0
	s_waitcnt lgkmcnt(1)
	v_mfma_f32_16x16x32_bf16 v[50:53], v[58:61], v[2:5], v[50:53]
	s_waitcnt lgkmcnt(0)
	v_mfma_f32_16x16x32_bf16 v[54:57], v[62:65], v[2:5], v[54:57]
	s_nop 5
	v_fma_f32 v26, v74, v50, v26
	v_fma_f32 v27, v74, v51, v27
	v_pk_fma_f32 v[28:29], v[74:75], v[52:53], v[28:29] op_sel_hi:[0,1,1]
	v_pk_fma_f32 v[72:73], v[76:77], v[54:55], v[26:27] op_sel_hi:[0,1,1]
	v_add_u32_e32 v54, 0x9000, v161
	v_pk_fma_f32 v[70:71], v[76:77], v[56:57], v[28:29] op_sel_hi:[0,1,1]
	ds_read2_b64 v[26:29], v54 offset1:4
	ds_read2_b64 v[50:53], v54 offset0:8 offset1:12
	s_waitcnt lgkmcnt(1)
	v_mfma_f32_16x16x32_bf16 v[26:29], v[26:29], v[10:13], 0
	s_waitcnt lgkmcnt(0)
	v_mfma_f32_16x16x32_bf16 v[26:29], v[50:53], v[14:17], v[26:29]
	ds_read2_b64 v[50:53], v54 offset0:16 offset1:20
	s_waitcnt lgkmcnt(0)
	v_mfma_f32_16x16x32_bf16 v[26:29], v[50:53], v[18:21], v[26:29]
	ds_read2_b64 v[50:53], v54 offset0:24 offset1:28
	s_waitcnt lgkmcnt(0)
	v_mfma_f32_16x16x32_bf16 v[26:29], v[50:53], v[22:25], v[26:29]
	ds_read_b128 v[50:53], v162
	ds_read_b128 v[54:57], v163
	ds_read_b128 v[58:61], v162 offset:64
	ds_read_b128 v[62:65], v163 offset:64
	s_waitcnt lgkmcnt(3)
	v_mfma_f32_16x16x32_bf16 v[50:53], v[50:53], v[6:9], 0
	s_waitcnt lgkmcnt(2)
	v_mfma_f32_16x16x32_bf16 v[54:57], v[54:57], v[6:9], 0
	s_waitcnt lgkmcnt(1)
	v_mfma_f32_16x16x32_bf16 v[50:53], v[58:61], v[2:5], v[50:53]
	s_waitcnt lgkmcnt(0)
	v_mfma_f32_16x16x32_bf16 v[54:57], v[62:65], v[2:5], v[54:57]
	s_nop 5
	v_fma_f32 v26, v74, v50, v26
	v_fma_f32 v27, v74, v51, v27
	v_pk_fma_f32 v[28:29], v[74:75], v[52:53], v[28:29] op_sel_hi:[0,1,1]
	v_pk_fma_f32 v[68:69], v[76:77], v[54:55], v[26:27] op_sel_hi:[0,1,1]
	v_add_u32_e32 v54, 0x9000, v164
	v_pk_fma_f32 v[66:67], v[76:77], v[56:57], v[28:29] op_sel_hi:[0,1,1]
	ds_read2_b64 v[26:29], v54 offset1:4
	ds_read2_b64 v[50:53], v54 offset0:8 offset1:12
	s_waitcnt lgkmcnt(1)
	v_mfma_f32_16x16x32_bf16 v[26:29], v[26:29], v[10:13], 0
	s_waitcnt lgkmcnt(0)
	v_mfma_f32_16x16x32_bf16 v[26:29], v[50:53], v[14:17], v[26:29]
	ds_read2_b64 v[50:53], v54 offset0:16 offset1:20
	s_waitcnt lgkmcnt(0)
	v_mfma_f32_16x16x32_bf16 v[26:29], v[50:53], v[18:21], v[26:29]
	ds_read2_b64 v[50:53], v54 offset0:24 offset1:28
	s_waitcnt lgkmcnt(0)
	v_mfma_f32_16x16x32_bf16 v[26:29], v[50:53], v[22:25], v[26:29]
	ds_read_b128 v[50:53], v165
	ds_read_b128 v[54:57], v166
	ds_read_b128 v[58:61], v165 offset:64
	ds_read_b128 v[62:65], v166 offset:64
	s_waitcnt lgkmcnt(3)
	v_mfma_f32_16x16x32_bf16 v[50:53], v[50:53], v[6:9], 0
	s_waitcnt lgkmcnt(2)
	v_mfma_f32_16x16x32_bf16 v[54:57], v[54:57], v[6:9], 0
	s_waitcnt lgkmcnt(1)
	v_mfma_f32_16x16x32_bf16 v[50:53], v[58:61], v[2:5], v[50:53]
	s_waitcnt lgkmcnt(0)
	v_mfma_f32_16x16x32_bf16 v[54:57], v[62:65], v[2:5], v[54:57]
	s_nop 5
	v_fma_f32 v26, v74, v50, v26
	v_fma_f32 v27, v74, v51, v27
	v_pk_fma_f32 v[28:29], v[74:75], v[52:53], v[28:29] op_sel_hi:[0,1,1]
	v_pk_fma_f32 v[64:65], v[76:77], v[54:55], v[26:27] op_sel_hi:[0,1,1]
	v_add_u32_e32 v54, 0x9000, v167
	v_pk_fma_f32 v[62:63], v[76:77], v[56:57], v[28:29] op_sel_hi:[0,1,1]
	ds_read2_b64 v[26:29], v54 offset1:4
	ds_read2_b64 v[50:53], v54 offset0:8 offset1:12
	s_waitcnt lgkmcnt(1)
	v_mfma_f32_16x16x32_bf16 v[26:29], v[26:29], v[10:13], 0
	s_waitcnt lgkmcnt(0)
	v_mfma_f32_16x16x32_bf16 v[26:29], v[50:53], v[14:17], v[26:29]
	ds_read2_b64 v[50:53], v54 offset0:16 offset1:20
	s_waitcnt lgkmcnt(0)
	v_mfma_f32_16x16x32_bf16 v[26:29], v[50:53], v[18:21], v[26:29]
	ds_read2_b64 v[50:53], v54 offset0:24 offset1:28
	s_waitcnt lgkmcnt(0)
	v_mfma_f32_16x16x32_bf16 v[26:29], v[50:53], v[22:25], v[26:29]
	ds_read_b128 v[50:53], v168
	ds_read_b128 v[54:57], v169
	ds_read_b128 v[58:61], v168 offset:64
	ds_read_b128 v[184:187], v169 offset:64
	s_waitcnt lgkmcnt(3)
	v_mfma_f32_16x16x32_bf16 v[50:53], v[50:53], v[6:9], 0
	s_waitcnt lgkmcnt(2)
	v_mfma_f32_16x16x32_bf16 v[54:57], v[54:57], v[6:9], 0
	s_waitcnt lgkmcnt(1)
	v_mfma_f32_16x16x32_bf16 v[50:53], v[58:61], v[2:5], v[50:53]
	s_waitcnt lgkmcnt(0)
	v_mfma_f32_16x16x32_bf16 v[54:57], v[184:187], v[2:5], v[54:57]
	s_nop 5
	v_fma_f32 v26, v74, v50, v26
	v_fma_f32 v27, v74, v51, v27
	v_pk_fma_f32 v[28:29], v[74:75], v[52:53], v[28:29] op_sel_hi:[0,1,1]
	v_pk_fma_f32 v[60:61], v[76:77], v[54:55], v[26:27] op_sel_hi:[0,1,1]
	v_add_u32_e32 v54, 0x9000, v170
	v_pk_fma_f32 v[58:59], v[76:77], v[56:57], v[28:29] op_sel_hi:[0,1,1]
	ds_read2_b64 v[26:29], v54 offset1:4
	ds_read2_b64 v[50:53], v54 offset0:8 offset1:12
	s_waitcnt lgkmcnt(1)
	v_mfma_f32_16x16x32_bf16 v[26:29], v[26:29], v[10:13], 0
	s_waitcnt lgkmcnt(0)
	v_mfma_f32_16x16x32_bf16 v[26:29], v[50:53], v[14:17], v[26:29]
	ds_read2_b64 v[50:53], v54 offset0:16 offset1:20
	s_waitcnt lgkmcnt(0)
	v_mfma_f32_16x16x32_bf16 v[26:29], v[50:53], v[18:21], v[26:29]
	ds_read2_b64 v[50:53], v54 offset0:24 offset1:28
	s_waitcnt lgkmcnt(0)
	v_mfma_f32_16x16x32_bf16 v[26:29], v[50:53], v[22:25], v[26:29]
	ds_read_b128 v[50:53], v171
	ds_read_b128 v[54:57], v172
	ds_read_b128 v[184:187], v171 offset:64
	ds_read_b128 v[194:197], v172 offset:64
	s_waitcnt lgkmcnt(3)
	v_mfma_f32_16x16x32_bf16 v[50:53], v[50:53], v[6:9], 0
	s_waitcnt lgkmcnt(2)
	v_mfma_f32_16x16x32_bf16 v[54:57], v[54:57], v[6:9], 0
	s_waitcnt lgkmcnt(1)
	v_mfma_f32_16x16x32_bf16 v[50:53], v[184:187], v[2:5], v[50:53]
	s_waitcnt lgkmcnt(0)
	v_mfma_f32_16x16x32_bf16 v[184:187], v[194:197], v[2:5], v[54:57]
	s_nop 5
	v_fma_f32 v26, v74, v50, v26
	v_fma_f32 v27, v74, v51, v27
	v_pk_fma_f32 v[28:29], v[74:75], v[52:53], v[28:29] op_sel_hi:[0,1,1]
	v_pk_fma_f32 v[56:57], v[76:77], v[184:185], v[26:27] op_sel_hi:[0,1,1]
	v_add_u32_e32 v184, 0x9000, v173
	v_pk_fma_f32 v[54:55], v[76:77], v[186:187], v[28:29] op_sel_hi:[0,1,1]
	ds_read2_b64 v[26:29], v184 offset1:4
	ds_read2_b64 v[50:53], v184 offset0:8 offset1:12
	s_waitcnt lgkmcnt(1)
	v_mfma_f32_16x16x32_bf16 v[26:29], v[26:29], v[10:13], 0
	s_waitcnt lgkmcnt(0)
	v_mfma_f32_16x16x32_bf16 v[26:29], v[50:53], v[14:17], v[26:29]
	ds_read2_b64 v[50:53], v184 offset0:16 offset1:20
	s_waitcnt lgkmcnt(0)
	v_mfma_f32_16x16x32_bf16 v[26:29], v[50:53], v[18:21], v[26:29]
	ds_read2_b64 v[50:53], v184 offset0:24 offset1:28
	s_waitcnt lgkmcnt(0)
	v_mfma_f32_16x16x32_bf16 v[26:29], v[50:53], v[22:25], v[26:29]
	ds_read_b128 v[50:53], v174
	ds_read_b128 v[184:187], v175
	ds_read_b128 v[194:197], v174 offset:64
	ds_read_b128 v[198:201], v175 offset:64
	s_waitcnt lgkmcnt(3)
	v_mfma_f32_16x16x32_bf16 v[50:53], v[50:53], v[6:9], 0
	s_waitcnt lgkmcnt(2)
	v_mfma_f32_16x16x32_bf16 v[184:187], v[184:187], v[6:9], 0
	s_waitcnt lgkmcnt(1)
	v_mfma_f32_16x16x32_bf16 v[50:53], v[194:197], v[2:5], v[50:53]
	s_waitcnt lgkmcnt(0)
	v_mfma_f32_16x16x32_bf16 v[184:187], v[198:201], v[2:5], v[184:187]
	s_nop 5
	v_fma_f32 v28, v74, v52, v28
	v_fma_f32 v29, v74, v53, v29
	v_pk_fma_f32 v[26:27], v[74:75], v[50:51], v[26:27] op_sel_hi:[0,1,1]
	v_pk_fma_f32 v[50:51], v[76:77], v[186:187], v[28:29] op_sel_hi:[0,1,1]
	v_pk_fma_f32 v[52:53], v[76:77], v[184:185], v[26:27] op_sel_hi:[0,1,1]
	ds_read2_b64 v[26:29], v188 offset1:4
	ds_read2_b64 v[184:187], v188 offset0:8 offset1:12
	s_waitcnt lgkmcnt(1)
	v_mfma_f32_16x16x32_bf16 v[26:29], v[26:29], v[10:13], 0
	s_waitcnt lgkmcnt(0)
	v_mfma_f32_16x16x32_bf16 v[26:29], v[184:187], v[14:17], v[26:29]
	ds_read2_b64 v[184:187], v188 offset0:16 offset1:20
	s_waitcnt lgkmcnt(0)
	v_mfma_f32_16x16x32_bf16 v[26:29], v[184:187], v[18:21], v[26:29]
	ds_read2_b64 v[184:187], v188 offset0:24 offset1:28
	v_add_u32_e32 v188, 0x9000, v179
	s_waitcnt lgkmcnt(0)
	v_mfma_f32_16x16x32_bf16 v[26:29], v[184:187], v[22:25], v[26:29]
	ds_read_b128 v[184:187], v177
	ds_read_b128 v[194:197], v178
	ds_read_b128 v[198:201], v177 offset:64
	ds_read_b128 v[202:205], v178 offset:64
	s_waitcnt lgkmcnt(3)
	v_mfma_f32_16x16x32_bf16 v[184:187], v[184:187], v[6:9], 0
	s_waitcnt lgkmcnt(2)
	v_mfma_f32_16x16x32_bf16 v[194:197], v[194:197], v[6:9], 0
	s_waitcnt lgkmcnt(1)
	v_mfma_f32_16x16x32_bf16 v[184:187], v[198:201], v[2:5], v[184:187]
	s_waitcnt lgkmcnt(0)
	v_mfma_f32_16x16x32_bf16 v[194:197], v[202:205], v[2:5], v[194:197]
	s_nop 5
	v_fma_f32 v28, v74, v186, v28
	v_fma_f32 v29, v74, v187, v29
	v_pk_fma_f32 v[184:185], v[74:75], v[184:185], v[26:27] op_sel_hi:[0,1,1]
	v_pk_fma_f32 v[26:27], v[76:77], v[196:197], v[28:29] op_sel_hi:[0,1,1]
	v_pk_fma_f32 v[28:29], v[76:77], v[194:195], v[184:185] op_sel_hi:[0,1,1]
	ds_read2_b64 v[184:187], v188 offset1:4
	s_waitcnt lgkmcnt(0)
	v_mfma_f32_16x16x32_bf16 v[10:13], v[184:187], v[10:13], 0
	ds_read2_b64 v[184:187], v188 offset0:8 offset1:12
	s_waitcnt lgkmcnt(0)
	v_mfma_f32_16x16x32_bf16 v[10:13], v[184:187], v[14:17], v[10:13]
	ds_read2_b64 v[14:17], v188 offset0:16 offset1:20
	s_waitcnt lgkmcnt(0)
	v_mfma_f32_16x16x32_bf16 v[10:13], v[14:17], v[18:21], v[10:13]
	ds_read2_b64 v[14:17], v188 offset0:24 offset1:28
	s_waitcnt lgkmcnt(0)
	v_mfma_f32_16x16x32_bf16 v[10:13], v[14:17], v[22:25], v[10:13]
	ds_read_b128 v[14:17], v180
	ds_read_b128 v[18:21], v181
	s_waitcnt lgkmcnt(1)
	v_mfma_f32_16x16x32_bf16 v[14:17], v[14:17], v[6:9], 0
	s_waitcnt lgkmcnt(0)
	v_mfma_f32_16x16x32_bf16 v[6:9], v[18:21], v[6:9], 0
	ds_read_b128 v[18:21], v180 offset:64
	ds_read_b128 v[22:25], v181 offset:64
	s_waitcnt lgkmcnt(1)
	v_mfma_f32_16x16x32_bf16 v[14:17], v[18:21], v[2:5], v[14:17]
	s_waitcnt lgkmcnt(0)
	v_mfma_f32_16x16x32_bf16 v[4:7], v[22:25], v[2:5], v[6:9]
	v_mov_b32_e32 v232, s14
	v_mov_b32_e32 v233, 0
	v_lshlrev_b32_e32 v232, 9, v232
	v_lshl_add_u64 v[232:233], v[34:35], 0, v[232:233]
	global_load_dwordx4 v[22:25], v[232:233], off
	global_load_dwordx4 v[184:187], v[232:233], off offset:64
	global_load_dwordx4 v[194:197], v[232:233], off offset:128
	global_load_dwordx4 v[198:201], v[232:233], off offset:192
	global_load_dwordx4 v[202:205], v[232:233], off offset:256
	global_load_dwordx4 v[224:227], v[232:233], off offset:320
	global_load_dwordx4 v[246:249], v[232:233], off offset:384
	global_load_dwordx4 v[250:253], v[232:233], off offset:448
	s_nop 5
	v_fma_f32 v2, v74, v16, v12
	v_fma_f32 v3, v74, v17, v13
	v_add_f32_e32 v12, v58, v59
	v_mov_b32_e32 v13, v55
	v_pk_fma_f32 v[8:9], v[74:75], v[14:15], v[10:11] op_sel_hi:[0,1,1]
	v_mov_b32_e32 v10, v71
	v_pk_fma_f32 v[2:3], v[76:77], v[6:7], v[2:3] op_sel_hi:[0,1,1]
	v_pk_fma_f32 v[4:5], v[76:77], v[4:5], v[8:9] op_sel_hi:[0,1,1]
	v_mov_b32_e32 v6, v72
	v_mov_b32_e32 v7, v68
	v_mov_b32_e32 v8, v73
	v_mov_b32_e32 v9, v69
	v_pk_add_f32 v[6:7], v[6:7], v[8:9]
	v_mov_b32_e32 v8, v70
	v_mov_b32_e32 v9, v66
	v_mov_b32_e32 v11, v67
	v_pk_add_f32 v[8:9], v[8:9], v[10:11]
	v_mov_b32_e32 v10, v64
	v_pk_add_f32 v[6:7], v[6:7], v[8:9]
	v_pk_mov_b32 v[8:9], v[64:65], v[62:63] op_sel:[1,0]
	v_mov_b32_e32 v11, v63
	v_pk_add_f32 v[8:9], v[8:9], v[10:11]
	v_add_f32_e32 v6, 0, v6
	v_pk_add_f32 v[8:9], v[8:9], v[8:9] op_sel:[0,1] op_sel_hi:[1,0]
	v_add_f32_e32 v6, v6, v7
	v_add_f32_e32 v10, v60, v61
	v_mov_b32_e32 v7, v56
	v_mov_b32_e32 v9, v57
	v_mov_b32_e32 v11, v54
	v_pk_add_f32 v[6:7], v[6:7], v[8:9]
	v_pk_add_f32 v[8:9], v[10:11], v[12:13]
	v_mov_b32_e32 v10, v52
	v_pk_add_f32 v[6:7], v[6:7], v[8:9]
	v_pk_mov_b32 v[8:9], v[52:53], v[50:51] op_sel:[1,0]
	v_mov_b32_e32 v11, v51
	v_pk_add_f32 v[8:9], v[8:9], v[10:11]
	v_pk_add_f32 v[6:7], v[6:7], v[6:7] op_sel:[0,1] op_sel_hi:[1,0]
	v_pk_add_f32 v[8:9], v[8:9], v[8:9] op_sel:[0,1] op_sel_hi:[1,0]
	v_add_f32_e32 v10, v28, v29
	v_add_f32_e32 v12, v26, v27
	v_mov_b32_e32 v7, v4
	v_mov_b32_e32 v9, v5
	v_mov_b32_e32 v11, v2
	v_mov_b32_e32 v13, v3
	v_pk_add_f32 v[6:7], v[6:7], v[8:9]
	v_pk_add_f32 v[8:9], v[10:11], v[12:13]
	s_nop 0
	v_pk_add_f32 v[6:7], v[6:7], v[8:9]
	s_nop 0
	v_add_f32_e32 v6, v6, v7
	ds_bpermute_b32 v7, v80, v6
	s_waitcnt lgkmcnt(0)
	v_add_f32_e32 v6, v6, v7
	ds_bpermute_b32 v7, v81, v6
	s_waitcnt lgkmcnt(0)
	v_add_f32_e32 v14, v6, v7
	v_fmamk_f32 v73, v14, 0xbc000000, v73
	v_fmamk_f32 v69, v14, 0xbc000000, v69
	v_fmamk_f32 v71, v14, 0xbc000000, v71
	v_fmac_f32_e32 v72, 0xbc000000, v14
	v_fmamk_f32 v67, v14, 0xbc000000, v67
	v_fmac_f32_e32 v68, 0xbc000000, v14
	v_mov_b32_e32 v8, v73
	v_mov_b32_e32 v9, v69
	v_fmac_f32_e32 v70, 0xbc000000, v14
	v_fmac_f32_e32 v66, 0xbc000000, v14
	v_mov_b32_e32 v6, v72
	v_mov_b32_e32 v7, v68
	v_pk_mul_f32 v[8:9], v[8:9], v[8:9]
	v_mov_b32_e32 v10, v71
	v_mov_b32_e32 v11, v67
	v_pk_fma_f32 v[6:7], v[6:7], v[6:7], v[8:9]
	v_mov_b32_e32 v8, v70
	v_mov_b32_e32 v9, v66
	v_pk_mul_f32 v[10:11], v[10:11], v[10:11]
	v_fmamk_f32 v65, v14, 0xbc000000, v65
	v_pk_fma_f32 v[8:9], v[8:9], v[8:9], v[10:11]
	v_fmac_f32_e32 v64, 0xbc000000, v14
	v_pk_add_f32 v[6:7], v[6:7], v[8:9]
	v_fmamk_f32 v63, v14, 0xbc000000, v63
	v_fmac_f32_e32 v62, 0xbc000000, v14
	v_pk_add_f32 v[6:7], v[6:7], v[6:7] op_sel_hi:[0,1]
	v_pk_mul_f32 v[8:9], v[62:63], v[62:63]
	v_pk_mul_f32 v[10:11], v[64:65], v[64:65]
	v_fmac_f32_e32 v60, 0xbc000000, v14
	v_pk_mov_b32 v[12:13], v[10:11], v[8:9] op_sel:[1,0]
	v_mov_b32_e32 v11, v9
	v_fmamk_f32 v61, v14, 0xbc000000, v61
	v_fmac_f32_e32 v58, 0xbc000000, v14
	v_mul_f32_e32 v6, v60, v60
	v_pk_add_f32 v[8:9], v[12:13], v[10:11]
	v_fmamk_f32 v59, v14, 0xbc000000, v59
	v_pk_fma_f32 v[10:11], v[60:61], v[60:61], v[6:7] op_sel_hi:[1,1,0]
	v_mul_f32_e32 v6, v58, v58
	v_pk_add_f32 v[8:9], v[8:9], v[8:9] op_sel_hi:[0,1]
	v_pk_fma_f32 v[12:13], v[58:59], v[58:59], v[6:7] op_sel_hi:[1,1,0]
	v_fmamk_f32 v55, v14, 0xbc000000, v55
	v_fmac_f32_e32 v54, 0xbc000000, v14
	v_fmamk_f32 v57, v14, 0xbc000000, v57
	v_fmac_f32_e32 v56, 0xbc000000, v14
	v_mul_f32_e32 v10, v56, v56
	v_mul_f32_e32 v12, v57, v57
	v_mul_f32_e32 v8, v54, v54
	v_mul_f32_e32 v6, v55, v55
	v_pk_add_f32 v[10:11], v[10:11], v[12:13]
	v_pk_add_f32 v[6:7], v[8:9], v[6:7]
	v_fmamk_f32 v53, v14, 0xbc000000, v53
	v_pk_add_f32 v[6:7], v[10:11], v[6:7]
	v_fmac_f32_e32 v52, 0xbc000000, v14
	v_fmamk_f32 v51, v14, 0xbc000000, v51
	v_fmac_f32_e32 v50, 0xbc000000, v14
	v_pk_add_f32 v[6:7], v[6:7], v[6:7] op_sel_hi:[0,1]
	v_pk_mul_f32 v[8:9], v[50:51], v[50:51]
	v_pk_mul_f32 v[10:11], v[52:53], v[52:53]
	v_fmac_f32_e32 v28, 0xbc000000, v14
	v_pk_mov_b32 v[12:13], v[10:11], v[8:9] op_sel:[1,0]
	v_mov_b32_e32 v11, v9
	v_fmamk_f32 v29, v14, 0xbc000000, v29
	v_fmac_f32_e32 v26, 0xbc000000, v14
	v_mul_f32_e32 v6, v28, v28
	v_pk_add_f32 v[8:9], v[12:13], v[10:11]
	v_fmamk_f32 v27, v14, 0xbc000000, v27
	v_pk_fma_f32 v[10:11], v[28:29], v[28:29], v[6:7] op_sel_hi:[1,1,0]
	v_mul_f32_e32 v6, v26, v26
	v_pk_add_f32 v[8:9], v[8:9], v[8:9] op_sel_hi:[0,1]
	v_pk_fma_f32 v[12:13], v[26:27], v[26:27], v[6:7] op_sel_hi:[1,1,0]
	v_fmamk_f32 v3, v14, 0xbc000000, v3
	v_fmac_f32_e32 v2, 0xbc000000, v14
	v_fmamk_f32 v5, v14, 0xbc000000, v5
	v_fmac_f32_e32 v4, 0xbc000000, v14
	v_mul_f32_e32 v10, v4, v4
	v_mul_f32_e32 v12, v5, v5
	v_mul_f32_e32 v8, v2, v2
	v_mul_f32_e32 v6, v3, v3
	v_pk_add_f32 v[10:11], v[10:11], v[12:13]
	v_pk_add_f32 v[6:7], v[8:9], v[6:7]
	s_nop 0
	v_pk_add_f32 v[6:7], v[10:11], v[6:7]
	s_nop 0
	v_add_f32_e32 v6, v6, v7
	ds_bpermute_b32 v7, v80, v6
	s_waitcnt lgkmcnt(0)
	v_add_f32_e32 v6, v6, v7
	ds_bpermute_b32 v7, v81, v6
	s_waitcnt lgkmcnt(0)
	v_add_f32_e32 v6, v6, v7
	v_fmamk_f32 v6, v6, 0x3c000000, v223
	v_cmp_gt_f32_e32 vcc, s74, v6
	v_mul_f32_e32 v7, 0x4f800000, v6
	s_nop 0
	v_cndmask_b32_e32 v6, v6, v7, vcc
	v_sqrt_f32_e32 v7, v6
	s_nop 0
	v_add_u32_e32 v8, -1, v7
	v_fma_f32 v9, -v8, v7, v6
	v_cmp_ge_f32_e64 s[74:75], 0, v9
	v_add_u32_e32 v9, 1, v7
	s_nop 0
	v_cndmask_b32_e64 v8, v7, v8, s[74:75]
	v_fma_f32 v7, -v9, v7, v6
	v_cmp_lt_f32_e64 s[74:75], 0, v7
	s_nop 1
	v_cndmask_b32_e64 v7, v8, v9, s[74:75]
	v_mul_f32_e32 v8, 0x37800000, v7
	v_cndmask_b32_e32 v7, v7, v8, vcc
	v_mov_b32_e32 v8, 0x260
	v_cmp_class_f32_e32 vcc, v6, v8
	s_nop 1
	v_cndmask_b32_e32 v6, v7, v6, vcc
	v_div_scale_f32 v7, s[74:75], v6, v6, 1.0
	v_rcp_f32_e32 v8, v7
	s_nop 0
	v_fma_f32 v9, -v7, v8, 1.0
	v_fmac_f32_e32 v8, v9, v8
	v_div_scale_f32 v9, vcc, 1.0, v6, 1.0
	v_mul_f32_e32 v10, v9, v8
	v_fma_f32 v11, -v7, v10, v9
	v_fmac_f32_e32 v10, v11, v8
	v_fma_f32 v7, -v7, v10, v9
	v_div_fmas_f32 v7, v7, v8, v10
	v_add_u32_e32 v8, s15, v77
	v_ashrrev_i32_e32 v9, 31, v8
	v_lshlrev_b64 v[8:9], 10, v[8:9]
	v_lshl_add_u64 v[8:9], s[72:73], 0, v[8:9]
	v_lshl_add_u64 v[8:9], v[8:9], 0, s[84:85]
	v_lshl_add_u64 v[8:9], v[8:9], 0, v[0:1]
	s_lshl_b32 s84, s14, 9
	v_lshl_add_u64 v[10:11], v[34:35], 0, s[84:85]
	s_waitcnt vmcnt(0)
	v_mov_b64_e32 v[16:17], v[206:207]
	v_mov_b64_e32 v[12:13], v[22:23]
	v_mov_b64_e32 v[14:15], v[24:25]
	v_div_fixup_f32 v6, v7, v6, 1.0
	v_pk_mul_f32 v[18:19], v[72:73], v[6:7] op_sel_hi:[1,0]
	v_pk_mul_f32 v[20:21], v[70:71], v[6:7] op_sel_hi:[1,0]
	s_cmpk_lt_i32 s81, 0x600
	v_pk_mul_f32 v[12:13], v[12:13], v[18:19]
	v_lshlrev_b32_e32 v18, 16, v16
	v_mul_f32_e32 v7, 0xbfb8aa3b, v18
	v_exp_f32_e32 v7, v7
	v_and_b32_e32 v19, 0xffff0000, v16
	v_pk_mul_f32 v[14:15], v[14:15], v[20:21]
	v_lshlrev_b32_e32 v16, 16, v17
	v_add_f32_e32 v7, 1.0, v7
	v_rcp_f32_e32 v20, v7
	v_mul_f32_e32 v7, 0xbfb8aa3b, v19
	v_exp_f32_e32 v7, v7
	v_and_b32_e32 v17, 0xffff0000, v17
	v_add_f32_e32 v7, 1.0, v7
	v_rcp_f32_e32 v21, v7
	v_mul_f32_e32 v7, 0xbfb8aa3b, v16
	v_exp_f32_e32 v7, v7
	v_pk_mul_f32 v[18:19], v[20:21], v[18:19]
	s_nop 0
	v_pk_mul_f32 v[12:13], v[18:19], v[12:13]
	v_add_f32_e32 v7, 1.0, v7
	v_rcp_f32_e32 v18, v7
	v_mul_f32_e32 v7, 0xbfb8aa3b, v17
	v_exp_f32_e32 v7, v7
	v_cvt_pk_bf16_f32 v12, v12, v13
	v_add_f32_e32 v7, 1.0, v7
	v_rcp_f32_e32 v19, v7
	v_pk_mul_f32 v[20:21], v[66:67], v[6:7] op_sel_hi:[1,0]
	v_pk_mul_f32 v[16:17], v[18:19], v[16:17]
	s_nop 0
	v_pk_mul_f32 v[14:15], v[16:17], v[14:15]
	v_pk_mul_f32 v[18:19], v[68:69], v[6:7] op_sel_hi:[1,0]
	v_cvt_pk_bf16_f32 v13, v14, v15
	global_store_dwordx2 v[8:9], v[12:13], off
	v_mov_b64_e32 v[16:17], v[208:209]
	v_mov_b64_e32 v[12:13], v[184:185]
	v_mov_b64_e32 v[14:15], v[186:187]
	v_pk_mul_f32 v[12:13], v[12:13], v[18:19]
	v_lshlrev_b32_e32 v18, 16, v16
	v_mul_f32_e32 v7, 0xbfb8aa3b, v18
	v_exp_f32_e32 v7, v7
	v_and_b32_e32 v19, 0xffff0000, v16
	v_pk_mul_f32 v[14:15], v[14:15], v[20:21]
	v_lshlrev_b32_e32 v16, 16, v17
	v_add_f32_e32 v7, 1.0, v7
	v_rcp_f32_e32 v20, v7
	v_mul_f32_e32 v7, 0xbfb8aa3b, v19
	v_exp_f32_e32 v7, v7
	v_and_b32_e32 v17, 0xffff0000, v17
	v_add_f32_e32 v7, 1.0, v7
	v_rcp_f32_e32 v21, v7
	v_mul_f32_e32 v7, 0xbfb8aa3b, v16
	v_exp_f32_e32 v7, v7
	v_pk_mul_f32 v[18:19], v[20:21], v[18:19]
	s_nop 0
	v_pk_mul_f32 v[12:13], v[18:19], v[12:13]
	v_add_f32_e32 v7, 1.0, v7
	v_rcp_f32_e32 v18, v7
	v_mul_f32_e32 v7, 0xbfb8aa3b, v17
	v_exp_f32_e32 v7, v7
	v_cvt_pk_bf16_f32 v12, v12, v13
	v_add_f32_e32 v7, 1.0, v7
	v_rcp_f32_e32 v19, v7
	v_pk_mul_f32 v[20:21], v[62:63], v[6:7] op_sel_hi:[1,0]
	v_pk_mul_f32 v[16:17], v[18:19], v[16:17]
	s_nop 0
	v_pk_mul_f32 v[14:15], v[16:17], v[14:15]
	v_pk_mul_f32 v[18:19], v[64:65], v[6:7] op_sel_hi:[1,0]
	v_cvt_pk_bf16_f32 v13, v14, v15
	global_store_dwordx2 v[8:9], v[12:13], off offset:32
	v_mov_b64_e32 v[16:17], v[210:211]
	v_mov_b64_e32 v[12:13], v[194:195]
	v_mov_b64_e32 v[14:15], v[196:197]
	v_pk_mul_f32 v[12:13], v[12:13], v[18:19]
	v_lshlrev_b32_e32 v18, 16, v16
	v_mul_f32_e32 v7, 0xbfb8aa3b, v18
	v_exp_f32_e32 v7, v7
	v_and_b32_e32 v19, 0xffff0000, v16
	v_pk_mul_f32 v[14:15], v[14:15], v[20:21]
	v_lshlrev_b32_e32 v16, 16, v17
	v_add_f32_e32 v7, 1.0, v7
	v_rcp_f32_e32 v20, v7
	v_mul_f32_e32 v7, 0xbfb8aa3b, v19
	v_exp_f32_e32 v7, v7
	v_and_b32_e32 v17, 0xffff0000, v17
	v_add_f32_e32 v7, 1.0, v7
	v_rcp_f32_e32 v21, v7
	v_mul_f32_e32 v7, 0xbfb8aa3b, v16
	v_exp_f32_e32 v7, v7
	v_pk_mul_f32 v[18:19], v[20:21], v[18:19]
	s_nop 0
	v_pk_mul_f32 v[12:13], v[18:19], v[12:13]
	v_add_f32_e32 v7, 1.0, v7
	v_rcp_f32_e32 v18, v7
	v_mul_f32_e32 v7, 0xbfb8aa3b, v17
	v_exp_f32_e32 v7, v7
	v_cvt_pk_bf16_f32 v12, v12, v13
	v_add_f32_e32 v7, 1.0, v7
	v_rcp_f32_e32 v19, v7
	v_pk_mul_f32 v[20:21], v[58:59], v[6:7] op_sel_hi:[1,0]
	v_pk_mul_f32 v[16:17], v[18:19], v[16:17]
	s_nop 0
	v_pk_mul_f32 v[14:15], v[16:17], v[14:15]
	v_pk_mul_f32 v[18:19], v[60:61], v[6:7] op_sel_hi:[1,0]
	v_cvt_pk_bf16_f32 v13, v14, v15
	global_store_dwordx2 v[8:9], v[12:13], off offset:64
	v_mov_b64_e32 v[12:13], v[212:213]
	v_mov_b64_e32 v[14:15], v[198:199]
	v_mov_b64_e32 v[16:17], v[200:201]
	v_pk_mul_f32 v[14:15], v[14:15], v[18:19]
	v_lshlrev_b32_e32 v18, 16, v12
	v_mul_f32_e32 v7, 0xbfb8aa3b, v18
	v_exp_f32_e32 v7, v7
	v_and_b32_e32 v19, 0xffff0000, v12
	v_pk_mul_f32 v[16:17], v[16:17], v[20:21]
	v_add_f32_e32 v7, 1.0, v7
	v_rcp_f32_e32 v20, v7
	v_mul_f32_e32 v7, 0xbfb8aa3b, v19
	v_exp_f32_e32 v7, v7
	s_nop 0
	v_add_f32_e32 v7, 1.0, v7
	v_rcp_f32_e32 v21, v7
	s_nop 0
	v_pk_mul_f32 v[18:19], v[20:21], v[18:19]
	s_nop 0
	v_pk_mul_f32 v[14:15], v[18:19], v[14:15]
	s_nop 0
	v_cvt_pk_bf16_f32 v12, v14, v15
	v_lshlrev_b32_e32 v14, 16, v13
	v_mul_f32_e32 v7, 0xbfb8aa3b, v14
	v_exp_f32_e32 v7, v7
	v_and_b32_e32 v15, 0xffff0000, v13
	v_add_f32_e32 v7, 1.0, v7
	v_rcp_f32_e32 v18, v7
	v_mul_f32_e32 v7, 0xbfb8aa3b, v15
	v_exp_f32_e32 v7, v7
	s_nop 0
	v_add_f32_e32 v7, 1.0, v7
	v_rcp_f32_e32 v19, v7
	v_pk_mul_f32 v[20:21], v[54:55], v[6:7] op_sel_hi:[1,0]
	v_pk_mul_f32 v[14:15], v[18:19], v[14:15]
	s_nop 0
	v_pk_mul_f32 v[14:15], v[14:15], v[16:17]
	v_pk_mul_f32 v[18:19], v[56:57], v[6:7] op_sel_hi:[1,0]
	v_cvt_pk_bf16_f32 v13, v14, v15
	global_store_dwordx2 v[8:9], v[12:13], off offset:96
	v_mov_b64_e32 v[16:17], v[214:215]
	v_mov_b64_e32 v[12:13], v[202:203]
	v_mov_b64_e32 v[14:15], v[204:205]
	v_pk_mul_f32 v[12:13], v[12:13], v[18:19]
	v_lshlrev_b32_e32 v18, 16, v16
	v_mul_f32_e32 v7, 0xbfb8aa3b, v18
	v_exp_f32_e32 v7, v7
	v_and_b32_e32 v19, 0xffff0000, v16
	v_pk_mul_f32 v[14:15], v[14:15], v[20:21]
	v_lshlrev_b32_e32 v16, 16, v17
	v_add_f32_e32 v7, 1.0, v7
	v_rcp_f32_e32 v20, v7
	v_mul_f32_e32 v7, 0xbfb8aa3b, v19
	v_exp_f32_e32 v7, v7
	v_and_b32_e32 v17, 0xffff0000, v17
	v_add_f32_e32 v7, 1.0, v7
	v_rcp_f32_e32 v21, v7
	v_mul_f32_e32 v7, 0xbfb8aa3b, v16
	v_exp_f32_e32 v7, v7
	v_pk_mul_f32 v[18:19], v[20:21], v[18:19]
	s_nop 0
	v_pk_mul_f32 v[12:13], v[18:19], v[12:13]
	v_add_f32_e32 v7, 1.0, v7
	v_rcp_f32_e32 v18, v7
	v_mul_f32_e32 v7, 0xbfb8aa3b, v17
	v_exp_f32_e32 v7, v7
	v_cvt_pk_bf16_f32 v12, v12, v13
	v_add_f32_e32 v7, 1.0, v7
	v_rcp_f32_e32 v19, v7
	v_pk_mul_f32 v[20:21], v[50:51], v[6:7] op_sel_hi:[1,0]
	v_pk_mul_f32 v[16:17], v[18:19], v[16:17]
	s_nop 0
	v_pk_mul_f32 v[14:15], v[16:17], v[14:15]
	v_pk_mul_f32 v[18:19], v[52:53], v[6:7] op_sel_hi:[1,0]
	v_cvt_pk_bf16_f32 v13, v14, v15
	global_store_dwordx2 v[8:9], v[12:13], off offset:128
	v_mov_b64_e32 v[16:17], v[216:217]
	v_mov_b64_e32 v[12:13], v[224:225]
	v_mov_b64_e32 v[14:15], v[226:227]
	v_pk_mul_f32 v[12:13], v[12:13], v[18:19]
	v_lshlrev_b32_e32 v18, 16, v16
	v_mul_f32_e32 v7, 0xbfb8aa3b, v18
	v_exp_f32_e32 v7, v7
	v_and_b32_e32 v19, 0xffff0000, v16
	v_pk_mul_f32 v[14:15], v[14:15], v[20:21]
	v_lshlrev_b32_e32 v16, 16, v17
	v_add_f32_e32 v7, 1.0, v7
	v_rcp_f32_e32 v20, v7
	v_mul_f32_e32 v7, 0xbfb8aa3b, v19
	v_exp_f32_e32 v7, v7
	v_and_b32_e32 v17, 0xffff0000, v17
	v_add_f32_e32 v7, 1.0, v7
	v_rcp_f32_e32 v21, v7
	v_mul_f32_e32 v7, 0xbfb8aa3b, v16
	v_exp_f32_e32 v7, v7
	v_pk_mul_f32 v[18:19], v[20:21], v[18:19]
	s_nop 0
	v_pk_mul_f32 v[12:13], v[18:19], v[12:13]
	v_add_f32_e32 v7, 1.0, v7
	v_rcp_f32_e32 v18, v7
	v_mul_f32_e32 v7, 0xbfb8aa3b, v17
	v_exp_f32_e32 v7, v7
	v_cvt_pk_bf16_f32 v12, v12, v13
	v_add_f32_e32 v7, 1.0, v7
	v_rcp_f32_e32 v19, v7
	v_pk_mul_f32 v[20:21], v[26:27], v[6:7] op_sel_hi:[1,0]
	v_pk_mul_f32 v[16:17], v[18:19], v[16:17]
	s_nop 0
	v_pk_mul_f32 v[14:15], v[16:17], v[14:15]
	v_pk_mul_f32 v[18:19], v[28:29], v[6:7] op_sel_hi:[1,0]
	v_cvt_pk_bf16_f32 v13, v14, v15
	global_store_dwordx2 v[8:9], v[12:13], off offset:160
	v_mov_b64_e32 v[16:17], v[218:219]
	v_mov_b64_e32 v[12:13], v[246:247]
	v_mov_b64_e32 v[14:15], v[248:249]
	v_pk_mul_f32 v[12:13], v[12:13], v[18:19]
	v_lshlrev_b32_e32 v18, 16, v16
	v_mul_f32_e32 v7, 0xbfb8aa3b, v18
	v_exp_f32_e32 v7, v7
	v_and_b32_e32 v19, 0xffff0000, v16
	v_pk_mul_f32 v[14:15], v[14:15], v[20:21]
	v_lshlrev_b32_e32 v16, 16, v17
	v_add_f32_e32 v7, 1.0, v7
	v_rcp_f32_e32 v20, v7
	v_mul_f32_e32 v7, 0xbfb8aa3b, v19
	v_exp_f32_e32 v7, v7
	v_and_b32_e32 v17, 0xffff0000, v17
	v_add_f32_e32 v7, 1.0, v7
	v_rcp_f32_e32 v21, v7
	v_mul_f32_e32 v7, 0xbfb8aa3b, v16
	v_exp_f32_e32 v7, v7
	v_pk_mul_f32 v[18:19], v[20:21], v[18:19]
	s_nop 0
	v_pk_mul_f32 v[12:13], v[18:19], v[12:13]
	v_add_f32_e32 v7, 1.0, v7
	v_rcp_f32_e32 v18, v7
	v_mul_f32_e32 v7, 0xbfb8aa3b, v17
	v_exp_f32_e32 v7, v7
	v_cvt_pk_bf16_f32 v12, v12, v13
	v_add_f32_e32 v7, 1.0, v7
	v_rcp_f32_e32 v19, v7
	v_pk_mul_f32 v[4:5], v[4:5], v[6:7] op_sel_hi:[1,0]
	v_pk_mul_f32 v[2:3], v[2:3], v[6:7] op_sel_hi:[1,0]
	v_pk_mul_f32 v[16:17], v[18:19], v[16:17]
	s_nop 0
	v_pk_mul_f32 v[14:15], v[16:17], v[14:15]
	s_nop 0
	v_cvt_pk_bf16_f32 v13, v14, v15
	global_store_dwordx2 v[8:9], v[12:13], off offset:192
	v_mov_b64_e32 v[12:13], v[220:221]
	v_mov_b64_e32 v[14:15], v[250:251]
	v_mov_b64_e32 v[16:17], v[252:253]
	v_lshlrev_b32_e32 v6, 16, v12
	v_and_b32_e32 v7, 0xffff0000, v12
	v_mul_f32_e32 v10, 0xbfb8aa3b, v6
	v_mul_f32_e32 v11, 0xbfb8aa3b, v7
	v_exp_f32_e32 v10, v10
	v_exp_f32_e32 v11, v11
	v_pk_mul_f32 v[4:5], v[14:15], v[4:5]
	v_pk_mul_f32 v[2:3], v[16:17], v[2:3]
	v_add_f32_e32 v10, 1.0, v10
	v_add_f32_e32 v11, 1.0, v11
	v_rcp_f32_e32 v10, v10
	v_rcp_f32_e32 v11, v11
	s_nop 0
	v_pk_mul_f32 v[6:7], v[10:11], v[6:7]
	s_nop 0
	v_pk_mul_f32 v[4:5], v[4:5], v[6:7]
	v_lshlrev_b32_e32 v6, 16, v13
	v_cvt_pk_bf16_f32 v4, v4, v5
	v_mul_f32_e32 v5, 0xbfb8aa3b, v6
	v_exp_f32_e32 v5, v5
	v_and_b32_e32 v7, 0xffff0000, v13
	v_add_f32_e32 v5, 1.0, v5
	v_rcp_f32_e32 v10, v5
	v_mul_f32_e32 v5, 0xbfb8aa3b, v7
	v_exp_f32_e32 v5, v5
	s_nop 0
	v_add_f32_e32 v5, 1.0, v5
	v_rcp_f32_e32 v11, v5
	s_nop 0
	v_pk_mul_f32 v[6:7], v[10:11], v[6:7]
	s_nop 0
	v_pk_mul_f32 v[2:3], v[2:3], v[6:7]
	s_nop 0
	v_cvt_pk_bf16_f32 v5, v2, v3
	global_store_dwordx2 v[8:9], v[4:5], off offset:224
	s_barrier
	s_cbranch_scc1 .LBB0_174
	v_readlane_b32 s96, v255, 10
	v_readlane_b32 s97, v255, 11
	v_readlane_b32 s74, v255, 8
	v_readlane_b32 s2, v255, 13
	v_readlane_b32 s75, v255, 9
	v_readlane_b32 s97, v255, 12
	v_readlane_b32 s93, v255, 19

.LBB0_290:
	s_add_u32 s26, s24, 0xfffc0080
	s_addc_u32 s27, s25, -1
	s_add_i32 s51, 0, 0x10000
	s_cmp_eq_u32 s50, 12
	s_cselect_b32 s29, s17, s27
	s_cselect_b32 s28, s46, s26
	s_cselect_b32 s27, s15, s49
	s_cselect_b32 s26, s47, s48
	s_add_i32 s54, 0, 0x14000
	v_add_u32_e32 v154, s51, v173
	v_add_u32_e32 v170, s54, v173
	ds_read_b128 v[130:133], v154
	ds_read_b128 v[134:137], v154 offset:1024
	ds_read_b128 v[138:141], v154 offset:2048
	ds_read_b128 v[154:157], v154 offset:3072
	ds_read_b128 v[158:161], v170
	ds_read_b128 v[162:165], v170 offset:1024
	ds_read_b128 v[166:169], v170 offset:2048
	ds_read_b128 v[176:179], v170 offset:3072
	v_lshl_add_u64 v[170:171], s[24:25], 0, v[150:151]
	s_add_i32 m0, s38, 0xc000
	ds_read_b128 v[180:183], v175
	ds_read_b128 v[184:187], v175 offset:1024
	ds_read_b128 v[192:195], v175 offset:2048
	ds_read_b128 v[196:199], v175 offset:3072
	ds_read_b128 v[200:203], v175 offset:4096
	ds_read_b128 v[204:207], v175 offset:5120
	ds_read_b128 v[208:211], v175 offset:6144
	ds_read_b128 v[212:215], v175 offset:7168
	global_load_lds_dwordx4 v[170:171], off
	v_lshl_add_u64 v[170:171], s[24:25], 0, v[152:153]
	s_add_i32 m0, s38, 0xe000
	s_nop 0
	global_load_lds_dwordx4 v[170:171], off
	s_waitcnt vmcnt(8)
	s_waitcnt lgkmcnt(0)
	s_barrier
	s_setprio 1
	s_waitcnt lgkmcnt(0)
	v_mfma_f32_16x16x32_bf16 v[126:129], v[130:133], v[180:183], v[126:129]
	v_mfma_f32_16x16x32_bf16 v[122:125], v[138:141], v[180:183], v[122:125]
	v_mfma_f32_16x16x32_bf16 v[110:113], v[130:133], v[192:195], v[110:113]
	v_mfma_f32_16x16x32_bf16 v[106:109], v[138:141], v[192:195], v[106:109]
	v_mfma_f32_16x16x32_bf16 v[94:97], v[130:133], v[200:203], v[94:97]
	v_mfma_f32_16x16x32_bf16 v[90:93], v[138:141], v[200:203], v[90:93]
	v_mfma_f32_16x16x32_bf16 v[78:81], v[130:133], v[208:211], v[78:81]
	v_mfma_f32_16x16x32_bf16 v[74:77], v[138:141], v[208:211], v[74:77]
	v_mfma_f32_16x16x32_bf16 v[126:129], v[134:137], v[184:187], v[126:129]
	v_mfma_f32_16x16x32_bf16 v[122:125], v[154:157], v[184:187], v[122:125]
	v_mfma_f32_16x16x32_bf16 v[110:113], v[134:137], v[196:199], v[110:113]
	v_mfma_f32_16x16x32_bf16 v[106:109], v[154:157], v[196:199], v[106:109]
	v_mfma_f32_16x16x32_bf16 v[94:97], v[134:137], v[204:207], v[94:97]
	v_mfma_f32_16x16x32_bf16 v[90:93], v[154:157], v[204:207], v[90:93]
	v_mfma_f32_16x16x32_bf16 v[78:81], v[134:137], v[212:215], v[78:81]
	v_mfma_f32_16x16x32_bf16 v[74:77], v[154:157], v[212:215], v[74:77]
	s_setprio 0
	s_setprio 1
	v_mfma_f32_16x16x32_bf16 v[118:121], v[158:161], v[180:183], v[118:121]
	v_mfma_f32_16x16x32_bf16 v[114:117], v[166:169], v[180:183], v[114:117]
	v_mfma_f32_16x16x32_bf16 v[102:105], v[158:161], v[192:195], v[102:105]
	v_mfma_f32_16x16x32_bf16 v[98:101], v[166:169], v[192:195], v[98:101]
	v_mfma_f32_16x16x32_bf16 v[86:89], v[158:161], v[200:203], v[86:89]
	v_mfma_f32_16x16x32_bf16 v[82:85], v[166:169], v[200:203], v[82:85]
	v_mfma_f32_16x16x32_bf16 v[70:73], v[158:161], v[208:211], v[70:73]
	v_mfma_f32_16x16x32_bf16 v[66:69], v[166:169], v[208:211], v[66:69]
	v_mfma_f32_16x16x32_bf16 v[118:121], v[162:165], v[184:187], v[118:121]
	v_mfma_f32_16x16x32_bf16 v[114:117], v[176:179], v[184:187], v[114:117]
	v_mfma_f32_16x16x32_bf16 v[102:105], v[162:165], v[196:199], v[102:105]
	v_mfma_f32_16x16x32_bf16 v[98:101], v[176:179], v[196:199], v[98:101]
	v_mfma_f32_16x16x32_bf16 v[86:89], v[162:165], v[204:207], v[86:89]
	v_mfma_f32_16x16x32_bf16 v[82:85], v[176:179], v[204:207], v[82:85]
	v_mfma_f32_16x16x32_bf16 v[70:73], v[162:165], v[212:215], v[70:73]
	v_mfma_f32_16x16x32_bf16 v[66:69], v[176:179], v[212:215], v[66:69]
	s_setprio 0
	s_barrier
	s_add_i32 s51, s51, s36
	v_lshl_add_u64 v[170:171], s[26:27], 0, v[0:1]
	s_mov_b32 m0, s51
	ds_read_b128 v[180:183], v175 offset:16384
	ds_read_b128 v[184:187], v175 offset:17408
	ds_read_b128 v[192:195], v175 offset:18432
	ds_read_b128 v[196:199], v175 offset:19456
	ds_read_b128 v[200:203], v175 offset:20480
	ds_read_b128 v[204:207], v175 offset:21504
	ds_read_b128 v[208:211], v175 offset:22528
	ds_read_b128 v[212:215], v175 offset:23552
	global_load_lds_dwordx4 v[170:171], off
	s_add_i32 m0, s51, 0x2000
	s_add_u32 s52, s26, 0x40000
	v_lshl_add_u64 v[188:189], s[26:27], 0, v[142:143]
	s_addc_u32 s53, s27, 0
	s_add_i32 s51, s54, s36
	global_load_lds_dwordx4 v[188:189], off
	v_lshl_add_u64 v[216:217], s[52:53], 0, v[0:1]
	s_mov_b32 m0, s51
	v_lshl_add_u64 v[218:219], s[28:29], 0, v[144:145]
	global_load_lds_dwordx4 v[216:217], off
	v_lshl_add_u64 v[216:217], s[52:53], 0, v[142:143]
	s_add_i32 m0, s51, 0x2000
	s_nop 0
	global_load_lds_dwordx4 v[216:217], off
	v_lshl_add_u64 v[216:217], s[28:29], 0, v[146:147]
	s_mov_b32 m0, s38
	s_nop 0
	global_load_lds_dwordx4 v[216:217], off
	s_mov_b32 m0, s39
	s_nop 0
	global_load_lds_dwordx4 v[218:219], off
	s_waitcnt vmcnt(8)
	s_waitcnt lgkmcnt(0)
	s_barrier
	s_setprio 1
	s_waitcnt lgkmcnt(0)
	v_mfma_f32_16x16x32_bf16 v[62:65], v[130:133], v[180:183], v[62:65]
	v_mfma_f32_16x16x32_bf16 v[58:61], v[138:141], v[180:183], v[58:61]
	v_mfma_f32_16x16x32_bf16 v[46:49], v[130:133], v[192:195], v[46:49]
	v_mfma_f32_16x16x32_bf16 v[42:45], v[138:141], v[192:195], v[42:45]
	v_mfma_f32_16x16x32_bf16 v[30:33], v[130:133], v[200:203], v[30:33]
	v_mfma_f32_16x16x32_bf16 v[26:29], v[138:141], v[200:203], v[26:29]
	v_mfma_f32_16x16x32_bf16 v[14:17], v[130:133], v[208:211], v[14:17]
	v_mfma_f32_16x16x32_bf16 v[10:13], v[138:141], v[208:211], v[10:13]
	v_mfma_f32_16x16x32_bf16 v[62:65], v[134:137], v[184:187], v[62:65]
	v_mfma_f32_16x16x32_bf16 v[58:61], v[154:157], v[184:187], v[58:61]
	v_mfma_f32_16x16x32_bf16 v[46:49], v[134:137], v[196:199], v[46:49]
	v_mfma_f32_16x16x32_bf16 v[42:45], v[154:157], v[196:199], v[42:45]
	v_mfma_f32_16x16x32_bf16 v[30:33], v[134:137], v[204:207], v[30:33]
	v_mfma_f32_16x16x32_bf16 v[26:29], v[154:157], v[204:207], v[26:29]
	v_mfma_f32_16x16x32_bf16 v[14:17], v[134:137], v[212:215], v[14:17]
	v_mfma_f32_16x16x32_bf16 v[10:13], v[154:157], v[212:215], v[10:13]
	s_setprio 0
	s_setprio 1
	v_mfma_f32_16x16x32_bf16 v[54:57], v[158:161], v[180:183], v[54:57]
	v_mfma_f32_16x16x32_bf16 v[50:53], v[166:169], v[180:183], v[50:53]
	v_mfma_f32_16x16x32_bf16 v[38:41], v[158:161], v[192:195], v[38:41]
	v_mfma_f32_16x16x32_bf16 v[34:37], v[166:169], v[192:195], v[34:37]
	v_mfma_f32_16x16x32_bf16 v[22:25], v[158:161], v[200:203], v[22:25]
	v_mfma_f32_16x16x32_bf16 v[18:21], v[166:169], v[200:203], v[18:21]
	v_mfma_f32_16x16x32_bf16 v[6:9], v[158:161], v[208:211], v[6:9]
	v_mfma_f32_16x16x32_bf16 v[2:5], v[166:169], v[208:211], v[2:5]
	v_mfma_f32_16x16x32_bf16 v[54:57], v[162:165], v[184:187], v[54:57]
	v_mfma_f32_16x16x32_bf16 v[50:53], v[176:179], v[184:187], v[50:53]
	v_mfma_f32_16x16x32_bf16 v[38:41], v[162:165], v[196:199], v[38:41]
	v_mfma_f32_16x16x32_bf16 v[34:37], v[176:179], v[196:199], v[34:37]
	v_mfma_f32_16x16x32_bf16 v[22:25], v[162:165], v[204:207], v[22:25]
	v_mfma_f32_16x16x32_bf16 v[18:21], v[176:179], v[204:207], v[18:21]
	v_mfma_f32_16x16x32_bf16 v[6:9], v[162:165], v[212:215], v[6:9]
	v_mfma_f32_16x16x32_bf16 v[2:5], v[176:179], v[212:215], v[2:5]
	s_setprio 0
	s_barrier
	s_add_i32 s51, 0, 0x18000
	s_add_i32 s52, 0, 0x1c000
	v_add_u32_e32 v154, s51, v173
	v_add_u32_e32 v176, s52, v173
	ds_read_b128 v[130:133], v154
	ds_read_b128 v[134:137], v154 offset:1024
	ds_read_b128 v[138:141], v154 offset:2048
	ds_read_b128 v[154:157], v154 offset:3072
	ds_read_b128 v[158:161], v176
	ds_read_b128 v[162:165], v176 offset:1024
	ds_read_b128 v[166:169], v176 offset:2048
	ds_read_b128 v[176:179], v176 offset:3072
	s_add_u32 s28, s28, 0x40000
	s_addc_u32 s29, s29, 0
	s_mov_b32 m0, s40
	v_lshl_add_u64 v[220:221], s[28:29], 0, v[146:147]
	ds_read_b128 v[180:183], v175 offset:32768
	ds_read_b128 v[184:187], v175 offset:33792
	ds_read_b128 v[192:195], v175 offset:34816
	ds_read_b128 v[196:199], v175 offset:35840
	ds_read_b128 v[200:203], v175 offset:36864
	ds_read_b128 v[204:207], v175 offset:37888
	ds_read_b128 v[208:211], v175 offset:38912
	ds_read_b128 v[212:215], v175 offset:39936
	global_load_lds_dwordx4 v[220:221], off
	v_lshl_add_u64 v[220:221], s[28:29], 0, v[144:145]
	s_mov_b32 m0, s41
	s_nop 0
	global_load_lds_dwordx4 v[220:221], off
	s_waitcnt vmcnt(8)
	s_waitcnt lgkmcnt(0)
	s_barrier
	s_setprio 1
	s_waitcnt lgkmcnt(0)
	v_mfma_f32_16x16x32_bf16 v[126:129], v[130:133], v[180:183], v[126:129]
	v_mfma_f32_16x16x32_bf16 v[122:125], v[138:141], v[180:183], v[122:125]
	v_mfma_f32_16x16x32_bf16 v[110:113], v[130:133], v[192:195], v[110:113]
	v_mfma_f32_16x16x32_bf16 v[106:109], v[138:141], v[192:195], v[106:109]
	v_mfma_f32_16x16x32_bf16 v[94:97], v[130:133], v[200:203], v[94:97]
	v_mfma_f32_16x16x32_bf16 v[90:93], v[138:141], v[200:203], v[90:93]
	v_mfma_f32_16x16x32_bf16 v[78:81], v[130:133], v[208:211], v[78:81]
	v_mfma_f32_16x16x32_bf16 v[74:77], v[138:141], v[208:211], v[74:77]
	v_mfma_f32_16x16x32_bf16 v[126:129], v[134:137], v[184:187], v[126:129]
	v_mfma_f32_16x16x32_bf16 v[122:125], v[154:157], v[184:187], v[122:125]
	v_mfma_f32_16x16x32_bf16 v[110:113], v[134:137], v[196:199], v[110:113]
	v_mfma_f32_16x16x32_bf16 v[106:109], v[154:157], v[196:199], v[106:109]
	v_mfma_f32_16x16x32_bf16 v[94:97], v[134:137], v[204:207], v[94:97]
	v_mfma_f32_16x16x32_bf16 v[90:93], v[154:157], v[204:207], v[90:93]
	v_mfma_f32_16x16x32_bf16 v[78:81], v[134:137], v[212:215], v[78:81]
	v_mfma_f32_16x16x32_bf16 v[74:77], v[154:157], v[212:215], v[74:77]
	s_setprio 0
	s_setprio 1
	v_mfma_f32_16x16x32_bf16 v[118:121], v[158:161], v[180:183], v[118:121]
	v_mfma_f32_16x16x32_bf16 v[114:117], v[166:169], v[180:183], v[114:117]
	v_mfma_f32_16x16x32_bf16 v[102:105], v[158:161], v[192:195], v[102:105]
	v_mfma_f32_16x16x32_bf16 v[98:101], v[166:169], v[192:195], v[98:101]
	v_mfma_f32_16x16x32_bf16 v[86:89], v[158:161], v[200:203], v[86:89]
	v_mfma_f32_16x16x32_bf16 v[82:85], v[166:169], v[200:203], v[82:85]
	v_mfma_f32_16x16x32_bf16 v[70:73], v[158:161], v[208:211], v[70:73]
	v_mfma_f32_16x16x32_bf16 v[66:69], v[166:169], v[208:211], v[66:69]
	v_mfma_f32_16x16x32_bf16 v[118:121], v[162:165], v[184:187], v[118:121]
	v_mfma_f32_16x16x32_bf16 v[114:117], v[176:179], v[184:187], v[114:117]
	v_mfma_f32_16x16x32_bf16 v[102:105], v[162:165], v[196:199], v[102:105]
	v_mfma_f32_16x16x32_bf16 v[98:101], v[176:179], v[196:199], v[98:101]
	v_mfma_f32_16x16x32_bf16 v[86:89], v[162:165], v[204:207], v[86:89]
	v_mfma_f32_16x16x32_bf16 v[82:85], v[176:179], v[204:207], v[82:85]
	v_mfma_f32_16x16x32_bf16 v[70:73], v[162:165], v[212:215], v[70:73]
	v_mfma_f32_16x16x32_bf16 v[66:69], v[176:179], v[212:215], v[66:69]
	s_setprio 0
	s_barrier
	s_add_i32 s28, s51, s36
	v_lshl_add_u64 v[170:171], v[170:171], 0, s[86:87]
	s_mov_b32 m0, s28
	ds_read_b128 v[180:183], v175 offset:49152
	ds_read_b128 v[184:187], v175 offset:50176
	ds_read_b128 v[192:195], v175 offset:51200
	ds_read_b128 v[196:199], v175 offset:52224
	ds_read_b128 v[200:203], v175 offset:53248
	ds_read_b128 v[204:207], v175 offset:54272
	ds_read_b128 v[208:211], v175 offset:55296
	ds_read_b128 v[212:215], v175 offset:56320
	global_load_lds_dwordx4 v[170:171], off
	s_add_i32 m0, s28, 0x2000
	s_add_u32 s26, s26, 0x40080
	v_lshl_add_u64 v[170:171], v[188:189], 0, s[86:87]
	s_addc_u32 s27, s27, 0
	s_add_i32 s28, s52, s36
	global_load_lds_dwordx4 v[170:171], off
	v_lshl_add_u64 v[170:171], s[26:27], 0, v[0:1]
	s_mov_b32 m0, s28
	s_nop 0
	global_load_lds_dwordx4 v[170:171], off
	v_lshl_add_u64 v[170:171], s[26:27], 0, v[142:143]
	s_add_i32 m0, s28, 0x2000
	s_nop 0
	global_load_lds_dwordx4 v[170:171], off
	v_lshl_add_u64 v[170:171], v[216:217], 0, s[86:87]
	s_mov_b32 m0, s42
	s_nop 0
	global_load_lds_dwordx4 v[170:171], off
	v_lshl_add_u64 v[170:171], v[218:219], 0, s[86:87]
	s_mov_b32 m0, s43
	s_nop 0
	global_load_lds_dwordx4 v[170:171], off
	s_waitcnt vmcnt(8)
	s_waitcnt lgkmcnt(0)
	s_barrier
	s_setprio 1
	s_waitcnt lgkmcnt(0)
	v_mfma_f32_16x16x32_bf16 v[62:65], v[130:133], v[180:183], v[62:65]
	v_mfma_f32_16x16x32_bf16 v[58:61], v[138:141], v[180:183], v[58:61]
	v_mfma_f32_16x16x32_bf16 v[46:49], v[130:133], v[192:195], v[46:49]
	v_mfma_f32_16x16x32_bf16 v[42:45], v[138:141], v[192:195], v[42:45]
	v_mfma_f32_16x16x32_bf16 v[30:33], v[130:133], v[200:203], v[30:33]
	v_mfma_f32_16x16x32_bf16 v[26:29], v[138:141], v[200:203], v[26:29]
	v_mfma_f32_16x16x32_bf16 v[14:17], v[130:133], v[208:211], v[14:17]
	v_mfma_f32_16x16x32_bf16 v[10:13], v[138:141], v[208:211], v[10:13]
	v_mfma_f32_16x16x32_bf16 v[62:65], v[134:137], v[184:187], v[62:65]
	v_mfma_f32_16x16x32_bf16 v[58:61], v[154:157], v[184:187], v[58:61]
	v_mfma_f32_16x16x32_bf16 v[46:49], v[134:137], v[196:199], v[46:49]
	v_mfma_f32_16x16x32_bf16 v[42:45], v[154:157], v[196:199], v[42:45]
	v_mfma_f32_16x16x32_bf16 v[30:33], v[134:137], v[204:207], v[30:33]
	v_mfma_f32_16x16x32_bf16 v[26:29], v[154:157], v[204:207], v[26:29]
	v_mfma_f32_16x16x32_bf16 v[14:17], v[134:137], v[212:215], v[14:17]
	v_mfma_f32_16x16x32_bf16 v[10:13], v[154:157], v[212:215], v[10:13]
	s_setprio 0
	s_setprio 1
	v_mfma_f32_16x16x32_bf16 v[54:57], v[158:161], v[180:183], v[54:57]
	v_mfma_f32_16x16x32_bf16 v[50:53], v[166:169], v[180:183], v[50:53]
	v_mfma_f32_16x16x32_bf16 v[38:41], v[158:161], v[192:195], v[38:41]
	v_mfma_f32_16x16x32_bf16 v[34:37], v[166:169], v[192:195], v[34:37]
	v_mfma_f32_16x16x32_bf16 v[22:25], v[158:161], v[200:203], v[22:25]
	v_mfma_f32_16x16x32_bf16 v[18:21], v[166:169], v[200:203], v[18:21]
	v_mfma_f32_16x16x32_bf16 v[6:9], v[158:161], v[208:211], v[6:9]
	v_mfma_f32_16x16x32_bf16 v[2:5], v[166:169], v[208:211], v[2:5]
	v_mfma_f32_16x16x32_bf16 v[54:57], v[162:165], v[184:187], v[54:57]
	v_mfma_f32_16x16x32_bf16 v[50:53], v[176:179], v[184:187], v[50:53]
	v_mfma_f32_16x16x32_bf16 v[38:41], v[162:165], v[196:199], v[38:41]
	v_mfma_f32_16x16x32_bf16 v[34:37], v[176:179], v[196:199], v[34:37]
	v_mfma_f32_16x16x32_bf16 v[22:25], v[162:165], v[204:207], v[22:25]
	v_mfma_f32_16x16x32_bf16 v[18:21], v[176:179], v[204:207], v[18:21]
	v_mfma_f32_16x16x32_bf16 v[6:9], v[162:165], v[212:215], v[6:9]
	v_mfma_f32_16x16x32_bf16 v[2:5], v[176:179], v[212:215], v[2:5]
	s_setprio 0
	s_barrier
	s_add_i32 s50, s50, 2
	s_add_u32 s24, s24, 0x100
	s_addc_u32 s25, s25, 0
	s_add_u32 s48, s48, 0x100
	s_addc_u32 s49, s49, 0
	s_cmp_gt_u32 s50, 13
	s_cbranch_scc0 .LBB0_290
	s_and_b64 vcc, exec, s[12:13]
	s_cbranch_vccz .LBB0_293
	s_barrier
.LBB0_293:
	v_lshl_add_u32 v168, s22, 8, v172
	v_ashrrev_i32_e32 v169, 31, v168
	v_lshlrev_b64 v[130:131], 6, v[168:169]
	v_lshl_add_u64 v[130:131], v[148:149], 0, v[130:131]
	global_load_dwordx4 v[176:179], v[130:131], off
	v_or_b32_e32 v166, 16, v168
	v_ashrrev_i32_e32 v167, 31, v166
	v_lshlrev_b64 v[130:131], 6, v[166:167]
	v_lshl_add_u64 v[130:131], v[148:149], 0, v[130:131]
	global_load_dwordx4 v[180:183], v[130:131], off
	v_or_b32_e32 v164, 32, v168
	v_ashrrev_i32_e32 v165, 31, v164
	v_lshlrev_b64 v[130:131], 6, v[164:165]
	v_lshl_add_u64 v[130:131], v[148:149], 0, v[130:131]
	global_load_dwordx4 v[184:187], v[130:131], off
	v_or_b32_e32 v162, 48, v168
	v_ashrrev_i32_e32 v163, 31, v162
	v_lshlrev_b64 v[130:131], 6, v[162:163]
	v_lshl_add_u64 v[130:131], v[148:149], 0, v[130:131]
	global_load_dwordx4 v[192:195], v[130:131], off
	v_add_u32_e32 v160, 0x80, v168
	v_ashrrev_i32_e32 v161, 31, v160
	v_lshlrev_b64 v[130:131], 6, v[160:161]
	v_add_u32_e32 v158, 0x90, v168
	v_lshl_add_u64 v[130:131], v[148:149], 0, v[130:131]
	v_ashrrev_i32_e32 v159, 31, v158
	global_load_dwordx4 v[196:199], v[130:131], off
	v_lshlrev_b64 v[130:131], 6, v[158:159]
	v_add_u32_e32 v156, 0xa0, v168
	v_lshl_add_u64 v[130:131], v[148:149], 0, v[130:131]
	v_ashrrev_i32_e32 v157, 31, v156
	global_load_dwordx4 v[138:141], v[130:131], off
	v_lshlrev_b64 v[130:131], 6, v[156:157]
	v_add_u32_e32 v154, 0xb0, v168
	v_lshl_add_u64 v[130:131], v[148:149], 0, v[130:131]
	v_ashrrev_i32_e32 v155, 31, v154
	global_load_dwordx4 v[134:137], v[130:131], off
	v_lshlrev_b64 v[130:131], 6, v[154:155]
	v_lshl_add_u64 v[130:131], v[148:149], 0, v[130:131]
	global_load_dwordx4 v[130:133], v[130:131], off
	v_cmp_lt_i32_e32 vcc, v239, v244
	v_lshl_or_b32 v170, s23, 7, v174
	v_ashrrev_i32_e32 v171, 31, v170
	v_cndmask_b32_e32 v155, v234, v239, vcc
	v_cmp_lt_i32_e32 vcc, v240, v244
	v_lshlrev_b32_e32 v163, 2, v155
	v_pk_mul_f32 v[116:117], v[124:125], v[116:117]
	v_cndmask_b32_e32 v155, v234, v240, vcc
	v_lshlrev_b32_e32 v165, 2, v155
	v_pk_mul_f32 v[114:115], v[122:123], v[114:115]
	v_pk_mul_f32 v[120:121], v[128:129], v[120:121]
	v_pk_mul_f32 v[118:119], v[126:127], v[118:119]
	v_pk_mul_f32 v[100:101], v[108:109], v[100:101]
	v_pk_mul_f32 v[98:99], v[106:107], v[98:99]
	v_pk_mul_f32 v[104:105], v[112:113], v[104:105]
	v_pk_mul_f32 v[102:103], v[110:111], v[102:103]
	v_pk_mul_f32 v[84:85], v[92:93], v[84:85]
	v_pk_mul_f32 v[82:83], v[90:91], v[82:83]
	v_pk_mul_f32 v[88:89], v[96:97], v[88:89]
	v_pk_mul_f32 v[86:87], v[94:95], v[86:87]
	v_pk_mul_f32 v[68:69], v[76:77], v[68:69]
	v_pk_mul_f32 v[66:67], v[74:75], v[66:67]
	v_pk_mul_f32 v[72:73], v[80:81], v[72:73]
	v_pk_mul_f32 v[70:71], v[78:79], v[70:71]
	v_pk_mul_f32 v[52:53], v[60:61], v[52:53]
	v_pk_mul_f32 v[50:51], v[58:59], v[50:51]
	v_pk_mul_f32 v[56:57], v[64:65], v[56:57]
	v_pk_mul_f32 v[54:55], v[62:63], v[54:55]
	v_pk_mul_f32 v[36:37], v[44:45], v[36:37]
	v_pk_mul_f32 v[34:35], v[42:43], v[34:35]
	v_pk_mul_f32 v[40:41], v[48:49], v[40:41]
	v_pk_mul_f32 v[38:39], v[46:47], v[38:39]
	v_pk_mul_f32 v[20:21], v[28:29], v[20:21]
	v_pk_mul_f32 v[18:19], v[26:27], v[18:19]
	v_pk_mul_f32 v[24:25], v[32:33], v[24:25]
	v_pk_mul_f32 v[22:23], v[30:31], v[22:23]
	v_pk_mul_f32 v[4:5], v[12:13], v[4:5]
	v_pk_mul_f32 v[2:3], v[10:11], v[2:3]
	v_pk_mul_f32 v[8:9], v[16:17], v[8:9]
	v_pk_mul_f32 v[6:7], v[14:15], v[6:7]
	s_andn2_b64 vcc, exec, s[6:7]
	s_waitcnt vmcnt(0)
	v_add_f32_e32 v176, v176, v177
	v_add_f32_e32 v178, v178, v179
	v_add_f32_e32 v180, v180, v181
	v_add_f32_e32 v182, v182, v183
	v_add_f32_e32 v184, v184, v185
	v_add_f32_e32 v186, v186, v187
	v_add_f32_e32 v192, v192, v193
	v_add_f32_e32 v194, v194, v195
	v_add_f32_e32 v176, v176, v178
	v_add_f32_e32 v180, v180, v182
	v_add_f32_e32 v184, v184, v186
	v_add_f32_e32 v192, v192, v194
	ds_bpermute_b32 v177, v163, v176
	ds_bpermute_b32 v181, v163, v180
	ds_bpermute_b32 v185, v163, v184
	ds_bpermute_b32 v193, v163, v192
	s_waitcnt lgkmcnt(3)
	v_add_f32_e32 v176, v176, v177
	ds_bpermute_b32 v177, v165, v176
	s_waitcnt lgkmcnt(3)
	v_add_f32_e32 v180, v180, v181
	ds_bpermute_b32 v181, v165, v180
	s_waitcnt lgkmcnt(3)
	v_add_f32_e32 v184, v184, v185
	ds_bpermute_b32 v185, v165, v184
	s_waitcnt lgkmcnt(3)
	v_add_f32_e32 v192, v192, v193
	ds_bpermute_b32 v193, v165, v192
	s_waitcnt lgkmcnt(3)
	v_add_f32_e32 v176, v176, v177
	s_waitcnt lgkmcnt(2)
	v_add_f32_e32 v180, v180, v181
	s_waitcnt lgkmcnt(1)
	v_add_f32_e32 v184, v184, v185
	s_waitcnt lgkmcnt(0)
	v_add_f32_e32 v192, v192, v193
	v_fmamk_f32 v176, v176, 0x3a800000, v223
	v_fmamk_f32 v180, v180, 0x3a800000, v223
	v_fmamk_f32 v184, v184, 0x3a800000, v223
	v_fmamk_f32 v192, v192, 0x3a800000, v223
	v_rsq_f32_e32 v167, v176
	v_rsq_f32_e32 v161, v180
	v_rsq_f32_e32 v159, v184
	v_rsq_f32_e32 v157, v192
	v_mov_b32_e32 v176, v197
	v_mov_b32_e32 v177, v198
	v_mov_b32_e32 v197, v199
	v_pk_add_f32 v[176:177], v[176:177], v[196:197]
	s_nop 0
	v_add_f32_e32 v155, v176, v177
	v_mov_b32_e32 v176, v139
	v_mov_b32_e32 v177, v140
	v_mov_b32_e32 v139, v141
	v_mov_b32_e32 v140, v135
	v_mov_b32_e32 v141, v136
	v_mov_b32_e32 v135, v137
	v_mov_b32_e32 v136, v131
	v_mov_b32_e32 v137, v132
	v_mov_b32_e32 v131, v133
	v_pk_add_f32 v[134:135], v[140:141], v[134:135]
	v_pk_add_f32 v[130:131], v[136:137], v[130:131]
	v_add_f32_e32 v134, v134, v135
	v_add_f32_e32 v130, v130, v131
	ds_bpermute_b32 v135, v163, v134
	ds_bpermute_b32 v131, v163, v130
	ds_bpermute_b32 v169, v163, v155
	v_mul_f32_e32 v140, 0xbfb8aa3b, v167
	v_pk_add_f32 v[138:139], v[176:177], v[138:139]
	s_waitcnt lgkmcnt(2)
	v_add_f32_e32 v134, v134, v135
	s_waitcnt lgkmcnt(1)
	v_add_f32_e32 v130, v130, v131
	v_lshlrev_b64 v[132:133], 1, v[170:171]
	v_pk_mul_f32 v[170:171], v[128:129], v[140:141] op_sel_hi:[1,0]
	v_pk_mul_f32 v[176:177], v[126:127], v[140:141] op_sel_hi:[1,0]
	ds_bpermute_b32 v135, v165, v134
	ds_bpermute_b32 v131, v165, v130
	v_pk_mul_f32 v[178:179], v[124:125], v[140:141] op_sel_hi:[1,0]
	v_pk_mul_f32 v[140:141], v[122:123], v[140:141] op_sel_hi:[1,0]
	v_exp_f32_e32 v176, v176
	v_exp_f32_e32 v177, v177
	v_exp_f32_e32 v170, v170
	v_exp_f32_e32 v171, v171
	v_exp_f32_e32 v140, v140
	v_exp_f32_e32 v141, v141
	v_exp_f32_e32 v178, v178
	v_exp_f32_e32 v179, v179
	s_waitcnt lgkmcnt(2)
	v_add_f32_e32 v155, v155, v169
	ds_bpermute_b32 v169, v165, v155
	v_pk_add_f32 v[170:171], v[170:171], 1.0 op_sel_hi:[1,0]
	v_pk_add_f32 v[176:177], v[176:177], 1.0 op_sel_hi:[1,0]
	s_waitcnt lgkmcnt(2)
	v_add_f32_e32 v134, v134, v135
	s_waitcnt lgkmcnt(1)
	v_add_f32_e32 v130, v130, v131
	v_pk_add_f32 v[178:179], v[178:179], 1.0 op_sel_hi:[1,0]
	v_pk_add_f32 v[140:141], v[140:141], 1.0 op_sel_hi:[1,0]
	v_rcp_f32_e32 v122, v176
	v_rcp_f32_e32 v123, v177
	v_rcp_f32_e32 v124, v170
	v_rcp_f32_e32 v125, v171
	v_fmamk_f32 v134, v134, 0x3a800000, v223
	v_fmamk_f32 v130, v130, 0x3a800000, v223
	v_rcp_f32_e32 v126, v140
	v_rcp_f32_e32 v127, v141
	v_rcp_f32_e32 v128, v178
	v_rcp_f32_e32 v129, v179
	v_rsq_f32_e32 v135, v134
	v_rsq_f32_e32 v134, v130
	v_mov_b64_e32 v[130:131], s[10:11]
	v_mad_i64_i32 v[136:137], s[22:23], v168, s57, v[130:131]
	v_mul_f32_e32 v168, v167, v167
	s_waitcnt lgkmcnt(0)
	v_pk_mul_f32 v[122:123], v[168:169], v[122:123] op_sel_hi:[0,1]
	v_pk_mul_f32 v[124:125], v[168:169], v[124:125] op_sel_hi:[0,1]
	v_pk_mul_f32 v[120:121], v[120:121], v[124:125]
	v_pk_mul_f32 v[118:119], v[118:119], v[122:123]
	v_pk_mul_f32 v[122:123], v[168:169], v[126:127] op_sel_hi:[0,1]
	v_pk_mul_f32 v[124:125], v[168:169], v[128:129] op_sel_hi:[0,1]
	v_pk_mul_f32 v[124:125], v[116:117], v[124:125]
	v_pk_mul_f32 v[116:117], v[114:115], v[122:123]
	v_lshl_add_u64 v[136:137], v[136:137], 0, v[132:133]
	v_cvt_pk_bf16_f32 v114, v118, v119
	v_cvt_pk_bf16_f32 v115, v120, v121
	v_cvt_pk_bf16_f32 v116, v116, v117
	v_cvt_pk_bf16_f32 v117, v124, v125
	global_store_dwordx4 v[136:137], v[114:117], off
	v_mul_f32_e32 v118, v161, v161
	v_add_f32_e32 v155, v155, v169
	v_mul_f32_e32 v116, 0xbfb8aa3b, v161
	v_pk_mul_f32 v[120:121], v[112:113], v[116:117] op_sel_hi:[1,0]
	v_pk_mul_f32 v[122:123], v[110:111], v[116:117] op_sel_hi:[1,0]
	v_pk_mul_f32 v[124:125], v[108:109], v[116:117] op_sel_hi:[1,0]
	v_pk_mul_f32 v[116:117], v[106:107], v[116:117] op_sel_hi:[1,0]
	v_exp_f32_e32 v122, v122
	v_exp_f32_e32 v123, v123
	v_exp_f32_e32 v120, v120
	v_exp_f32_e32 v121, v121
	v_exp_f32_e32 v116, v116
	v_exp_f32_e32 v117, v117
	v_exp_f32_e32 v124, v124
	v_exp_f32_e32 v125, v125
	v_pk_add_f32 v[120:121], v[120:121], 1.0 op_sel_hi:[1,0]
	v_pk_add_f32 v[122:123], v[122:123], 1.0 op_sel_hi:[1,0]
	v_pk_add_f32 v[116:117], v[116:117], 1.0 op_sel_hi:[1,0]
	v_pk_add_f32 v[124:125], v[124:125], 1.0 op_sel_hi:[1,0]
	v_rcp_f32_e32 v106, v122
	v_rcp_f32_e32 v107, v123
	v_rcp_f32_e32 v108, v120
	v_rcp_f32_e32 v109, v121
	v_rcp_f32_e32 v110, v116
	v_rcp_f32_e32 v111, v117
	v_rcp_f32_e32 v112, v124
	v_rcp_f32_e32 v113, v125
	v_pk_mul_f32 v[106:107], v[118:119], v[106:107] op_sel_hi:[0,1]
	v_pk_mul_f32 v[108:109], v[118:119], v[108:109] op_sel_hi:[0,1]
	v_pk_mul_f32 v[104:105], v[104:105], v[108:109]
	v_pk_mul_f32 v[102:103], v[102:103], v[106:107]
	v_pk_mul_f32 v[106:107], v[118:119], v[110:111] op_sel_hi:[0,1]
	v_pk_mul_f32 v[108:109], v[118:119], v[112:113] op_sel_hi:[0,1]
	v_mad_i64_i32 v[114:115], s[22:23], v166, s57, v[130:131]
	v_pk_mul_f32 v[108:109], v[100:101], v[108:109]
	v_pk_mul_f32 v[100:101], v[98:99], v[106:107]
	v_lshl_add_u64 v[114:115], v[114:115], 0, v[132:133]
	v_cvt_pk_bf16_f32 v98, v102, v103
	v_cvt_pk_bf16_f32 v99, v104, v105
	v_cvt_pk_bf16_f32 v100, v100, v101
	v_cvt_pk_bf16_f32 v101, v108, v109
	global_store_dwordx4 v[114:115], v[98:101], off
	v_mul_f32_e32 v102, v159, v159
	v_fmamk_f32 v155, v155, 0x3a800000, v223
	v_mul_f32_e32 v100, 0xbfb8aa3b, v159
	v_pk_mul_f32 v[104:105], v[96:97], v[100:101] op_sel_hi:[1,0]
	v_pk_mul_f32 v[106:107], v[94:95], v[100:101] op_sel_hi:[1,0]
	v_pk_mul_f32 v[108:109], v[92:93], v[100:101] op_sel_hi:[1,0]
	v_pk_mul_f32 v[100:101], v[90:91], v[100:101] op_sel_hi:[1,0]
	v_exp_f32_e32 v106, v106
	v_exp_f32_e32 v107, v107
	v_exp_f32_e32 v104, v104
	v_exp_f32_e32 v105, v105
	v_exp_f32_e32 v100, v100
	v_exp_f32_e32 v101, v101
	v_exp_f32_e32 v108, v108
	v_exp_f32_e32 v109, v109
	v_pk_add_f32 v[104:105], v[104:105], 1.0 op_sel_hi:[1,0]
	v_pk_add_f32 v[106:107], v[106:107], 1.0 op_sel_hi:[1,0]
	v_pk_add_f32 v[100:101], v[100:101], 1.0 op_sel_hi:[1,0]
	v_pk_add_f32 v[108:109], v[108:109], 1.0 op_sel_hi:[1,0]
	v_rcp_f32_e32 v90, v106
	v_rcp_f32_e32 v91, v107
	v_rcp_f32_e32 v92, v104
	v_rcp_f32_e32 v93, v105
	v_rcp_f32_e32 v94, v100
	v_rcp_f32_e32 v95, v101
	v_rcp_f32_e32 v96, v108
	v_rcp_f32_e32 v97, v109
	v_pk_mul_f32 v[90:91], v[102:103], v[90:91] op_sel_hi:[0,1]
	v_pk_mul_f32 v[92:93], v[102:103], v[92:93] op_sel_hi:[0,1]
	v_pk_mul_f32 v[88:89], v[88:89], v[92:93]
	v_pk_mul_f32 v[86:87], v[86:87], v[90:91]
	v_pk_mul_f32 v[90:91], v[102:103], v[94:95] op_sel_hi:[0,1]
	v_pk_mul_f32 v[92:93], v[102:103], v[96:97] op_sel_hi:[0,1]
	v_mad_i64_i32 v[98:99], s[22:23], v164, s57, v[130:131]
	v_pk_mul_f32 v[92:93], v[84:85], v[92:93]
	v_pk_mul_f32 v[84:85], v[82:83], v[90:91]
	v_lshl_add_u64 v[98:99], v[98:99], 0, v[132:133]
	v_cvt_pk_bf16_f32 v82, v86, v87
	v_cvt_pk_bf16_f32 v83, v88, v89
	v_cvt_pk_bf16_f32 v84, v84, v85
	v_cvt_pk_bf16_f32 v85, v92, v93
	global_store_dwordx4 v[98:99], v[82:85], off
	v_mul_f32_e32 v86, v157, v157
	v_rsq_f32_e32 v155, v155
	v_mul_f32_e32 v84, 0xbfb8aa3b, v157
	v_pk_mul_f32 v[88:89], v[80:81], v[84:85] op_sel_hi:[1,0]
	v_pk_mul_f32 v[90:91], v[78:79], v[84:85] op_sel_hi:[1,0]
	v_pk_mul_f32 v[92:93], v[76:77], v[84:85] op_sel_hi:[1,0]
	v_pk_mul_f32 v[84:85], v[74:75], v[84:85] op_sel_hi:[1,0]
	v_exp_f32_e32 v90, v90
	v_exp_f32_e32 v91, v91
	v_exp_f32_e32 v88, v88
	v_exp_f32_e32 v89, v89
	v_exp_f32_e32 v84, v84
	v_exp_f32_e32 v85, v85
	v_exp_f32_e32 v92, v92
	v_exp_f32_e32 v93, v93
	v_pk_add_f32 v[88:89], v[88:89], 1.0 op_sel_hi:[1,0]
	v_pk_add_f32 v[90:91], v[90:91], 1.0 op_sel_hi:[1,0]
	v_pk_add_f32 v[84:85], v[84:85], 1.0 op_sel_hi:[1,0]
	v_pk_add_f32 v[92:93], v[92:93], 1.0 op_sel_hi:[1,0]
	v_rcp_f32_e32 v74, v90
	v_rcp_f32_e32 v75, v91
	v_rcp_f32_e32 v76, v88
	v_rcp_f32_e32 v77, v89
	v_rcp_f32_e32 v78, v84
	v_rcp_f32_e32 v79, v85
	v_rcp_f32_e32 v80, v92
	v_rcp_f32_e32 v81, v93
	v_pk_mul_f32 v[74:75], v[86:87], v[74:75] op_sel_hi:[0,1]
	v_pk_mul_f32 v[76:77], v[86:87], v[76:77] op_sel_hi:[0,1]
	v_add_f32_e32 v138, v138, v139
	v_pk_mul_f32 v[72:73], v[72:73], v[76:77]
	v_pk_mul_f32 v[70:71], v[70:71], v[74:75]
	v_pk_mul_f32 v[74:75], v[86:87], v[78:79] op_sel_hi:[0,1]
	v_pk_mul_f32 v[76:77], v[86:87], v[80:81] op_sel_hi:[0,1]
	ds_bpermute_b32 v139, v163, v138
	v_mad_i64_i32 v[82:83], s[22:23], v162, s57, v[130:131]
	v_pk_mul_f32 v[76:77], v[68:69], v[76:77]
	v_pk_mul_f32 v[68:69], v[66:67], v[74:75]
	v_lshl_add_u64 v[82:83], v[82:83], 0, v[132:133]
	v_cvt_pk_bf16_f32 v66, v70, v71
	v_cvt_pk_bf16_f32 v67, v72, v73
	v_cvt_pk_bf16_f32 v68, v68, v69
	v_cvt_pk_bf16_f32 v69, v76, v77
	global_store_dwordx4 v[82:83], v[66:69], off
	s_waitcnt lgkmcnt(0)
	v_add_f32_e32 v138, v138, v139
	ds_bpermute_b32 v139, v165, v138
	v_mul_f32_e32 v68, 0xbfb8aa3b, v155
	v_pk_mul_f32 v[72:73], v[64:65], v[68:69] op_sel_hi:[1,0]
	v_pk_mul_f32 v[74:75], v[62:63], v[68:69] op_sel_hi:[1,0]
	v_pk_mul_f32 v[76:77], v[60:61], v[68:69] op_sel_hi:[1,0]
	v_pk_mul_f32 v[68:69], v[58:59], v[68:69] op_sel_hi:[1,0]
	v_exp_f32_e32 v74, v74
	v_exp_f32_e32 v75, v75
	v_exp_f32_e32 v72, v72
	v_exp_f32_e32 v73, v73
	v_exp_f32_e32 v68, v68
	v_exp_f32_e32 v69, v69
	v_exp_f32_e32 v76, v76
	v_exp_f32_e32 v77, v77
	v_pk_add_f32 v[72:73], v[72:73], 1.0 op_sel_hi:[1,0]
	v_pk_add_f32 v[74:75], v[74:75], 1.0 op_sel_hi:[1,0]
	v_pk_add_f32 v[68:69], v[68:69], 1.0 op_sel_hi:[1,0]
	v_pk_add_f32 v[76:77], v[76:77], 1.0 op_sel_hi:[1,0]
	v_rcp_f32_e32 v58, v74
	v_rcp_f32_e32 v59, v75
	v_rcp_f32_e32 v60, v72
	v_rcp_f32_e32 v61, v73
	v_rcp_f32_e32 v62, v68
	v_rcp_f32_e32 v63, v69
	v_rcp_f32_e32 v64, v76
	v_rcp_f32_e32 v65, v77
	s_waitcnt lgkmcnt(0)
	v_add_f32_e32 v138, v138, v139
	v_fmamk_f32 v138, v138, 0x3a800000, v223
	v_mul_f32_e32 v70, v155, v155
	v_rsq_f32_e32 v138, v138
	v_pk_mul_f32 v[58:59], v[70:71], v[58:59] op_sel_hi:[0,1]
	v_pk_mul_f32 v[60:61], v[70:71], v[60:61] op_sel_hi:[0,1]
	v_pk_mul_f32 v[56:57], v[56:57], v[60:61]
	v_pk_mul_f32 v[54:55], v[54:55], v[58:59]
	v_pk_mul_f32 v[58:59], v[70:71], v[62:63] op_sel_hi:[0,1]
	v_pk_mul_f32 v[60:61], v[70:71], v[64:65] op_sel_hi:[0,1]
	v_mad_i64_i32 v[66:67], s[22:23], v160, s57, v[130:131]
	v_pk_mul_f32 v[60:61], v[52:53], v[60:61]
	v_pk_mul_f32 v[52:53], v[50:51], v[58:59]
	v_lshl_add_u64 v[66:67], v[66:67], 0, v[132:133]
	v_cvt_pk_bf16_f32 v50, v54, v55
	v_cvt_pk_bf16_f32 v51, v56, v57
	v_cvt_pk_bf16_f32 v52, v52, v53
	v_cvt_pk_bf16_f32 v53, v60, v61
	global_store_dwordx4 v[66:67], v[50:53], off
	v_mul_f32_e32 v54, v138, v138
	s_nop 0
	v_mul_f32_e32 v52, 0xbfb8aa3b, v138
	v_pk_mul_f32 v[56:57], v[48:49], v[52:53] op_sel_hi:[1,0]
	v_pk_mul_f32 v[58:59], v[46:47], v[52:53] op_sel_hi:[1,0]
	v_pk_mul_f32 v[60:61], v[44:45], v[52:53] op_sel_hi:[1,0]
	v_pk_mul_f32 v[52:53], v[42:43], v[52:53] op_sel_hi:[1,0]
	v_exp_f32_e32 v58, v58
	v_exp_f32_e32 v59, v59
	v_exp_f32_e32 v56, v56
	v_exp_f32_e32 v57, v57
	v_exp_f32_e32 v52, v52
	v_exp_f32_e32 v53, v53
	v_exp_f32_e32 v60, v60
	v_exp_f32_e32 v61, v61
	v_pk_add_f32 v[56:57], v[56:57], 1.0 op_sel_hi:[1,0]
	v_pk_add_f32 v[58:59], v[58:59], 1.0 op_sel_hi:[1,0]
	v_pk_add_f32 v[52:53], v[52:53], 1.0 op_sel_hi:[1,0]
	v_pk_add_f32 v[60:61], v[60:61], 1.0 op_sel_hi:[1,0]
	v_rcp_f32_e32 v42, v58
	v_rcp_f32_e32 v43, v59
	v_rcp_f32_e32 v44, v56
	v_rcp_f32_e32 v45, v57
	v_rcp_f32_e32 v46, v52
	v_rcp_f32_e32 v47, v53
	v_rcp_f32_e32 v48, v60
	v_rcp_f32_e32 v49, v61
	v_pk_mul_f32 v[42:43], v[54:55], v[42:43] op_sel_hi:[0,1]
	v_pk_mul_f32 v[44:45], v[54:55], v[44:45] op_sel_hi:[0,1]
	v_pk_mul_f32 v[40:41], v[40:41], v[44:45]
	v_pk_mul_f32 v[38:39], v[38:39], v[42:43]
	v_pk_mul_f32 v[42:43], v[54:55], v[46:47] op_sel_hi:[0,1]
	v_pk_mul_f32 v[44:45], v[54:55], v[48:49] op_sel_hi:[0,1]
	v_mad_i64_i32 v[50:51], s[22:23], v158, s57, v[130:131]
	v_pk_mul_f32 v[44:45], v[36:37], v[44:45]
	v_pk_mul_f32 v[36:37], v[34:35], v[42:43]
	v_lshl_add_u64 v[50:51], v[50:51], 0, v[132:133]
	v_cvt_pk_bf16_f32 v34, v38, v39
	v_cvt_pk_bf16_f32 v35, v40, v41
	v_cvt_pk_bf16_f32 v36, v36, v37
	v_cvt_pk_bf16_f32 v37, v44, v45
	global_store_dwordx4 v[50:51], v[34:37], off
	v_mul_f32_e32 v38, v135, v135
	s_nop 0
	v_mul_f32_e32 v36, 0xbfb8aa3b, v135
	v_pk_mul_f32 v[40:41], v[32:33], v[36:37] op_sel_hi:[1,0]
	v_pk_mul_f32 v[42:43], v[30:31], v[36:37] op_sel_hi:[1,0]
	v_pk_mul_f32 v[44:45], v[28:29], v[36:37] op_sel_hi:[1,0]
	v_pk_mul_f32 v[36:37], v[26:27], v[36:37] op_sel_hi:[1,0]
	v_exp_f32_e32 v42, v42
	v_exp_f32_e32 v43, v43
	v_exp_f32_e32 v40, v40
	v_exp_f32_e32 v41, v41
	v_exp_f32_e32 v36, v36
	v_exp_f32_e32 v37, v37
	v_exp_f32_e32 v44, v44
	v_exp_f32_e32 v45, v45
	v_pk_add_f32 v[40:41], v[40:41], 1.0 op_sel_hi:[1,0]
	v_pk_add_f32 v[42:43], v[42:43], 1.0 op_sel_hi:[1,0]
	v_pk_add_f32 v[36:37], v[36:37], 1.0 op_sel_hi:[1,0]
	v_pk_add_f32 v[44:45], v[44:45], 1.0 op_sel_hi:[1,0]
	v_rcp_f32_e32 v26, v42
	v_rcp_f32_e32 v27, v43
	v_rcp_f32_e32 v28, v40
	v_rcp_f32_e32 v29, v41
	v_rcp_f32_e32 v30, v36
	v_rcp_f32_e32 v31, v37
	v_rcp_f32_e32 v32, v44
	v_rcp_f32_e32 v33, v45
	v_pk_mul_f32 v[26:27], v[38:39], v[26:27] op_sel_hi:[0,1]
	v_pk_mul_f32 v[28:29], v[38:39], v[28:29] op_sel_hi:[0,1]
	v_pk_mul_f32 v[24:25], v[24:25], v[28:29]
	v_pk_mul_f32 v[22:23], v[22:23], v[26:27]
	v_pk_mul_f32 v[26:27], v[38:39], v[30:31] op_sel_hi:[0,1]
	v_pk_mul_f32 v[28:29], v[38:39], v[32:33] op_sel_hi:[0,1]
	v_mad_i64_i32 v[34:35], s[22:23], v156, s57, v[130:131]
	v_pk_mul_f32 v[28:29], v[20:21], v[28:29]
	v_pk_mul_f32 v[20:21], v[18:19], v[26:27]
	v_lshl_add_u64 v[34:35], v[34:35], 0, v[132:133]
	v_cvt_pk_bf16_f32 v18, v22, v23
	v_cvt_pk_bf16_f32 v19, v24, v25
	v_cvt_pk_bf16_f32 v20, v20, v21
	v_cvt_pk_bf16_f32 v21, v28, v29
	global_store_dwordx4 v[34:35], v[18:21], off
	v_mul_f32_e32 v22, v134, v134
	s_nop 0
	v_mul_f32_e32 v20, 0xbfb8aa3b, v134
	v_pk_mul_f32 v[24:25], v[16:17], v[20:21] op_sel_hi:[1,0]
	v_pk_mul_f32 v[26:27], v[14:15], v[20:21] op_sel_hi:[1,0]
	v_pk_mul_f32 v[28:29], v[12:13], v[20:21] op_sel_hi:[1,0]
	v_pk_mul_f32 v[20:21], v[10:11], v[20:21] op_sel_hi:[1,0]
	v_exp_f32_e32 v26, v26
	v_exp_f32_e32 v27, v27
	v_exp_f32_e32 v24, v24
	v_exp_f32_e32 v25, v25
	v_exp_f32_e32 v20, v20
	v_exp_f32_e32 v21, v21
	v_exp_f32_e32 v28, v28
	v_exp_f32_e32 v29, v29
	v_pk_add_f32 v[24:25], v[24:25], 1.0 op_sel_hi:[1,0]
	v_pk_add_f32 v[26:27], v[26:27], 1.0 op_sel_hi:[1,0]
	v_pk_add_f32 v[20:21], v[20:21], 1.0 op_sel_hi:[1,0]
	v_pk_add_f32 v[28:29], v[28:29], 1.0 op_sel_hi:[1,0]
	v_rcp_f32_e32 v10, v26
	v_rcp_f32_e32 v11, v27
	v_rcp_f32_e32 v12, v24
	v_rcp_f32_e32 v13, v25
	v_rcp_f32_e32 v14, v20
	v_rcp_f32_e32 v15, v21
	v_rcp_f32_e32 v16, v28
	v_rcp_f32_e32 v17, v29
	v_pk_mul_f32 v[10:11], v[22:23], v[10:11] op_sel_hi:[0,1]
	v_pk_mul_f32 v[12:13], v[22:23], v[12:13] op_sel_hi:[0,1]
	v_pk_mul_f32 v[8:9], v[8:9], v[12:13]
	v_pk_mul_f32 v[6:7], v[6:7], v[10:11]
	v_pk_mul_f32 v[10:11], v[22:23], v[14:15] op_sel_hi:[0,1]
	v_pk_mul_f32 v[12:13], v[22:23], v[16:17] op_sel_hi:[0,1]
	v_mad_i64_i32 v[18:19], s[22:23], v154, s57, v[130:131]
	v_pk_mul_f32 v[12:13], v[4:5], v[12:13]
	v_pk_mul_f32 v[4:5], v[2:3], v[10:11]
	v_lshl_add_u64 v[18:19], v[18:19], 0, v[132:133]
	v_cvt_pk_bf16_f32 v2, v6, v7
	v_cvt_pk_bf16_f32 v3, v8, v9
	v_cvt_pk_bf16_f32 v4, v4, v5
	v_cvt_pk_bf16_f32 v5, v12, v13
	s_mov_b64 s[22:23], -1
	global_store_dwordx4 v[18:19], v[2:5], off
	s_cbranch_vccnz .LBB0_286
	s_andn2_b64 vcc, exec, s[8:9]
	s_cbranch_vccnz .LBB0_285
	s_barrier
	s_branch .LBB0_285

.LBB0_331:
	s_add_i32 s68, s34, 2
	s_add_u32 s69, s30, 0x80
	s_addc_u32 s35, s31, 0
	s_add_i32 s72, 0, 0x10000
	s_cmp_eq_u32 s51, s34
	s_cselect_b32 s35, s11, s35
	s_cselect_b32 s34, s10, s69
	s_cselect_b32 s71, s13, s67
	s_cselect_b32 s70, s12, s66
	s_add_i32 s69, 0, 0x14000
	v_add_u32_e32 v142, s72, v245
	v_add_u32_e32 v158, s69, v245
	ds_read_b128 v[130:133], v142
	ds_read_b128 v[134:137], v142 offset:1024
	ds_read_b128 v[138:141], v142 offset:2048
	ds_read_b128 v[142:145], v142 offset:3072
	ds_read_b128 v[146:149], v158
	ds_read_b128 v[150:153], v158 offset:1024
	ds_read_b128 v[154:157], v158 offset:2048
	ds_read_b128 v[158:161], v158 offset:3072
	v_lshl_add_u64 v[210:211], s[30:31], 0, v[198:199]
	s_add_i32 m0, s43, 0xc000
	ds_read_b128 v[162:165], v247
	ds_read_b128 v[166:169], v247 offset:1024
	ds_read_b128 v[170:173], v247 offset:2048
	ds_read_b128 v[174:177], v247 offset:3072
	ds_read_b128 v[178:181], v247 offset:4096
	ds_read_b128 v[182:185], v247 offset:5120
	ds_read_b128 v[202:205], v247 offset:6144
	ds_read_b128 v[206:209], v247 offset:7168
	global_load_lds_dwordx4 v[210:211], off
	v_lshl_add_u64 v[210:211], s[30:31], 0, v[200:201]
	s_add_i32 m0, s43, 0xe000
	s_nop 0
	global_load_lds_dwordx4 v[210:211], off
	s_waitcnt vmcnt(8)
	s_waitcnt lgkmcnt(0)
	s_barrier
	s_setprio 1
	s_waitcnt lgkmcnt(0)
	v_mfma_f32_16x16x32_bf16 v[126:129], v[130:133], v[162:165], v[126:129]
	v_mfma_f32_16x16x32_bf16 v[122:125], v[138:141], v[162:165], v[122:125]
	v_mfma_f32_16x16x32_bf16 v[110:113], v[130:133], v[170:173], v[110:113]
	v_mfma_f32_16x16x32_bf16 v[106:109], v[138:141], v[170:173], v[106:109]
	v_mfma_f32_16x16x32_bf16 v[94:97], v[130:133], v[178:181], v[94:97]
	v_mfma_f32_16x16x32_bf16 v[90:93], v[138:141], v[178:181], v[90:93]
	v_mfma_f32_16x16x32_bf16 v[78:81], v[130:133], v[202:205], v[78:81]
	v_mfma_f32_16x16x32_bf16 v[74:77], v[138:141], v[202:205], v[74:77]
	v_mfma_f32_16x16x32_bf16 v[126:129], v[134:137], v[166:169], v[126:129]
	v_mfma_f32_16x16x32_bf16 v[122:125], v[142:145], v[166:169], v[122:125]
	v_mfma_f32_16x16x32_bf16 v[110:113], v[134:137], v[174:177], v[110:113]
	v_mfma_f32_16x16x32_bf16 v[106:109], v[142:145], v[174:177], v[106:109]
	v_mfma_f32_16x16x32_bf16 v[94:97], v[134:137], v[182:185], v[94:97]
	v_mfma_f32_16x16x32_bf16 v[90:93], v[142:145], v[182:185], v[90:93]
	v_mfma_f32_16x16x32_bf16 v[78:81], v[134:137], v[206:209], v[78:81]
	v_mfma_f32_16x16x32_bf16 v[74:77], v[142:145], v[206:209], v[74:77]
	s_setprio 0
	s_setprio 1
	v_mfma_f32_16x16x32_bf16 v[118:121], v[146:149], v[162:165], v[118:121]
	v_mfma_f32_16x16x32_bf16 v[114:117], v[154:157], v[162:165], v[114:117]
	v_mfma_f32_16x16x32_bf16 v[102:105], v[146:149], v[170:173], v[102:105]
	v_mfma_f32_16x16x32_bf16 v[98:101], v[154:157], v[170:173], v[98:101]
	v_mfma_f32_16x16x32_bf16 v[86:89], v[146:149], v[178:181], v[86:89]
	v_mfma_f32_16x16x32_bf16 v[82:85], v[154:157], v[178:181], v[82:85]
	v_mfma_f32_16x16x32_bf16 v[70:73], v[146:149], v[202:205], v[70:73]
	v_mfma_f32_16x16x32_bf16 v[66:69], v[154:157], v[202:205], v[66:69]
	v_mfma_f32_16x16x32_bf16 v[118:121], v[150:153], v[166:169], v[118:121]
	v_mfma_f32_16x16x32_bf16 v[114:117], v[158:161], v[166:169], v[114:117]
	v_mfma_f32_16x16x32_bf16 v[102:105], v[150:153], v[174:177], v[102:105]
	v_mfma_f32_16x16x32_bf16 v[98:101], v[158:161], v[174:177], v[98:101]
	v_mfma_f32_16x16x32_bf16 v[86:89], v[150:153], v[182:185], v[86:89]
	v_mfma_f32_16x16x32_bf16 v[82:85], v[158:161], v[182:185], v[82:85]
	v_mfma_f32_16x16x32_bf16 v[70:73], v[150:153], v[206:209], v[70:73]
	v_mfma_f32_16x16x32_bf16 v[66:69], v[158:161], v[206:209], v[66:69]
	s_setprio 0
	s_barrier
	s_add_i32 s72, s72, s38
	v_lshl_add_u64 v[210:211], s[70:71], 0, v[0:1]
	s_mov_b32 m0, s72
	ds_read_b128 v[162:165], v247 offset:16384
	ds_read_b128 v[166:169], v247 offset:17408
	ds_read_b128 v[170:173], v247 offset:18432
	ds_read_b128 v[174:177], v247 offset:19456
	ds_read_b128 v[178:181], v247 offset:20480
	ds_read_b128 v[182:185], v247 offset:21504
	ds_read_b128 v[202:205], v247 offset:22528
	ds_read_b128 v[206:209], v247 offset:23552
	global_load_lds_dwordx4 v[210:211], off
	s_add_i32 m0, s72, 0x2000
	v_lshl_add_u64 v[212:213], s[70:71], 0, v[192:193]
	s_add_u32 s70, s70, s22
	s_addc_u32 s71, s71, 0
	s_add_i32 s69, s69, s38
	global_load_lds_dwordx4 v[212:213], off
	v_lshl_add_u64 v[214:215], s[70:71], 0, v[0:1]
	s_mov_b32 m0, s69
	v_lshl_add_u64 v[216:217], s[70:71], 0, v[192:193]
	global_load_lds_dwordx4 v[214:215], off
	s_add_i32 m0, s69, 0x2000
	v_lshl_add_u64 v[218:219], s[34:35], 0, v[186:187]
	global_load_lds_dwordx4 v[216:217], off
	s_mov_b32 m0, s43
	v_lshl_add_u64 v[220:221], s[34:35], 0, v[188:189]
	global_load_lds_dwordx4 v[218:219], off
	s_mov_b32 m0, s44
	s_nop 0
	global_load_lds_dwordx4 v[220:221], off
	s_waitcnt vmcnt(8)
	s_waitcnt lgkmcnt(0)
	s_barrier
	s_setprio 1
	s_waitcnt lgkmcnt(0)
	v_mfma_f32_16x16x32_bf16 v[62:65], v[130:133], v[162:165], v[62:65]
	v_mfma_f32_16x16x32_bf16 v[58:61], v[138:141], v[162:165], v[58:61]
	v_mfma_f32_16x16x32_bf16 v[46:49], v[130:133], v[170:173], v[46:49]
	v_mfma_f32_16x16x32_bf16 v[42:45], v[138:141], v[170:173], v[42:45]
	v_mfma_f32_16x16x32_bf16 v[30:33], v[130:133], v[178:181], v[30:33]
	v_mfma_f32_16x16x32_bf16 v[26:29], v[138:141], v[178:181], v[26:29]
	v_mfma_f32_16x16x32_bf16 v[14:17], v[130:133], v[202:205], v[14:17]
	v_mfma_f32_16x16x32_bf16 v[10:13], v[138:141], v[202:205], v[10:13]
	v_mfma_f32_16x16x32_bf16 v[62:65], v[134:137], v[166:169], v[62:65]
	v_mfma_f32_16x16x32_bf16 v[58:61], v[142:145], v[166:169], v[58:61]
	v_mfma_f32_16x16x32_bf16 v[46:49], v[134:137], v[174:177], v[46:49]
	v_mfma_f32_16x16x32_bf16 v[42:45], v[142:145], v[174:177], v[42:45]
	v_mfma_f32_16x16x32_bf16 v[30:33], v[134:137], v[182:185], v[30:33]
	v_mfma_f32_16x16x32_bf16 v[26:29], v[142:145], v[182:185], v[26:29]
	v_mfma_f32_16x16x32_bf16 v[14:17], v[134:137], v[206:209], v[14:17]
	v_mfma_f32_16x16x32_bf16 v[10:13], v[142:145], v[206:209], v[10:13]
	s_setprio 0
	s_setprio 1
	v_mfma_f32_16x16x32_bf16 v[54:57], v[146:149], v[162:165], v[54:57]
	v_mfma_f32_16x16x32_bf16 v[50:53], v[154:157], v[162:165], v[50:53]
	v_mfma_f32_16x16x32_bf16 v[38:41], v[146:149], v[170:173], v[38:41]
	v_mfma_f32_16x16x32_bf16 v[34:37], v[154:157], v[170:173], v[34:37]
	v_mfma_f32_16x16x32_bf16 v[22:25], v[146:149], v[178:181], v[22:25]
	v_mfma_f32_16x16x32_bf16 v[18:21], v[154:157], v[178:181], v[18:21]
	v_mfma_f32_16x16x32_bf16 v[6:9], v[146:149], v[202:205], v[6:9]
	v_mfma_f32_16x16x32_bf16 v[2:5], v[154:157], v[202:205], v[2:5]
	v_mfma_f32_16x16x32_bf16 v[54:57], v[150:153], v[166:169], v[54:57]
	v_mfma_f32_16x16x32_bf16 v[50:53], v[158:161], v[166:169], v[50:53]
	v_mfma_f32_16x16x32_bf16 v[38:41], v[150:153], v[174:177], v[38:41]
	v_mfma_f32_16x16x32_bf16 v[34:37], v[158:161], v[174:177], v[34:37]
	v_mfma_f32_16x16x32_bf16 v[22:25], v[150:153], v[182:185], v[22:25]
	v_mfma_f32_16x16x32_bf16 v[18:21], v[158:161], v[182:185], v[18:21]
	v_mfma_f32_16x16x32_bf16 v[6:9], v[150:153], v[206:209], v[6:9]
	v_mfma_f32_16x16x32_bf16 v[2:5], v[158:161], v[206:209], v[2:5]
	s_setprio 0
	s_barrier
	s_add_i32 s69, 0, 0x18000
	s_add_i32 s70, 0, 0x1c000
	v_add_u32_e32 v142, s69, v245
	v_add_u32_e32 v158, s70, v245
	ds_read_b128 v[130:133], v142
	ds_read_b128 v[134:137], v142 offset:1024
	ds_read_b128 v[138:141], v142 offset:2048
	ds_read_b128 v[142:145], v142 offset:3072
	ds_read_b128 v[146:149], v158
	ds_read_b128 v[150:153], v158 offset:1024
	ds_read_b128 v[154:157], v158 offset:2048
	ds_read_b128 v[158:161], v158 offset:3072
	s_add_u32 s34, s34, s22
	s_addc_u32 s35, s35, 0
	s_mov_b32 m0, s45
	v_lshl_add_u64 v[224:225], s[34:35], 0, v[186:187]
	ds_read_b128 v[162:165], v247 offset:32768
	ds_read_b128 v[166:169], v247 offset:33792
	ds_read_b128 v[170:173], v247 offset:34816
	ds_read_b128 v[174:177], v247 offset:35840
	ds_read_b128 v[178:181], v247 offset:36864
	ds_read_b128 v[182:185], v247 offset:37888
	ds_read_b128 v[202:205], v247 offset:38912
	ds_read_b128 v[206:209], v247 offset:39936
	global_load_lds_dwordx4 v[224:225], off
	v_lshl_add_u64 v[224:225], s[34:35], 0, v[188:189]
	s_mov_b32 m0, s46
	s_nop 0
	global_load_lds_dwordx4 v[224:225], off
	s_waitcnt vmcnt(8)
	s_waitcnt lgkmcnt(0)
	s_barrier
	s_setprio 1
	s_waitcnt lgkmcnt(0)
	v_mfma_f32_16x16x32_bf16 v[126:129], v[130:133], v[162:165], v[126:129]
	v_mfma_f32_16x16x32_bf16 v[122:125], v[138:141], v[162:165], v[122:125]
	v_mfma_f32_16x16x32_bf16 v[110:113], v[130:133], v[170:173], v[110:113]
	v_mfma_f32_16x16x32_bf16 v[106:109], v[138:141], v[170:173], v[106:109]
	v_mfma_f32_16x16x32_bf16 v[94:97], v[130:133], v[178:181], v[94:97]
	v_mfma_f32_16x16x32_bf16 v[90:93], v[138:141], v[178:181], v[90:93]
	v_mfma_f32_16x16x32_bf16 v[78:81], v[130:133], v[202:205], v[78:81]
	v_mfma_f32_16x16x32_bf16 v[74:77], v[138:141], v[202:205], v[74:77]
	v_mfma_f32_16x16x32_bf16 v[126:129], v[134:137], v[166:169], v[126:129]
	v_mfma_f32_16x16x32_bf16 v[122:125], v[142:145], v[166:169], v[122:125]
	v_mfma_f32_16x16x32_bf16 v[110:113], v[134:137], v[174:177], v[110:113]
	v_mfma_f32_16x16x32_bf16 v[106:109], v[142:145], v[174:177], v[106:109]
	v_mfma_f32_16x16x32_bf16 v[94:97], v[134:137], v[182:185], v[94:97]
	v_mfma_f32_16x16x32_bf16 v[90:93], v[142:145], v[182:185], v[90:93]
	v_mfma_f32_16x16x32_bf16 v[78:81], v[134:137], v[206:209], v[78:81]
	v_mfma_f32_16x16x32_bf16 v[74:77], v[142:145], v[206:209], v[74:77]
	s_setprio 0
	s_setprio 1
	v_mfma_f32_16x16x32_bf16 v[118:121], v[146:149], v[162:165], v[118:121]
	v_mfma_f32_16x16x32_bf16 v[114:117], v[154:157], v[162:165], v[114:117]
	v_mfma_f32_16x16x32_bf16 v[102:105], v[146:149], v[170:173], v[102:105]
	v_mfma_f32_16x16x32_bf16 v[98:101], v[154:157], v[170:173], v[98:101]
	v_mfma_f32_16x16x32_bf16 v[86:89], v[146:149], v[178:181], v[86:89]
	v_mfma_f32_16x16x32_bf16 v[82:85], v[154:157], v[178:181], v[82:85]
	v_mfma_f32_16x16x32_bf16 v[70:73], v[146:149], v[202:205], v[70:73]
	v_mfma_f32_16x16x32_bf16 v[66:69], v[154:157], v[202:205], v[66:69]
	v_mfma_f32_16x16x32_bf16 v[118:121], v[150:153], v[166:169], v[118:121]
	v_mfma_f32_16x16x32_bf16 v[114:117], v[158:161], v[166:169], v[114:117]
	v_mfma_f32_16x16x32_bf16 v[102:105], v[150:153], v[174:177], v[102:105]
	v_mfma_f32_16x16x32_bf16 v[98:101], v[158:161], v[174:177], v[98:101]
	v_mfma_f32_16x16x32_bf16 v[86:89], v[150:153], v[182:185], v[86:89]
	v_mfma_f32_16x16x32_bf16 v[82:85], v[158:161], v[182:185], v[82:85]
	v_mfma_f32_16x16x32_bf16 v[70:73], v[150:153], v[206:209], v[70:73]
	v_mfma_f32_16x16x32_bf16 v[66:69], v[158:161], v[206:209], v[66:69]
	s_setprio 0
	s_barrier
	s_add_i32 s34, s69, s38
	v_lshl_add_u64 v[210:211], v[210:211], 0, s[86:87]
	s_mov_b32 m0, s34
	ds_read_b128 v[162:165], v247 offset:49152
	ds_read_b128 v[166:169], v247 offset:50176
	ds_read_b128 v[170:173], v247 offset:51200
	ds_read_b128 v[174:177], v247 offset:52224
	ds_read_b128 v[178:181], v247 offset:53248
	ds_read_b128 v[182:185], v247 offset:54272
	ds_read_b128 v[202:205], v247 offset:55296
	ds_read_b128 v[206:209], v247 offset:56320
	global_load_lds_dwordx4 v[210:211], off
	v_lshl_add_u64 v[210:211], v[212:213], 0, s[86:87]
	s_add_i32 m0, s34, 0x2000
	s_add_i32 s34, s70, s38
	global_load_lds_dwordx4 v[210:211], off
	v_lshl_add_u64 v[210:211], v[214:215], 0, s[86:87]
	s_mov_b32 m0, s34
	s_nop 0
	global_load_lds_dwordx4 v[210:211], off
	v_lshl_add_u64 v[210:211], v[216:217], 0, s[86:87]
	s_add_i32 m0, s34, 0x2000
	s_nop 0
	global_load_lds_dwordx4 v[210:211], off
	v_lshl_add_u64 v[210:211], v[218:219], 0, s[86:87]
	s_mov_b32 m0, s49
	s_nop 0
	global_load_lds_dwordx4 v[210:211], off
	v_lshl_add_u64 v[210:211], v[220:221], 0, s[86:87]
	s_mov_b32 m0, s50
	s_nop 0
	global_load_lds_dwordx4 v[210:211], off
	s_waitcnt vmcnt(8)
	s_waitcnt lgkmcnt(0)
	s_barrier
	s_setprio 1
	s_waitcnt lgkmcnt(0)
	v_mfma_f32_16x16x32_bf16 v[62:65], v[130:133], v[162:165], v[62:65]
	v_mfma_f32_16x16x32_bf16 v[58:61], v[138:141], v[162:165], v[58:61]
	v_mfma_f32_16x16x32_bf16 v[46:49], v[130:133], v[170:173], v[46:49]
	v_mfma_f32_16x16x32_bf16 v[42:45], v[138:141], v[170:173], v[42:45]
	v_mfma_f32_16x16x32_bf16 v[30:33], v[130:133], v[178:181], v[30:33]
	v_mfma_f32_16x16x32_bf16 v[26:29], v[138:141], v[178:181], v[26:29]
	v_mfma_f32_16x16x32_bf16 v[14:17], v[130:133], v[202:205], v[14:17]
	v_mfma_f32_16x16x32_bf16 v[10:13], v[138:141], v[202:205], v[10:13]
	v_mfma_f32_16x16x32_bf16 v[62:65], v[134:137], v[166:169], v[62:65]
	v_mfma_f32_16x16x32_bf16 v[58:61], v[142:145], v[166:169], v[58:61]
	v_mfma_f32_16x16x32_bf16 v[46:49], v[134:137], v[174:177], v[46:49]
	v_mfma_f32_16x16x32_bf16 v[42:45], v[142:145], v[174:177], v[42:45]
	v_mfma_f32_16x16x32_bf16 v[30:33], v[134:137], v[182:185], v[30:33]
	v_mfma_f32_16x16x32_bf16 v[26:29], v[142:145], v[182:185], v[26:29]
	v_mfma_f32_16x16x32_bf16 v[14:17], v[134:137], v[206:209], v[14:17]
	v_mfma_f32_16x16x32_bf16 v[10:13], v[142:145], v[206:209], v[10:13]
	s_setprio 0
	s_setprio 1
	v_mfma_f32_16x16x32_bf16 v[54:57], v[146:149], v[162:165], v[54:57]
	v_mfma_f32_16x16x32_bf16 v[50:53], v[154:157], v[162:165], v[50:53]
	v_mfma_f32_16x16x32_bf16 v[38:41], v[146:149], v[170:173], v[38:41]
	v_mfma_f32_16x16x32_bf16 v[34:37], v[154:157], v[170:173], v[34:37]
	v_mfma_f32_16x16x32_bf16 v[22:25], v[146:149], v[178:181], v[22:25]
	v_mfma_f32_16x16x32_bf16 v[18:21], v[154:157], v[178:181], v[18:21]
	v_mfma_f32_16x16x32_bf16 v[6:9], v[146:149], v[202:205], v[6:9]
	v_mfma_f32_16x16x32_bf16 v[2:5], v[154:157], v[202:205], v[2:5]
	v_mfma_f32_16x16x32_bf16 v[54:57], v[150:153], v[166:169], v[54:57]
	v_mfma_f32_16x16x32_bf16 v[50:53], v[158:161], v[166:169], v[50:53]
	v_mfma_f32_16x16x32_bf16 v[38:41], v[150:153], v[174:177], v[38:41]
	v_mfma_f32_16x16x32_bf16 v[34:37], v[158:161], v[174:177], v[34:37]
	v_mfma_f32_16x16x32_bf16 v[22:25], v[150:153], v[182:185], v[22:25]
	v_mfma_f32_16x16x32_bf16 v[18:21], v[158:161], v[182:185], v[18:21]
	v_mfma_f32_16x16x32_bf16 v[6:9], v[150:153], v[206:209], v[6:9]
	v_mfma_f32_16x16x32_bf16 v[2:5], v[158:161], v[206:209], v[2:5]
	s_setprio 0
	s_barrier
	s_add_u32 s30, s30, 0x100
	s_addc_u32 s31, s31, 0
	s_add_u32 s66, s66, 0x100
	s_addc_u32 s67, s67, 0
	s_cmp_ge_u32 s68, s48
	s_mov_b32 s34, s68
	s_cbranch_scc0 .LBB0_331
	v_lshl_add_u32 v204, s65, 8, v191
	v_lshl_or_b32 v202, s64, 8, v246
	v_or_b32_e32 v210, 16, v204
	v_or_b32_e32 v208, 32, v204
	v_or_b32_e32 v206, 48, v204
	s_andn2_b64 vcc, exec, s[28:29]
	v_ashrrev_i32_e32 v203, 31, v202
	v_ashrrev_i32_e32 v205, 31, v204
	v_ashrrev_i32_e32 v211, 31, v210
	v_ashrrev_i32_e32 v209, 31, v208
	v_ashrrev_i32_e32 v207, 31, v206
	s_cbranch_vccnz .LBB0_350
	s_cmp_lt_i32 s65, 64
	s_cselect_b32 s30, s19, s17
	s_cselect_b32 s31, s18, s16
	v_mov_b32_e32 v130, s31
	v_mov_b32_e32 v131, s30
	v_lshl_add_u64 v[212:213], v[202:203], 2, v[130:131]
	v_lshlrev_b64 v[130:131], 12, v[204:205]
	v_lshl_add_u64 v[130:131], v[212:213], 0, v[130:131]
	global_load_dwordx4 v[182:185], v[130:131], off offset:16 nt
	global_load_dwordx4 v[214:217], v[130:131], off nt
	global_load_dwordx4 v[178:181], v[130:131], off offset:528 nt
	global_load_dwordx4 v[218:221], v[130:131], off offset:512 nt
	v_lshlrev_b64 v[130:131], 12, v[210:211]
	v_lshl_add_u64 v[130:131], v[212:213], 0, v[130:131]
	global_load_dwordx4 v[170:173], v[130:131], off offset:16 nt
	global_load_dwordx4 v[174:177], v[130:131], off nt
	global_load_dwordx4 v[162:165], v[130:131], off offset:528 nt
	global_load_dwordx4 v[166:169], v[130:131], off offset:512 nt
	v_lshlrev_b64 v[130:131], 12, v[208:209]
	v_lshl_add_u64 v[130:131], v[212:213], 0, v[130:131]
	global_load_dwordx4 v[154:157], v[130:131], off offset:16 nt
	global_load_dwordx4 v[158:161], v[130:131], off nt
	global_load_dwordx4 v[138:141], v[130:131], off offset:528 nt
	global_load_dwordx4 v[146:149], v[130:131], off offset:512 nt
	v_lshlrev_b64 v[130:131], 12, v[206:207]
	v_lshl_add_u64 v[134:135], v[212:213], 0, v[130:131]
	global_load_dwordx4 v[142:145], v[134:135], off offset:16 nt
	global_load_dwordx4 v[150:153], v[134:135], off nt
	global_load_dwordx4 v[130:133], v[134:135], off offset:528 nt
	s_nop 0
	global_load_dwordx4 v[134:137], v[134:135], off offset:512 nt
	v_cmp_lt_i32_e32 vcc, v239, v244
	v_lshlrev_b64 v[224:225], 11, v[204:205]
	s_lshl_b32 s30, s64, 2
	v_cndmask_b32_e32 v195, v234, v239, vcc
	v_cmp_lt_i32_e32 vcc, v240, v244
	v_lshlrev_b32_e32 v248, 2, v195
	s_ashr_i32 s31, s30, 31
	v_cndmask_b32_e32 v195, v234, v240, vcc
	v_lshlrev_b32_e32 v249, 2, v195
	v_mov_b32_e32 v195, v194
	s_waitcnt vmcnt(0)
	v_pk_fma_f32 v[226:227], v[194:195], v[124:125], v[184:185]
	v_pk_fma_f32 v[184:185], v[196:197], v[122:123], v[182:183]
	v_pk_fma_f32 v[216:217], v[194:195], v[128:129], v[216:217]
	v_pk_fma_f32 v[214:215], v[196:197], v[126:127], v[214:215]
	v_pk_mul_f32 v[182:183], v[226:227], v[226:227]
	v_pk_mul_f32 v[250:251], v[184:185], v[184:185]
	v_pk_fma_f32 v[182:183], v[216:217], v[216:217], v[182:183]
	v_pk_fma_f32 v[250:251], v[214:215], v[214:215], v[250:251]
	v_add_f32_e32 v182, v182, v183
	v_add_f32_e32 v232, v250, v251
	v_add_f32_e32 v232, v232, v182
	v_cvt_pk_bf16_f32 v182, v214, v215
	v_lshl_add_u64 v[214:215], s[26:27], 0, v[224:225]
	v_cvt_pk_bf16_f32 v183, v216, v217
	v_cvt_pk_bf16_f32 v184, v184, v185
	v_cvt_pk_bf16_f32 v185, v226, v227
	v_lshl_add_u64 v[214:215], v[202:203], 1, v[214:215]
	v_pk_fma_f32 v[216:217], v[194:195], v[116:117], v[180:181]
	v_pk_fma_f32 v[180:181], v[196:197], v[114:115], v[178:179]
	global_store_dwordx4 v[214:215], v[182:185], off
	v_pk_mul_f32 v[178:179], v[216:217], v[216:217]
	s_nop 0
	v_pk_fma_f32 v[182:183], v[194:195], v[120:121], v[220:221]
	v_pk_fma_f32 v[184:185], v[196:197], v[118:119], v[218:219]
	v_pk_mul_f32 v[218:219], v[180:181], v[180:181]
	v_pk_fma_f32 v[178:179], v[182:183], v[182:183], v[178:179]
	v_pk_fma_f32 v[218:219], v[184:185], v[184:185], v[218:219]
	v_add_f32_e32 v178, v178, v179
	v_add_f32_e32 v218, v218, v219
	v_add_f32_e32 v178, v218, v178
	v_add_f32_e32 v218, v232, v178
	v_cvt_pk_bf16_f32 v178, v184, v185
	v_cvt_pk_bf16_f32 v179, v182, v183
	v_cvt_pk_bf16_f32 v180, v180, v181
	v_cvt_pk_bf16_f32 v181, v216, v217
	global_store_dwordx4 v[214:215], v[178:181], off offset:256
	ds_bpermute_b32 v178, v248, v218
	s_waitcnt lgkmcnt(0)
	v_add_f32_e32 v178, v218, v178
	ds_bpermute_b32 v179, v249, v178
	s_and_saveexec_b64 s[34:35], s[6:7]
	s_cbranch_execz .LBB0_335
	v_lshlrev_b64 v[180:181], 6, v[204:205]
	v_lshl_add_u64 v[180:181], s[24:25], 0, v[180:181]
	v_lshl_add_u64 v[180:181], s[30:31], 2, v[180:181]
	s_lshl_b32 s84, s47, 2
	v_lshl_add_u64 v[180:181], v[180:181], 0, s[84:85]
	s_waitcnt lgkmcnt(0)
	v_add_f32_e32 v178, v178, v179
	global_store_dword v[180:181], v178, off

.LBB0_394:
	s_add_u32 s12, s10, 0xfffc0080
	s_addc_u32 s13, s11, -1
	s_add_i32 s47, 0, 0x10000
	s_cmp_eq_u32 s46, 12
	s_cselect_b32 s15, s31, s13
	s_cselect_b32 s14, s38, s12
	s_cselect_b32 s13, s29, s45
	s_cselect_b32 s12, s39, s44
	s_add_i32 s50, 0, 0x14000
	v_add_u32_e32 v62, s47, v182
	v_add_u32_e32 v174, s50, v182
	ds_read_b128 v[50:53], v62
	ds_read_b128 v[54:57], v62 offset:1024
	ds_read_b128 v[58:61], v62 offset:2048
	ds_read_b128 v[62:65], v62 offset:3072
	ds_read_b128 v[162:165], v174
	ds_read_b128 v[166:169], v174 offset:1024
	ds_read_b128 v[170:173], v174 offset:2048
	ds_read_b128 v[174:177], v174 offset:3072
	v_lshl_add_u64 v[216:217], s[10:11], 0, v[158:159]
	s_add_i32 m0, s41, 0xc000
	ds_read_b128 v[178:181], v184
	ds_read_b128 v[186:189], v184 offset:1024
	ds_read_b128 v[192:195], v184 offset:2048
	ds_read_b128 v[196:199], v184 offset:3072
	ds_read_b128 v[200:203], v184 offset:4096
	ds_read_b128 v[204:207], v184 offset:5120
	ds_read_b128 v[208:211], v184 offset:6144
	ds_read_b128 v[212:215], v184 offset:7168
	global_load_lds_dwordx4 v[216:217], off
	v_lshl_add_u64 v[216:217], s[10:11], 0, v[160:161]
	s_add_i32 m0, s41, 0xe000
	s_nop 0
	global_load_lds_dwordx4 v[216:217], off
	s_waitcnt vmcnt(8)
	s_waitcnt lgkmcnt(0)
	s_barrier
	s_setprio 1
	s_waitcnt lgkmcnt(0)
	v_mfma_f32_16x16x32_bf16 v[142:145], v[50:53], v[178:181], v[142:145]
	v_mfma_f32_16x16x32_bf16 v[138:141], v[58:61], v[178:181], v[138:141]
	v_mfma_f32_16x16x32_bf16 v[126:129], v[50:53], v[192:195], v[126:129]
	v_mfma_f32_16x16x32_bf16 v[122:125], v[58:61], v[192:195], v[122:125]
	v_mfma_f32_16x16x32_bf16 v[110:113], v[50:53], v[200:203], v[110:113]
	v_mfma_f32_16x16x32_bf16 v[106:109], v[58:61], v[200:203], v[106:109]
	v_mfma_f32_16x16x32_bf16 v[94:97], v[50:53], v[208:211], v[94:97]
	v_mfma_f32_16x16x32_bf16 v[90:93], v[58:61], v[208:211], v[90:93]
	v_mfma_f32_16x16x32_bf16 v[142:145], v[54:57], v[186:189], v[142:145]
	v_mfma_f32_16x16x32_bf16 v[138:141], v[62:65], v[186:189], v[138:141]
	v_mfma_f32_16x16x32_bf16 v[126:129], v[54:57], v[196:199], v[126:129]
	v_mfma_f32_16x16x32_bf16 v[122:125], v[62:65], v[196:199], v[122:125]
	v_mfma_f32_16x16x32_bf16 v[110:113], v[54:57], v[204:207], v[110:113]
	v_mfma_f32_16x16x32_bf16 v[106:109], v[62:65], v[204:207], v[106:109]
	v_mfma_f32_16x16x32_bf16 v[94:97], v[54:57], v[212:215], v[94:97]
	v_mfma_f32_16x16x32_bf16 v[90:93], v[62:65], v[212:215], v[90:93]
	s_setprio 0
	s_setprio 1
	v_mfma_f32_16x16x32_bf16 v[134:137], v[162:165], v[178:181], v[134:137]
	v_mfma_f32_16x16x32_bf16 v[130:133], v[170:173], v[178:181], v[130:133]
	v_mfma_f32_16x16x32_bf16 v[118:121], v[162:165], v[192:195], v[118:121]
	v_mfma_f32_16x16x32_bf16 v[114:117], v[170:173], v[192:195], v[114:117]
	v_mfma_f32_16x16x32_bf16 v[102:105], v[162:165], v[200:203], v[102:105]
	v_mfma_f32_16x16x32_bf16 v[98:101], v[170:173], v[200:203], v[98:101]
	v_mfma_f32_16x16x32_bf16 v[86:89], v[162:165], v[208:211], v[86:89]
	v_mfma_f32_16x16x32_bf16 v[82:85], v[170:173], v[208:211], v[82:85]
	v_mfma_f32_16x16x32_bf16 v[134:137], v[166:169], v[186:189], v[134:137]
	v_mfma_f32_16x16x32_bf16 v[130:133], v[174:177], v[186:189], v[130:133]
	v_mfma_f32_16x16x32_bf16 v[118:121], v[166:169], v[196:199], v[118:121]
	v_mfma_f32_16x16x32_bf16 v[114:117], v[174:177], v[196:199], v[114:117]
	v_mfma_f32_16x16x32_bf16 v[102:105], v[166:169], v[204:207], v[102:105]
	v_mfma_f32_16x16x32_bf16 v[98:101], v[174:177], v[204:207], v[98:101]
	v_mfma_f32_16x16x32_bf16 v[86:89], v[166:169], v[212:215], v[86:89]
	v_mfma_f32_16x16x32_bf16 v[82:85], v[174:177], v[212:215], v[82:85]
	s_setprio 0
	s_barrier
	s_add_i32 s47, s47, s68
	v_lshl_add_u64 v[216:217], s[12:13], 0, v[148:149]
	s_mov_b32 m0, s47
	ds_read_b128 v[178:181], v184 offset:16384
	ds_read_b128 v[186:189], v184 offset:17408
	ds_read_b128 v[192:195], v184 offset:18432
	ds_read_b128 v[196:199], v184 offset:19456
	ds_read_b128 v[200:203], v184 offset:20480
	ds_read_b128 v[204:207], v184 offset:21504
	ds_read_b128 v[208:211], v184 offset:22528
	ds_read_b128 v[212:215], v184 offset:23552
	global_load_lds_dwordx4 v[216:217], off
	s_add_i32 m0, s47, 0x2000
	s_add_u32 s48, s12, 0x40000
	v_lshl_add_u64 v[218:219], s[12:13], 0, v[152:153]
	s_addc_u32 s49, s13, 0
	s_add_i32 s47, s50, s68
	global_load_lds_dwordx4 v[218:219], off
	v_lshl_add_u64 v[220:221], s[48:49], 0, v[148:149]
	s_mov_b32 m0, s47
	v_lshl_add_u64 v[224:225], s[14:15], 0, v[150:151]
	global_load_lds_dwordx4 v[220:221], off
	v_lshl_add_u64 v[220:221], s[48:49], 0, v[152:153]
	s_add_i32 m0, s47, 0x2000
	s_nop 0
	global_load_lds_dwordx4 v[220:221], off
	v_lshl_add_u64 v[220:221], s[14:15], 0, v[146:147]
	s_mov_b32 m0, s41
	s_nop 0
	global_load_lds_dwordx4 v[220:221], off
	s_mov_b32 m0, s43
	s_nop 0
	global_load_lds_dwordx4 v[224:225], off
	s_waitcnt vmcnt(8)
	s_waitcnt lgkmcnt(0)
	s_barrier
	s_setprio 1
	s_waitcnt lgkmcnt(0)
	v_mfma_f32_16x16x32_bf16 v[78:81], v[50:53], v[178:181], v[78:81]
	v_mfma_f32_16x16x32_bf16 v[74:77], v[58:61], v[178:181], v[74:77]
	v_mfma_f32_16x16x32_bf16 v[46:49], v[50:53], v[192:195], v[46:49]
	v_mfma_f32_16x16x32_bf16 v[42:45], v[58:61], v[192:195], v[42:45]
	v_mfma_f32_16x16x32_bf16 v[30:33], v[50:53], v[200:203], v[30:33]
	v_mfma_f32_16x16x32_bf16 v[26:29], v[58:61], v[200:203], v[26:29]
	v_mfma_f32_16x16x32_bf16 v[14:17], v[50:53], v[208:211], v[14:17]
	v_mfma_f32_16x16x32_bf16 v[10:13], v[58:61], v[208:211], v[10:13]
	v_mfma_f32_16x16x32_bf16 v[78:81], v[54:57], v[186:189], v[78:81]
	v_mfma_f32_16x16x32_bf16 v[74:77], v[62:65], v[186:189], v[74:77]
	v_mfma_f32_16x16x32_bf16 v[46:49], v[54:57], v[196:199], v[46:49]
	v_mfma_f32_16x16x32_bf16 v[42:45], v[62:65], v[196:199], v[42:45]
	v_mfma_f32_16x16x32_bf16 v[30:33], v[54:57], v[204:207], v[30:33]
	v_mfma_f32_16x16x32_bf16 v[26:29], v[62:65], v[204:207], v[26:29]
	v_mfma_f32_16x16x32_bf16 v[14:17], v[54:57], v[212:215], v[14:17]
	v_mfma_f32_16x16x32_bf16 v[10:13], v[62:65], v[212:215], v[10:13]
	s_setprio 0
	s_setprio 1
	v_mfma_f32_16x16x32_bf16 v[38:41], v[162:165], v[192:195], v[38:41]
	v_mfma_f32_16x16x32_bf16 v[34:37], v[170:173], v[192:195], v[34:37]
	v_mfma_f32_16x16x32_bf16 v[22:25], v[162:165], v[200:203], v[22:25]
	v_mfma_f32_16x16x32_bf16 v[18:21], v[170:173], v[200:203], v[18:21]
	v_mfma_f32_16x16x32_bf16 v[6:9], v[162:165], v[208:211], v[6:9]
	v_mfma_f32_16x16x32_bf16 v[2:5], v[170:173], v[208:211], v[2:5]
	v_mfma_f32_16x16x32_bf16 v[50:53], v[162:165], v[178:181], v[70:73]
	v_mfma_f32_16x16x32_bf16 v[54:57], v[170:173], v[178:181], v[66:69]
	v_mfma_f32_16x16x32_bf16 v[38:41], v[166:169], v[196:199], v[38:41]
	v_mfma_f32_16x16x32_bf16 v[34:37], v[174:177], v[196:199], v[34:37]
	v_mfma_f32_16x16x32_bf16 v[22:25], v[166:169], v[204:207], v[22:25]
	v_mfma_f32_16x16x32_bf16 v[18:21], v[174:177], v[204:207], v[18:21]
	v_mfma_f32_16x16x32_bf16 v[6:9], v[166:169], v[212:215], v[6:9]
	v_mfma_f32_16x16x32_bf16 v[2:5], v[174:177], v[212:215], v[2:5]
	v_mfma_f32_16x16x32_bf16 v[50:53], v[166:169], v[186:189], v[50:53]
	v_mfma_f32_16x16x32_bf16 v[54:57], v[174:177], v[186:189], v[54:57]
	s_setprio 0
	s_barrier
	s_add_i32 s47, 0, 0x18000
	s_add_i32 s48, 0, 0x1c000
	v_add_u32_e32 v70, s47, v182
	v_add_u32_e32 v174, s48, v182
	ds_read_b128 v[58:61], v70
	ds_read_b128 v[62:65], v70 offset:1024
	ds_read_b128 v[66:69], v70 offset:2048
	ds_read_b128 v[70:73], v70 offset:3072
	ds_read_b128 v[162:165], v174
	ds_read_b128 v[166:169], v174 offset:1024
	ds_read_b128 v[170:173], v174 offset:2048
	ds_read_b128 v[174:177], v174 offset:3072
	s_add_u32 s14, s14, 0x40000
	s_addc_u32 s15, s15, 0
	s_mov_b32 m0, s69
	v_lshl_add_u64 v[226:227], s[14:15], 0, v[146:147]
	ds_read_b128 v[178:181], v184 offset:32768
	ds_read_b128 v[186:189], v184 offset:33792
	ds_read_b128 v[192:195], v184 offset:34816
	ds_read_b128 v[196:199], v184 offset:35840
	ds_read_b128 v[200:203], v184 offset:36864
	ds_read_b128 v[204:207], v184 offset:37888
	ds_read_b128 v[208:211], v184 offset:38912
	ds_read_b128 v[212:215], v184 offset:39936
	global_load_lds_dwordx4 v[226:227], off
	v_lshl_add_u64 v[226:227], s[14:15], 0, v[150:151]
	s_mov_b32 m0, s70
	s_nop 0
	global_load_lds_dwordx4 v[226:227], off
	s_waitcnt vmcnt(8)
	s_waitcnt lgkmcnt(0)
	s_barrier
	s_setprio 1
	s_waitcnt lgkmcnt(0)
	v_mfma_f32_16x16x32_bf16 v[142:145], v[58:61], v[178:181], v[142:145]
	v_mfma_f32_16x16x32_bf16 v[138:141], v[66:69], v[178:181], v[138:141]
	v_mfma_f32_16x16x32_bf16 v[126:129], v[58:61], v[192:195], v[126:129]
	v_mfma_f32_16x16x32_bf16 v[122:125], v[66:69], v[192:195], v[122:125]
	v_mfma_f32_16x16x32_bf16 v[110:113], v[58:61], v[200:203], v[110:113]
	v_mfma_f32_16x16x32_bf16 v[106:109], v[66:69], v[200:203], v[106:109]
	v_mfma_f32_16x16x32_bf16 v[94:97], v[58:61], v[208:211], v[94:97]
	v_mfma_f32_16x16x32_bf16 v[90:93], v[66:69], v[208:211], v[90:93]
	v_mfma_f32_16x16x32_bf16 v[142:145], v[62:65], v[186:189], v[142:145]
	v_mfma_f32_16x16x32_bf16 v[138:141], v[70:73], v[186:189], v[138:141]
	v_mfma_f32_16x16x32_bf16 v[126:129], v[62:65], v[196:199], v[126:129]
	v_mfma_f32_16x16x32_bf16 v[122:125], v[70:73], v[196:199], v[122:125]
	v_mfma_f32_16x16x32_bf16 v[110:113], v[62:65], v[204:207], v[110:113]
	v_mfma_f32_16x16x32_bf16 v[106:109], v[70:73], v[204:207], v[106:109]
	v_mfma_f32_16x16x32_bf16 v[94:97], v[62:65], v[212:215], v[94:97]
	v_mfma_f32_16x16x32_bf16 v[90:93], v[70:73], v[212:215], v[90:93]
	s_setprio 0
	s_setprio 1
	v_mfma_f32_16x16x32_bf16 v[134:137], v[162:165], v[178:181], v[134:137]
	v_mfma_f32_16x16x32_bf16 v[130:133], v[170:173], v[178:181], v[130:133]
	v_mfma_f32_16x16x32_bf16 v[118:121], v[162:165], v[192:195], v[118:121]
	v_mfma_f32_16x16x32_bf16 v[114:117], v[170:173], v[192:195], v[114:117]
	v_mfma_f32_16x16x32_bf16 v[102:105], v[162:165], v[200:203], v[102:105]
	v_mfma_f32_16x16x32_bf16 v[98:101], v[170:173], v[200:203], v[98:101]
	v_mfma_f32_16x16x32_bf16 v[86:89], v[162:165], v[208:211], v[86:89]
	v_mfma_f32_16x16x32_bf16 v[82:85], v[170:173], v[208:211], v[82:85]
	v_mfma_f32_16x16x32_bf16 v[134:137], v[166:169], v[186:189], v[134:137]
	v_mfma_f32_16x16x32_bf16 v[130:133], v[174:177], v[186:189], v[130:133]
	v_mfma_f32_16x16x32_bf16 v[118:121], v[166:169], v[196:199], v[118:121]
	v_mfma_f32_16x16x32_bf16 v[114:117], v[174:177], v[196:199], v[114:117]
	v_mfma_f32_16x16x32_bf16 v[102:105], v[166:169], v[204:207], v[102:105]
	v_mfma_f32_16x16x32_bf16 v[98:101], v[174:177], v[204:207], v[98:101]
	v_mfma_f32_16x16x32_bf16 v[86:89], v[166:169], v[212:215], v[86:89]
	v_mfma_f32_16x16x32_bf16 v[82:85], v[174:177], v[212:215], v[82:85]
	s_setprio 0
	s_barrier
	s_add_i32 s14, s47, s68
	v_lshl_add_u64 v[216:217], v[216:217], 0, s[86:87]
	s_mov_b32 m0, s14
	ds_read_b128 v[178:181], v184 offset:49152
	ds_read_b128 v[186:189], v184 offset:50176
	ds_read_b128 v[192:195], v184 offset:51200
	ds_read_b128 v[196:199], v184 offset:52224
	ds_read_b128 v[200:203], v184 offset:53248
	ds_read_b128 v[204:207], v184 offset:54272
	ds_read_b128 v[208:211], v184 offset:55296
	ds_read_b128 v[212:215], v184 offset:56320
	global_load_lds_dwordx4 v[216:217], off
	s_add_i32 m0, s14, 0x2000
	s_add_u32 s12, s12, 0x40080
	v_lshl_add_u64 v[216:217], v[218:219], 0, s[86:87]
	s_addc_u32 s13, s13, 0
	s_add_i32 s14, s48, s68
	global_load_lds_dwordx4 v[216:217], off
	v_lshl_add_u64 v[216:217], s[12:13], 0, v[148:149]
	s_mov_b32 m0, s14
	s_nop 0
	global_load_lds_dwordx4 v[216:217], off
	v_lshl_add_u64 v[216:217], s[12:13], 0, v[152:153]
	s_add_i32 m0, s14, 0x2000
	s_nop 0
	global_load_lds_dwordx4 v[216:217], off
	v_lshl_add_u64 v[216:217], v[220:221], 0, s[86:87]
	s_mov_b32 m0, s73
	s_nop 0
	global_load_lds_dwordx4 v[216:217], off
	v_lshl_add_u64 v[216:217], v[224:225], 0, s[86:87]
	s_mov_b32 m0, s74
	s_nop 0
	global_load_lds_dwordx4 v[216:217], off
	s_waitcnt vmcnt(8)
	s_waitcnt lgkmcnt(0)
	s_barrier
	s_setprio 1
	s_waitcnt lgkmcnt(0)
	v_mfma_f32_16x16x32_bf16 v[78:81], v[58:61], v[178:181], v[78:81]
	v_mfma_f32_16x16x32_bf16 v[74:77], v[66:69], v[178:181], v[74:77]
	v_mfma_f32_16x16x32_bf16 v[46:49], v[58:61], v[192:195], v[46:49]
	v_mfma_f32_16x16x32_bf16 v[42:45], v[66:69], v[192:195], v[42:45]
	v_mfma_f32_16x16x32_bf16 v[30:33], v[58:61], v[200:203], v[30:33]
	v_mfma_f32_16x16x32_bf16 v[26:29], v[66:69], v[200:203], v[26:29]
	v_mfma_f32_16x16x32_bf16 v[14:17], v[58:61], v[208:211], v[14:17]
	v_mfma_f32_16x16x32_bf16 v[10:13], v[66:69], v[208:211], v[10:13]
	v_mfma_f32_16x16x32_bf16 v[78:81], v[62:65], v[186:189], v[78:81]
	v_mfma_f32_16x16x32_bf16 v[74:77], v[70:73], v[186:189], v[74:77]
	v_mfma_f32_16x16x32_bf16 v[46:49], v[62:65], v[196:199], v[46:49]
	v_mfma_f32_16x16x32_bf16 v[42:45], v[70:73], v[196:199], v[42:45]
	v_mfma_f32_16x16x32_bf16 v[30:33], v[62:65], v[204:207], v[30:33]
	v_mfma_f32_16x16x32_bf16 v[26:29], v[70:73], v[204:207], v[26:29]
	v_mfma_f32_16x16x32_bf16 v[14:17], v[62:65], v[212:215], v[14:17]
	v_mfma_f32_16x16x32_bf16 v[10:13], v[70:73], v[212:215], v[10:13]
	s_setprio 0
	s_setprio 1
	v_mfma_f32_16x16x32_bf16 v[50:53], v[162:165], v[178:181], v[50:53]
	v_mfma_f32_16x16x32_bf16 v[70:73], v[166:169], v[186:189], v[50:53]
	v_mfma_f32_16x16x32_bf16 v[50:53], v[170:173], v[178:181], v[54:57]
	v_mfma_f32_16x16x32_bf16 v[38:41], v[162:165], v[192:195], v[38:41]
	v_mfma_f32_16x16x32_bf16 v[34:37], v[170:173], v[192:195], v[34:37]
	v_mfma_f32_16x16x32_bf16 v[22:25], v[162:165], v[200:203], v[22:25]
	v_mfma_f32_16x16x32_bf16 v[18:21], v[170:173], v[200:203], v[18:21]
	v_mfma_f32_16x16x32_bf16 v[6:9], v[162:165], v[208:211], v[6:9]
	v_mfma_f32_16x16x32_bf16 v[2:5], v[170:173], v[208:211], v[2:5]
	v_mfma_f32_16x16x32_bf16 v[66:69], v[174:177], v[186:189], v[50:53]
	v_mfma_f32_16x16x32_bf16 v[38:41], v[166:169], v[196:199], v[38:41]
	v_mfma_f32_16x16x32_bf16 v[34:37], v[174:177], v[196:199], v[34:37]
	v_mfma_f32_16x16x32_bf16 v[22:25], v[166:169], v[204:207], v[22:25]
	v_mfma_f32_16x16x32_bf16 v[18:21], v[174:177], v[204:207], v[18:21]
	v_mfma_f32_16x16x32_bf16 v[6:9], v[166:169], v[212:215], v[6:9]
	v_mfma_f32_16x16x32_bf16 v[2:5], v[174:177], v[212:215], v[2:5]
	s_setprio 0
	s_barrier
	s_add_i32 s46, s46, 2
	s_add_u32 s10, s10, 0x100
	s_addc_u32 s11, s11, 0
	s_add_u32 s44, s44, 0x100
	s_addc_u32 s45, s45, 0
	s_cmp_gt_u32 s46, 13
	s_cbranch_scc0 .LBB0_394
	s_and_b64 vcc, exec, s[24:25]
	s_cbranch_vccz .LBB0_397
	s_barrier

.LBB0_458:
	s_add_i32 s69, s38, 2
	s_add_u32 s70, s36, 0x80
	s_addc_u32 s39, s37, 0
	s_add_i32 s72, 0, 0x10000
	s_cmp_eq_u32 s63, s38
	s_cselect_b32 s39, s27, s39
	s_cselect_b32 s38, s35, s70
	s_cselect_b32 s71, s25, s68
	s_cselect_b32 s70, s66, s67
	s_add_i32 s73, 0, 0x14000
	v_add_u32_e32 v142, s72, v201
	v_add_u32_e32 v158, s73, v201
	ds_read_b128 v[130:133], v142
	ds_read_b128 v[134:137], v142 offset:1024
	ds_read_b128 v[138:141], v142 offset:2048
	ds_read_b128 v[142:145], v142 offset:3072
	ds_read_b128 v[146:149], v158
	ds_read_b128 v[150:153], v158 offset:1024
	ds_read_b128 v[154:157], v158 offset:2048
	ds_read_b128 v[158:161], v158 offset:3072
	v_lshl_add_u64 v[202:203], s[36:37], 0, v[182:183]
	s_add_i32 m0, s23, 0xc000
	ds_read_b128 v[162:165], v209
	ds_read_b128 v[166:169], v209 offset:1024
	ds_read_b128 v[170:173], v209 offset:2048
	ds_read_b128 v[186:189], v209 offset:3072
	ds_read_b128 v[192:195], v209 offset:4096
	ds_read_b128 v[196:199], v209 offset:5120
	ds_read_b128 v[210:213], v209 offset:6144
	ds_read_b128 v[214:217], v209 offset:7168
	global_load_lds_dwordx4 v[202:203], off
	v_lshl_add_u64 v[202:203], s[36:37], 0, v[184:185]
	s_add_i32 m0, s23, 0xe000
	s_nop 0
	global_load_lds_dwordx4 v[202:203], off
	s_waitcnt vmcnt(8)
	s_waitcnt lgkmcnt(0)
	s_barrier
	s_setprio 1
	s_waitcnt lgkmcnt(0)
	v_mfma_f32_16x16x32_bf16 v[126:129], v[130:133], v[162:165], v[126:129]
	v_mfma_f32_16x16x32_bf16 v[122:125], v[138:141], v[162:165], v[122:125]
	v_mfma_f32_16x16x32_bf16 v[118:121], v[130:133], v[170:173], v[118:121]
	v_mfma_f32_16x16x32_bf16 v[114:117], v[138:141], v[170:173], v[114:117]
	v_mfma_f32_16x16x32_bf16 v[110:113], v[130:133], v[192:195], v[110:113]
	v_mfma_f32_16x16x32_bf16 v[106:109], v[138:141], v[192:195], v[106:109]
	v_mfma_f32_16x16x32_bf16 v[102:105], v[130:133], v[210:213], v[102:105]
	v_mfma_f32_16x16x32_bf16 v[98:101], v[138:141], v[210:213], v[98:101]
	v_mfma_f32_16x16x32_bf16 v[126:129], v[134:137], v[166:169], v[126:129]
	v_mfma_f32_16x16x32_bf16 v[122:125], v[142:145], v[166:169], v[122:125]
	v_mfma_f32_16x16x32_bf16 v[118:121], v[134:137], v[186:189], v[118:121]
	v_mfma_f32_16x16x32_bf16 v[114:117], v[142:145], v[186:189], v[114:117]
	v_mfma_f32_16x16x32_bf16 v[110:113], v[134:137], v[196:199], v[110:113]
	v_mfma_f32_16x16x32_bf16 v[106:109], v[142:145], v[196:199], v[106:109]
	v_mfma_f32_16x16x32_bf16 v[102:105], v[134:137], v[214:217], v[102:105]
	v_mfma_f32_16x16x32_bf16 v[98:101], v[142:145], v[214:217], v[98:101]
	s_setprio 0
	s_setprio 1
	v_mfma_f32_16x16x32_bf16 v[82:85], v[146:149], v[162:165], v[82:85]
	v_mfma_f32_16x16x32_bf16 v[74:77], v[154:157], v[162:165], v[74:77]
	v_mfma_f32_16x16x32_bf16 v[70:73], v[146:149], v[170:173], v[70:73]
	v_mfma_f32_16x16x32_bf16 v[62:65], v[154:157], v[170:173], v[62:65]
	v_mfma_f32_16x16x32_bf16 v[54:57], v[146:149], v[192:195], v[54:57]
	v_mfma_f32_16x16x32_bf16 v[50:53], v[154:157], v[192:195], v[50:53]
	v_mfma_f32_16x16x32_bf16 v[38:41], v[146:149], v[210:213], v[38:41]
	v_mfma_f32_16x16x32_bf16 v[34:37], v[154:157], v[210:213], v[34:37]
	v_mfma_f32_16x16x32_bf16 v[82:85], v[150:153], v[166:169], v[82:85]
	v_mfma_f32_16x16x32_bf16 v[74:77], v[158:161], v[166:169], v[74:77]
	v_mfma_f32_16x16x32_bf16 v[70:73], v[150:153], v[186:189], v[70:73]
	v_mfma_f32_16x16x32_bf16 v[62:65], v[158:161], v[186:189], v[62:65]
	v_mfma_f32_16x16x32_bf16 v[54:57], v[150:153], v[196:199], v[54:57]
	v_mfma_f32_16x16x32_bf16 v[50:53], v[158:161], v[196:199], v[50:53]
	v_mfma_f32_16x16x32_bf16 v[38:41], v[150:153], v[214:217], v[38:41]
	v_mfma_f32_16x16x32_bf16 v[34:37], v[158:161], v[214:217], v[34:37]
	s_setprio 0
	s_barrier
	s_add_i32 s72, s72, s45
	v_lshl_add_u64 v[202:203], s[70:71], 0, v[0:1]
	s_mov_b32 m0, s72
	ds_read_b128 v[162:165], v209 offset:16384
	ds_read_b128 v[166:169], v209 offset:17408
	ds_read_b128 v[170:173], v209 offset:18432
	ds_read_b128 v[186:189], v209 offset:19456
	ds_read_b128 v[192:195], v209 offset:20480
	ds_read_b128 v[196:199], v209 offset:21504
	ds_read_b128 v[210:213], v209 offset:22528
	ds_read_b128 v[214:217], v209 offset:23552
	global_load_lds_dwordx4 v[202:203], off
	s_add_i32 m0, s72, 0x2000
	v_lshl_add_u64 v[206:207], s[70:71], 0, v[174:175]
	s_add_u32 s70, s70, s84
	s_addc_u32 s71, s71, 0
	s_add_i32 s72, s73, s45
	global_load_lds_dwordx4 v[206:207], off
	v_lshl_add_u64 v[218:219], s[70:71], 0, v[0:1]
	s_mov_b32 m0, s72
	v_lshl_add_u64 v[220:221], s[70:71], 0, v[174:175]
	global_load_lds_dwordx4 v[218:219], off
	s_add_i32 m0, s72, 0x2000
	v_lshl_add_u64 v[224:225], s[38:39], 0, v[178:179]
	global_load_lds_dwordx4 v[220:221], off
	s_mov_b32 m0, s23
	v_lshl_add_u64 v[226:227], s[38:39], 0, v[176:177]
	global_load_lds_dwordx4 v[224:225], off
	s_mov_b32 m0, s51
	s_nop 0
	global_load_lds_dwordx4 v[226:227], off
	s_waitcnt vmcnt(8)
	s_waitcnt lgkmcnt(0)
	s_barrier
	s_setprio 1
	s_waitcnt lgkmcnt(0)
	v_mfma_f32_16x16x32_bf16 v[94:97], v[130:133], v[162:165], v[94:97]
	v_mfma_f32_16x16x32_bf16 v[90:93], v[138:141], v[162:165], v[90:93]
	v_mfma_f32_16x16x32_bf16 v[86:89], v[130:133], v[170:173], v[86:89]
	v_mfma_f32_16x16x32_bf16 v[78:81], v[138:141], v[170:173], v[78:81]
	v_mfma_f32_16x16x32_bf16 v[66:69], v[130:133], v[192:195], v[66:69]
	v_mfma_f32_16x16x32_bf16 v[58:61], v[138:141], v[192:195], v[58:61]
	v_mfma_f32_16x16x32_bf16 v[46:49], v[130:133], v[210:213], v[46:49]
	v_mfma_f32_16x16x32_bf16 v[42:45], v[138:141], v[210:213], v[42:45]
	v_mfma_f32_16x16x32_bf16 v[94:97], v[134:137], v[166:169], v[94:97]
	v_mfma_f32_16x16x32_bf16 v[90:93], v[142:145], v[166:169], v[90:93]
	v_mfma_f32_16x16x32_bf16 v[86:89], v[134:137], v[186:189], v[86:89]
	v_mfma_f32_16x16x32_bf16 v[78:81], v[142:145], v[186:189], v[78:81]
	v_mfma_f32_16x16x32_bf16 v[66:69], v[134:137], v[196:199], v[66:69]
	v_mfma_f32_16x16x32_bf16 v[58:61], v[142:145], v[196:199], v[58:61]
	v_mfma_f32_16x16x32_bf16 v[46:49], v[134:137], v[214:217], v[46:49]
	v_mfma_f32_16x16x32_bf16 v[42:45], v[142:145], v[214:217], v[42:45]
	s_setprio 0
	s_setprio 1
	v_mfma_f32_16x16x32_bf16 v[30:33], v[146:149], v[162:165], v[30:33]
	v_mfma_f32_16x16x32_bf16 v[26:29], v[154:157], v[162:165], v[26:29]
	v_mfma_f32_16x16x32_bf16 v[22:25], v[146:149], v[170:173], v[22:25]
	v_mfma_f32_16x16x32_bf16 v[18:21], v[154:157], v[170:173], v[18:21]
	v_mfma_f32_16x16x32_bf16 v[14:17], v[146:149], v[192:195], v[14:17]
	v_mfma_f32_16x16x32_bf16 v[10:13], v[154:157], v[192:195], v[10:13]
	v_mfma_f32_16x16x32_bf16 v[6:9], v[146:149], v[210:213], v[6:9]
	v_mfma_f32_16x16x32_bf16 v[2:5], v[154:157], v[210:213], v[2:5]
	v_mfma_f32_16x16x32_bf16 v[30:33], v[150:153], v[166:169], v[30:33]
	v_mfma_f32_16x16x32_bf16 v[26:29], v[158:161], v[166:169], v[26:29]
	v_mfma_f32_16x16x32_bf16 v[22:25], v[150:153], v[186:189], v[22:25]
	v_mfma_f32_16x16x32_bf16 v[18:21], v[158:161], v[186:189], v[18:21]
	v_mfma_f32_16x16x32_bf16 v[14:17], v[150:153], v[196:199], v[14:17]
	v_mfma_f32_16x16x32_bf16 v[10:13], v[158:161], v[196:199], v[10:13]
	v_mfma_f32_16x16x32_bf16 v[6:9], v[150:153], v[214:217], v[6:9]
	v_mfma_f32_16x16x32_bf16 v[2:5], v[158:161], v[214:217], v[2:5]
	s_setprio 0
	s_barrier
	s_add_i32 s70, 0, 0x18000
	s_add_i32 s71, 0, 0x1c000
	v_add_u32_e32 v142, s70, v201
	v_add_u32_e32 v158, s71, v201
	ds_read_b128 v[130:133], v142
	ds_read_b128 v[134:137], v142 offset:1024
	ds_read_b128 v[138:141], v142 offset:2048
	ds_read_b128 v[142:145], v142 offset:3072
	ds_read_b128 v[146:149], v158
	ds_read_b128 v[150:153], v158 offset:1024
	ds_read_b128 v[154:157], v158 offset:2048
	ds_read_b128 v[158:161], v158 offset:3072
	s_add_u32 s38, s38, s84
	s_addc_u32 s39, s39, 0
	s_mov_b32 m0, s52
	v_lshl_add_u64 v[232:233], s[38:39], 0, v[178:179]
	ds_read_b128 v[162:165], v209 offset:32768
	ds_read_b128 v[166:169], v209 offset:33792
	ds_read_b128 v[170:173], v209 offset:34816
	ds_read_b128 v[186:189], v209 offset:35840
	ds_read_b128 v[192:195], v209 offset:36864
	ds_read_b128 v[196:199], v209 offset:37888
	ds_read_b128 v[210:213], v209 offset:38912
	ds_read_b128 v[214:217], v209 offset:39936
	global_load_lds_dwordx4 v[232:233], off
	v_lshl_add_u64 v[232:233], s[38:39], 0, v[176:177]
	s_mov_b32 m0, s53
	s_nop 0
	global_load_lds_dwordx4 v[232:233], off
	s_waitcnt vmcnt(8)
	s_waitcnt lgkmcnt(0)
	s_barrier
	s_setprio 1
	s_waitcnt lgkmcnt(0)
	v_mfma_f32_16x16x32_bf16 v[126:129], v[130:133], v[162:165], v[126:129]
	v_mfma_f32_16x16x32_bf16 v[122:125], v[138:141], v[162:165], v[122:125]
	v_mfma_f32_16x16x32_bf16 v[118:121], v[130:133], v[170:173], v[118:121]
	v_mfma_f32_16x16x32_bf16 v[114:117], v[138:141], v[170:173], v[114:117]
	v_mfma_f32_16x16x32_bf16 v[110:113], v[130:133], v[192:195], v[110:113]
	v_mfma_f32_16x16x32_bf16 v[106:109], v[138:141], v[192:195], v[106:109]
	v_mfma_f32_16x16x32_bf16 v[102:105], v[130:133], v[210:213], v[102:105]
	v_mfma_f32_16x16x32_bf16 v[98:101], v[138:141], v[210:213], v[98:101]
	v_mfma_f32_16x16x32_bf16 v[126:129], v[134:137], v[166:169], v[126:129]
	v_mfma_f32_16x16x32_bf16 v[122:125], v[142:145], v[166:169], v[122:125]
	v_mfma_f32_16x16x32_bf16 v[118:121], v[134:137], v[186:189], v[118:121]
	v_mfma_f32_16x16x32_bf16 v[114:117], v[142:145], v[186:189], v[114:117]
	v_mfma_f32_16x16x32_bf16 v[110:113], v[134:137], v[196:199], v[110:113]
	v_mfma_f32_16x16x32_bf16 v[106:109], v[142:145], v[196:199], v[106:109]
	v_mfma_f32_16x16x32_bf16 v[102:105], v[134:137], v[214:217], v[102:105]
	v_mfma_f32_16x16x32_bf16 v[98:101], v[142:145], v[214:217], v[98:101]
	s_setprio 0
	s_setprio 1
	v_mfma_f32_16x16x32_bf16 v[82:85], v[146:149], v[162:165], v[82:85]
	v_mfma_f32_16x16x32_bf16 v[74:77], v[154:157], v[162:165], v[74:77]
	v_mfma_f32_16x16x32_bf16 v[70:73], v[146:149], v[170:173], v[70:73]
	v_mfma_f32_16x16x32_bf16 v[62:65], v[154:157], v[170:173], v[62:65]
	v_mfma_f32_16x16x32_bf16 v[54:57], v[146:149], v[192:195], v[54:57]
	v_mfma_f32_16x16x32_bf16 v[50:53], v[154:157], v[192:195], v[50:53]
	v_mfma_f32_16x16x32_bf16 v[38:41], v[146:149], v[210:213], v[38:41]
	v_mfma_f32_16x16x32_bf16 v[34:37], v[154:157], v[210:213], v[34:37]
	v_mfma_f32_16x16x32_bf16 v[82:85], v[150:153], v[166:169], v[82:85]
	v_mfma_f32_16x16x32_bf16 v[74:77], v[158:161], v[166:169], v[74:77]
	v_mfma_f32_16x16x32_bf16 v[70:73], v[150:153], v[186:189], v[70:73]
	v_mfma_f32_16x16x32_bf16 v[62:65], v[158:161], v[186:189], v[62:65]
	v_mfma_f32_16x16x32_bf16 v[54:57], v[150:153], v[196:199], v[54:57]
	v_mfma_f32_16x16x32_bf16 v[50:53], v[158:161], v[196:199], v[50:53]
	v_mfma_f32_16x16x32_bf16 v[38:41], v[150:153], v[214:217], v[38:41]
	v_mfma_f32_16x16x32_bf16 v[34:37], v[158:161], v[214:217], v[34:37]
	s_setprio 0
	s_barrier
	s_add_i32 s38, s70, s45
	v_lshl_add_u64 v[202:203], v[202:203], 0, s[86:87]
	s_mov_b32 m0, s38
	ds_read_b128 v[162:165], v209 offset:49152
	ds_read_b128 v[166:169], v209 offset:50176
	ds_read_b128 v[170:173], v209 offset:51200
	ds_read_b128 v[186:189], v209 offset:52224
	ds_read_b128 v[192:195], v209 offset:53248
	ds_read_b128 v[196:199], v209 offset:54272
	ds_read_b128 v[210:213], v209 offset:55296
	ds_read_b128 v[214:217], v209 offset:56320
	global_load_lds_dwordx4 v[202:203], off
	v_lshl_add_u64 v[202:203], v[206:207], 0, s[86:87]
	s_add_i32 m0, s38, 0x2000
	s_add_i32 s38, s71, s45
	global_load_lds_dwordx4 v[202:203], off
	v_lshl_add_u64 v[202:203], v[218:219], 0, s[86:87]
	s_mov_b32 m0, s38
	s_nop 0
	global_load_lds_dwordx4 v[202:203], off
	v_lshl_add_u64 v[202:203], v[220:221], 0, s[86:87]
	s_add_i32 m0, s38, 0x2000
	s_nop 0
	global_load_lds_dwordx4 v[202:203], off
	v_lshl_add_u64 v[202:203], v[224:225], 0, s[86:87]
	s_mov_b32 m0, s54
	s_nop 0
	global_load_lds_dwordx4 v[202:203], off
	v_lshl_add_u64 v[202:203], v[226:227], 0, s[86:87]
	s_mov_b32 m0, s55
	s_nop 0
	global_load_lds_dwordx4 v[202:203], off
	s_waitcnt vmcnt(8)
	s_waitcnt lgkmcnt(0)
	s_barrier
	s_setprio 1
	s_waitcnt lgkmcnt(0)
	v_mfma_f32_16x16x32_bf16 v[94:97], v[130:133], v[162:165], v[94:97]
	v_mfma_f32_16x16x32_bf16 v[90:93], v[138:141], v[162:165], v[90:93]
	v_mfma_f32_16x16x32_bf16 v[86:89], v[130:133], v[170:173], v[86:89]
	v_mfma_f32_16x16x32_bf16 v[78:81], v[138:141], v[170:173], v[78:81]
	v_mfma_f32_16x16x32_bf16 v[66:69], v[130:133], v[192:195], v[66:69]
	v_mfma_f32_16x16x32_bf16 v[58:61], v[138:141], v[192:195], v[58:61]
	v_mfma_f32_16x16x32_bf16 v[46:49], v[130:133], v[210:213], v[46:49]
	v_mfma_f32_16x16x32_bf16 v[42:45], v[138:141], v[210:213], v[42:45]
	v_mfma_f32_16x16x32_bf16 v[94:97], v[134:137], v[166:169], v[94:97]
	v_mfma_f32_16x16x32_bf16 v[90:93], v[142:145], v[166:169], v[90:93]
	v_mfma_f32_16x16x32_bf16 v[86:89], v[134:137], v[186:189], v[86:89]
	v_mfma_f32_16x16x32_bf16 v[78:81], v[142:145], v[186:189], v[78:81]
	v_mfma_f32_16x16x32_bf16 v[66:69], v[134:137], v[196:199], v[66:69]
	v_mfma_f32_16x16x32_bf16 v[58:61], v[142:145], v[196:199], v[58:61]
	v_mfma_f32_16x16x32_bf16 v[46:49], v[134:137], v[214:217], v[46:49]
	v_mfma_f32_16x16x32_bf16 v[42:45], v[142:145], v[214:217], v[42:45]
	s_setprio 0
	s_setprio 1
	v_mfma_f32_16x16x32_bf16 v[30:33], v[146:149], v[162:165], v[30:33]
	v_mfma_f32_16x16x32_bf16 v[26:29], v[154:157], v[162:165], v[26:29]
	v_mfma_f32_16x16x32_bf16 v[22:25], v[146:149], v[170:173], v[22:25]
	v_mfma_f32_16x16x32_bf16 v[18:21], v[154:157], v[170:173], v[18:21]
	v_mfma_f32_16x16x32_bf16 v[14:17], v[146:149], v[192:195], v[14:17]
	v_mfma_f32_16x16x32_bf16 v[10:13], v[154:157], v[192:195], v[10:13]
	v_mfma_f32_16x16x32_bf16 v[6:9], v[146:149], v[210:213], v[6:9]
	v_mfma_f32_16x16x32_bf16 v[2:5], v[154:157], v[210:213], v[2:5]
	v_mfma_f32_16x16x32_bf16 v[30:33], v[150:153], v[166:169], v[30:33]
	v_mfma_f32_16x16x32_bf16 v[26:29], v[158:161], v[166:169], v[26:29]
	v_mfma_f32_16x16x32_bf16 v[22:25], v[150:153], v[186:189], v[22:25]
	v_mfma_f32_16x16x32_bf16 v[18:21], v[158:161], v[186:189], v[18:21]
	v_mfma_f32_16x16x32_bf16 v[14:17], v[150:153], v[196:199], v[14:17]
	v_mfma_f32_16x16x32_bf16 v[10:13], v[158:161], v[196:199], v[10:13]
	v_mfma_f32_16x16x32_bf16 v[6:9], v[150:153], v[214:217], v[6:9]
	v_mfma_f32_16x16x32_bf16 v[2:5], v[158:161], v[214:217], v[2:5]
	s_setprio 0
	s_barrier
	s_add_u32 s36, s36, 0x100
	s_addc_u32 s37, s37, 0
	s_add_u32 s67, s67, 0x100
	s_addc_u32 s68, s68, 0
	s_cmp_ge_u32 s69, s59
	s_mov_b32 s38, s69
	s_cbranch_scc0 .LBB0_458
	s_and_b64 vcc, exec, s[18:19]
	s_cbranch_vccz .LBB0_461
	s_barrier

.LBB0_465:
	s_cmp_lg_u32 s40, 0
	s_cbranch_scc0 .LBB0_471
	v_lshlrev_b64 v[130:131], 6, v[194:195]
	v_lshl_add_u64 v[130:131], v[180:181], 0, v[130:131]
	global_load_dwordx4 v[130:133], v[130:131], off
	v_lshlrev_b64 v[134:135], 6, v[192:193]
	v_lshl_add_u64 v[134:135], v[180:181], 0, v[134:135]
	global_load_dwordx4 v[134:137], v[134:135], off
	v_lshlrev_b64 v[138:139], 6, v[188:189]
	v_lshl_add_u64 v[138:139], v[180:181], 0, v[138:139]
	global_load_dwordx4 v[138:141], v[138:139], off
	v_lshlrev_b64 v[142:143], 6, v[186:187]
	v_lshl_add_u64 v[142:143], v[180:181], 0, v[142:143]
	global_load_dwordx4 v[142:145], v[142:143], off
	v_add_u32_e32 v206, 0x80, v194
	v_ashrrev_i32_e32 v207, 31, v206
	v_lshlrev_b64 v[146:147], 6, v[206:207]
	v_lshl_add_u64 v[146:147], v[180:181], 0, v[146:147]
	global_load_dwordx4 v[146:149], v[146:147], off
	v_add_u32_e32 v202, 0x90, v194
	v_ashrrev_i32_e32 v203, 31, v202
	v_cmp_lt_i32_e32 vcc, v239, v244
	v_lshlrev_b64 v[150:151], 6, v[202:203]
	v_lshl_add_u64 v[150:151], v[180:181], 0, v[150:151]
	v_cndmask_b32_e32 v162, v234, v239, vcc
	v_cmp_lt_i32_e32 vcc, v240, v244
	v_lshlrev_b32_e32 v164, 2, v162
	global_load_dwordx4 v[150:153], v[150:151], off
	v_cndmask_b32_e32 v162, v234, v240, vcc
	v_lshlrev_b32_e32 v165, 2, v162
	v_add_u32_e32 v198, 0xa0, v194
	v_ashrrev_i32_e32 v199, 31, v198
	v_lshlrev_b64 v[154:155], 6, v[198:199]
	v_lshl_add_u64 v[154:155], v[180:181], 0, v[154:155]
	global_load_dwordx4 v[154:157], v[154:155], off
	v_add_u32_e32 v196, 0xb0, v194
	v_ashrrev_i32_e32 v197, 31, v196
	v_lshlrev_b64 v[158:159], 6, v[196:197]
	v_lshl_add_u64 v[158:159], v[180:181], 0, v[158:159]
	global_load_dwordx4 v[158:161], v[158:159], off
	v_lshl_or_b32 v210, s22, 7, v205
	v_ashrrev_i32_e32 v211, 31, v210
	v_mov_b32_e32 v240, v236
	v_mov_b32_e32 v239, v231
	v_mov_b32_e32 v231, v230
	v_mov_b32_e32 v230, v229
	v_mov_b32_e32 v229, v228
	v_mov_b32_e32 v228, v254
	v_mov_b32_e32 v254, v235
	v_mov_b32_e32 v235, v222
	v_mov_b32_e32 v222, v238
	v_mov_b32_e32 v238, v241
	v_mov_b32_e32 v241, v245
	v_mov_b32_e32 v245, v237
	s_waitcnt vmcnt(0)
	v_add_f32_e32 v130, v130, v131
	v_add_f32_e32 v132, v132, v133
	v_add_f32_e32 v134, v134, v135
	v_add_f32_e32 v136, v136, v137
	v_add_f32_e32 v138, v138, v139
	v_add_f32_e32 v140, v140, v141
	v_add_f32_e32 v142, v142, v143
	v_add_f32_e32 v144, v144, v145
	v_add_f32_e32 v146, v146, v147
	v_add_f32_e32 v148, v148, v149
	v_add_f32_e32 v150, v150, v151
	v_add_f32_e32 v152, v152, v153
	v_add_f32_e32 v154, v154, v155
	v_add_f32_e32 v156, v156, v157
	v_add_f32_e32 v158, v158, v159
	v_add_f32_e32 v160, v160, v161
	v_add_f32_e32 v130, v130, v132
	v_add_f32_e32 v134, v134, v136
	v_add_f32_e32 v138, v138, v140
	v_add_f32_e32 v142, v142, v144
	v_add_f32_e32 v146, v146, v148
	v_add_f32_e32 v150, v150, v152
	v_add_f32_e32 v154, v154, v156
	v_add_f32_e32 v158, v158, v160
	ds_bpermute_b32 v131, v164, v130
	ds_bpermute_b32 v135, v164, v134
	ds_bpermute_b32 v139, v164, v138
	ds_bpermute_b32 v143, v164, v142
	ds_bpermute_b32 v147, v164, v146
	ds_bpermute_b32 v151, v164, v150
	ds_bpermute_b32 v155, v164, v154
	ds_bpermute_b32 v159, v164, v158
	s_waitcnt lgkmcnt(7)
	v_add_f32_e32 v130, v130, v131
	ds_bpermute_b32 v131, v165, v130
	s_waitcnt lgkmcnt(7)
	v_add_f32_e32 v134, v134, v135
	ds_bpermute_b32 v135, v165, v134
	s_waitcnt lgkmcnt(7)
	v_add_f32_e32 v138, v138, v139
	ds_bpermute_b32 v139, v165, v138
	s_waitcnt lgkmcnt(7)
	v_add_f32_e32 v142, v142, v143
	ds_bpermute_b32 v143, v165, v142
	s_waitcnt lgkmcnt(7)
	v_add_f32_e32 v146, v146, v147
	ds_bpermute_b32 v147, v165, v146
	s_waitcnt lgkmcnt(7)
	v_add_f32_e32 v150, v150, v151
	ds_bpermute_b32 v151, v165, v150
	s_waitcnt lgkmcnt(7)
	v_add_f32_e32 v154, v154, v155
	ds_bpermute_b32 v155, v165, v154
	s_waitcnt lgkmcnt(7)
	v_add_f32_e32 v158, v158, v159
	ds_bpermute_b32 v159, v165, v158
	s_waitcnt lgkmcnt(7)
	v_add_f32_e32 v130, v130, v131
	s_waitcnt lgkmcnt(6)
	v_add_f32_e32 v134, v134, v135
	s_waitcnt lgkmcnt(5)
	v_add_f32_e32 v138, v138, v139
	s_waitcnt lgkmcnt(4)
	v_add_f32_e32 v142, v142, v143
	s_waitcnt lgkmcnt(3)
	v_add_f32_e32 v146, v146, v147
	s_waitcnt lgkmcnt(2)
	v_add_f32_e32 v150, v150, v151
	s_waitcnt lgkmcnt(1)
	v_add_f32_e32 v154, v154, v155
	s_waitcnt lgkmcnt(0)
	v_add_f32_e32 v158, v158, v159
	v_fmamk_f32 v130, v130, 0x3a800000, v223
	v_fmamk_f32 v134, v134, 0x3a800000, v223
	v_fmamk_f32 v138, v138, 0x3a800000, v223
	v_fmamk_f32 v142, v142, 0x3a800000, v223
	v_fmamk_f32 v146, v146, 0x3a800000, v223
	v_fmamk_f32 v150, v150, 0x3a800000, v223
	v_fmamk_f32 v154, v154, 0x3a800000, v223
	v_fmamk_f32 v158, v158, 0x3a800000, v223
	v_rsq_f32_e32 v216, v130
	v_rsq_f32_e32 v220, v134
	v_rsq_f32_e32 v218, v138
	v_rsq_f32_e32 v214, v142
	v_rsq_f32_e32 v212, v146
	v_rsq_f32_e32 v208, v150
	v_rsq_f32_e32 v204, v154
	v_rsq_f32_e32 v200, v158
	v_lshlrev_b64 v[146:147], 10, v[194:195]
	v_lshl_add_u64 v[146:147], v[146:147], 0, v[210:211]
	v_lshlrev_b64 v[146:147], 1, v[146:147]
	v_lshl_add_u64 v[148:149], s[12:13], 0, v[146:147]
	v_lshl_add_u64 v[146:147], s[14:15], 0, v[146:147]
	v_lshlrev_b64 v[130:131], 2, v[210:211]
	v_lshl_add_u64 v[132:133], s[16:17], 0, v[130:131]
	global_load_dwordx4 v[138:141], v[132:133], off offset:16
	global_load_dwordx4 v[142:145], v[132:133], off
	v_lshl_add_u64 v[134:135], s[20:21], 0, v[130:131]
	global_load_dwordx4 v[130:133], v[134:135], off offset:16
	s_nop 0
	global_load_dwordx4 v[134:137], v[134:135], off
	s_waitcnt vmcnt(3)
	v_pk_fma_f32 v[248:249], v[124:125], v[216:217], v[140:141] op_sel_hi:[1,0,1]
	global_load_dwordx4 v[166:169], v[148:149], off
	global_load_dwordx4 v[224:227], v[146:147], off
	v_lshlrev_b64 v[146:147], 10, v[192:193]
	v_lshl_add_u64 v[146:147], v[146:147], 0, v[210:211]
	v_lshlrev_b64 v[146:147], 1, v[146:147]
	v_lshl_add_u64 v[148:149], s[12:13], 0, v[146:147]
	global_load_dwordx4 v[170:173], v[148:149], off
	v_lshl_add_u64 v[146:147], s[14:15], 0, v[146:147]
	global_load_dwordx4 v[162:165], v[146:147], off
	v_lshlrev_b64 v[146:147], 10, v[188:189]
	v_lshl_add_u64 v[146:147], v[146:147], 0, v[210:211]
	v_lshlrev_b64 v[146:147], 1, v[146:147]
	v_lshl_add_u64 v[148:149], s[12:13], 0, v[146:147]
	global_load_dwordx4 v[158:161], v[148:149], off
	v_lshl_add_u64 v[146:147], s[14:15], 0, v[146:147]
	global_load_dwordx4 v[154:157], v[146:147], off
	s_waitcnt vmcnt(8)
	v_pk_fma_f32 v[232:233], v[126:127], v[216:217], v[142:143] op_sel_hi:[1,0,1]
	v_pk_fma_f32 v[242:243], v[128:129], v[216:217], v[144:145] op_sel_hi:[1,0,1]
	v_pk_mul_f32 v[232:233], v[232:233], s[90:91] op_sel_hi:[1,0]
	v_pk_mul_f32 v[242:243], v[242:243], s[90:91] op_sel_hi:[1,0]
	v_pk_mul_f32 v[248:249], v[248:249], s[90:91] op_sel_hi:[1,0]
	v_exp_f32_e32 v232, v232
	v_exp_f32_e32 v233, v233
	v_exp_f32_e32 v242, v242
	v_exp_f32_e32 v243, v243
	v_exp_f32_e32 v248, v248
	v_exp_f32_e32 v249, v249
	v_lshlrev_b64 v[146:147], 10, v[186:187]
	v_lshl_add_u64 v[146:147], v[146:147], 0, v[210:211]
	v_lshlrev_b64 v[146:147], 1, v[146:147]
	v_pk_add_f32 v[242:243], v[242:243], 1.0 op_sel_hi:[1,0]
	v_pk_add_f32 v[232:233], v[232:233], 1.0 op_sel_hi:[1,0]
	v_pk_add_f32 v[248:249], v[248:249], 1.0 op_sel_hi:[1,0]
	v_lshl_add_u64 v[148:149], s[12:13], 0, v[146:147]
	v_rcp_f32_e32 v232, v232
	v_rcp_f32_e32 v233, v233
	v_rcp_f32_e32 v242, v242
	v_rcp_f32_e32 v243, v243
	v_rcp_f32_e32 v248, v248
	v_rcp_f32_e32 v249, v249
	global_load_dwordx4 v[150:153], v[148:149], off
	v_pk_fma_f32 v[246:247], v[122:123], v[216:217], v[138:139] op_sel_hi:[1,0,1]
	v_lshl_add_u64 v[146:147], s[14:15], 0, v[146:147]
	v_pk_mul_f32 v[246:247], v[246:247], s[90:91] op_sel_hi:[1,0]
	global_load_dwordx4 v[146:149], v[146:147], off
	v_exp_f32_e32 v246, v246
	v_exp_f32_e32 v247, v247
	s_waitcnt vmcnt(7)
	v_lshlrev_b32_e32 v250, 16, v166
	v_and_b32_e32 v251, 0xffff0000, v166
	v_lshlrev_b32_e32 v166, 16, v167
	v_and_b32_e32 v167, 0xffff0000, v167
	v_lshlrev_b32_e32 v236, 16, v169
	v_and_b32_e32 v237, 0xffff0000, v169
	v_lshlrev_b32_e32 v252, 16, v168
	v_and_b32_e32 v253, 0xffff0000, v168
	v_pk_mul_f32 v[168:169], v[242:243], v[166:167]
	v_pk_mul_f32 v[166:167], v[232:233], v[250:251]
	v_pk_mul_f32 v[248:249], v[248:249], v[236:237]
	v_pk_fma_f32 v[232:233], v[82:83], v[216:217], v[134:135] op_sel_hi:[1,0,1]
	v_pk_fma_f32 v[236:237], v[84:85], v[216:217], v[136:137] op_sel_hi:[1,0,1]
	v_pk_fma_f32 v[242:243], v[74:75], v[216:217], v[130:131] op_sel_hi:[1,0,1]
	v_pk_fma_f32 v[216:217], v[76:77], v[216:217], v[132:133] op_sel_hi:[1,0,1]
	v_pk_mul_f32 v[236:237], v[236:237], s[90:91] op_sel_hi:[1,0]
	v_pk_mul_f32 v[232:233], v[232:233], s[90:91] op_sel_hi:[1,0]
	v_pk_mul_f32 v[216:217], v[216:217], s[90:91] op_sel_hi:[1,0]
	v_pk_mul_f32 v[242:243], v[242:243], s[90:91] op_sel_hi:[1,0]
	v_exp_f32_e32 v232, v232
	v_exp_f32_e32 v233, v233
	v_exp_f32_e32 v236, v236
	v_exp_f32_e32 v237, v237
	v_exp_f32_e32 v216, v216
	v_exp_f32_e32 v217, v217
	v_exp_f32_e32 v242, v242
	v_exp_f32_e32 v243, v243
	v_pk_add_f32 v[246:247], v[246:247], 1.0 op_sel_hi:[1,0]
	v_pk_add_f32 v[236:237], v[236:237], 1.0 op_sel_hi:[1,0]
	v_rcp_f32_e32 v246, v246
	v_rcp_f32_e32 v247, v247
	v_pk_add_f32 v[232:233], v[232:233], 1.0 op_sel_hi:[1,0]
	v_pk_add_f32 v[216:217], v[216:217], 1.0 op_sel_hi:[1,0]
	v_pk_add_f32 v[242:243], v[242:243], 1.0 op_sel_hi:[1,0]
	v_rcp_f32_e32 v232, v232
	v_rcp_f32_e32 v233, v233
	v_rcp_f32_e32 v236, v236
	v_rcp_f32_e32 v237, v237
	v_rcp_f32_e32 v216, v216
	v_rcp_f32_e32 v217, v217
	v_rcp_f32_e32 v242, v242
	v_rcp_f32_e32 v243, v243
	v_pk_mul_f32 v[246:247], v[246:247], v[252:253]
	s_waitcnt vmcnt(6)
	v_lshlrev_b32_e32 v250, 16, v224
	v_and_b32_e32 v251, 0xffff0000, v224
	v_lshlrev_b32_e32 v224, 16, v225
	v_and_b32_e32 v225, 0xffff0000, v225
	v_lshlrev_b32_e32 v252, 16, v226
	v_and_b32_e32 v253, 0xffff0000, v226
	v_lshlrev_b32_e32 v226, 16, v227
	v_and_b32_e32 v227, 0xffff0000, v227
	v_pk_fma_f32 v[168:169], v[236:237], v[224:225], v[168:169]
	v_pk_fma_f32 v[166:167], v[232:233], v[250:251], v[166:167]
	v_pk_fma_f32 v[216:217], v[216:217], v[226:227], v[248:249]
	v_pk_fma_f32 v[224:225], v[242:243], v[252:253], v[246:247]
	v_cvt_pk_bf16_f32 v166, v166, v167
	v_cvt_pk_bf16_f32 v167, v168, v169
	v_cvt_pk_bf16_f32 v169, v216, v217
	v_lshlrev_b64 v[216:217], 11, v[194:195]
	v_cvt_pk_bf16_f32 v168, v224, v225
	v_lshl_add_u64 v[224:225], s[12:13], 0, v[216:217]
	v_lshlrev_b64 v[216:217], 1, v[210:211]
	v_lshl_add_u64 v[224:225], v[224:225], 0, v[216:217]
	global_store_dwordx4 v[224:225], v[166:169], off
	v_pk_fma_f32 v[224:225], v[114:115], v[220:221], v[138:139] op_sel_hi:[1,0,1]
	v_pk_fma_f32 v[226:227], v[116:117], v[220:221], v[140:141] op_sel_hi:[1,0,1]
	v_pk_fma_f32 v[166:167], v[118:119], v[220:221], v[142:143] op_sel_hi:[1,0,1]
	v_pk_fma_f32 v[168:169], v[120:121], v[220:221], v[144:145] op_sel_hi:[1,0,1]
	v_pk_mul_f32 v[166:167], v[166:167], s[90:91] op_sel_hi:[1,0]
	v_pk_mul_f32 v[168:169], v[168:169], s[90:91] op_sel_hi:[1,0]
	v_pk_mul_f32 v[226:227], v[226:227], s[90:91] op_sel_hi:[1,0]
	v_pk_mul_f32 v[224:225], v[224:225], s[90:91] op_sel_hi:[1,0]
	v_exp_f32_e32 v166, v166
	v_exp_f32_e32 v167, v167
	v_exp_f32_e32 v168, v168
	v_exp_f32_e32 v169, v169
	v_exp_f32_e32 v224, v224
	v_exp_f32_e32 v225, v225
	v_exp_f32_e32 v226, v226
	v_exp_f32_e32 v227, v227
	v_pk_add_f32 v[168:169], v[168:169], 1.0 op_sel_hi:[1,0]
	v_pk_add_f32 v[166:167], v[166:167], 1.0 op_sel_hi:[1,0]
	v_pk_add_f32 v[224:225], v[224:225], 1.0 op_sel_hi:[1,0]
	v_pk_add_f32 v[226:227], v[226:227], 1.0 op_sel_hi:[1,0]
	v_rcp_f32_e32 v166, v166
	v_rcp_f32_e32 v167, v167
	v_rcp_f32_e32 v168, v168
	v_rcp_f32_e32 v169, v169
	v_rcp_f32_e32 v224, v224
	v_rcp_f32_e32 v225, v225
	v_rcp_f32_e32 v226, v226
	v_rcp_f32_e32 v227, v227
	s_waitcnt vmcnt(6)
	v_lshlrev_b32_e32 v232, 16, v170
	v_and_b32_e32 v233, 0xffff0000, v170
	v_lshlrev_b32_e32 v170, 16, v171
	v_and_b32_e32 v171, 0xffff0000, v171
	v_lshlrev_b32_e32 v236, 16, v172
	v_and_b32_e32 v237, 0xffff0000, v172
	v_lshlrev_b32_e32 v172, 16, v173
	v_and_b32_e32 v173, 0xffff0000, v173
	v_pk_mul_f32 v[168:169], v[168:169], v[170:171]
	v_pk_mul_f32 v[166:167], v[166:167], v[232:233]
	v_pk_mul_f32 v[172:173], v[226:227], v[172:173]
	v_pk_mul_f32 v[170:171], v[224:225], v[236:237]
	v_pk_fma_f32 v[224:225], v[70:71], v[220:221], v[134:135] op_sel_hi:[1,0,1]
	v_pk_fma_f32 v[226:227], v[72:73], v[220:221], v[136:137] op_sel_hi:[1,0,1]
	v_pk_fma_f32 v[232:233], v[62:63], v[220:221], v[130:131] op_sel_hi:[1,0,1]
	v_pk_fma_f32 v[220:221], v[64:65], v[220:221], v[132:133] op_sel_hi:[1,0,1]
	v_pk_mul_f32 v[226:227], v[226:227], s[90:91] op_sel_hi:[1,0]
	v_pk_mul_f32 v[224:225], v[224:225], s[90:91] op_sel_hi:[1,0]
	v_pk_mul_f32 v[220:221], v[220:221], s[90:91] op_sel_hi:[1,0]
	v_pk_mul_f32 v[232:233], v[232:233], s[90:91] op_sel_hi:[1,0]
	v_exp_f32_e32 v224, v224
	v_exp_f32_e32 v225, v225
	v_exp_f32_e32 v226, v226
	v_exp_f32_e32 v227, v227
	v_exp_f32_e32 v232, v232
	v_exp_f32_e32 v233, v233
	v_exp_f32_e32 v220, v220
	v_exp_f32_e32 v221, v221
	v_pk_add_f32 v[226:227], v[226:227], 1.0 op_sel_hi:[1,0]
	v_pk_add_f32 v[224:225], v[224:225], 1.0 op_sel_hi:[1,0]
	v_pk_add_f32 v[232:233], v[232:233], 1.0 op_sel_hi:[1,0]
	v_pk_add_f32 v[220:221], v[220:221], 1.0 op_sel_hi:[1,0]
	v_rcp_f32_e32 v224, v224
	v_rcp_f32_e32 v225, v225
	v_rcp_f32_e32 v226, v226
	v_rcp_f32_e32 v227, v227
	v_rcp_f32_e32 v232, v232
	v_rcp_f32_e32 v233, v233
	v_rcp_f32_e32 v220, v220
	v_rcp_f32_e32 v221, v221
	s_waitcnt vmcnt(5)
	v_lshlrev_b32_e32 v236, 16, v162
	v_and_b32_e32 v237, 0xffff0000, v162
	v_lshlrev_b32_e32 v162, 16, v163
	v_and_b32_e32 v163, 0xffff0000, v163
	v_lshlrev_b32_e32 v242, 16, v164
	v_and_b32_e32 v243, 0xffff0000, v164
	v_lshlrev_b32_e32 v164, 16, v165
	v_and_b32_e32 v165, 0xffff0000, v165
	v_pk_fma_f32 v[168:169], v[226:227], v[162:163], v[168:169]
	v_pk_fma_f32 v[162:163], v[224:225], v[236:237], v[166:167]
	v_pk_fma_f32 v[166:167], v[220:221], v[164:165], v[172:173]
	v_pk_fma_f32 v[164:165], v[232:233], v[242:243], v[170:171]
	v_cvt_pk_bf16_f32 v162, v162, v163
	v_cvt_pk_bf16_f32 v164, v164, v165
	v_cvt_pk_bf16_f32 v165, v166, v167
	v_lshlrev_b64 v[166:167], 11, v[192:193]
	v_lshl_add_u64 v[166:167], s[12:13], 0, v[166:167]
	v_cvt_pk_bf16_f32 v163, v168, v169
	v_lshl_add_u64 v[166:167], v[166:167], 0, v[216:217]
	global_store_dwordx4 v[166:167], v[162:165], off
	v_pk_fma_f32 v[166:167], v[106:107], v[218:219], v[138:139] op_sel_hi:[1,0,1]
	v_pk_fma_f32 v[168:169], v[108:109], v[218:219], v[140:141] op_sel_hi:[1,0,1]
	v_pk_fma_f32 v[162:163], v[110:111], v[218:219], v[142:143] op_sel_hi:[1,0,1]
	v_pk_fma_f32 v[164:165], v[112:113], v[218:219], v[144:145] op_sel_hi:[1,0,1]
	v_pk_mul_f32 v[162:163], v[162:163], s[90:91] op_sel_hi:[1,0]
	v_pk_mul_f32 v[164:165], v[164:165], s[90:91] op_sel_hi:[1,0]
	v_pk_mul_f32 v[168:169], v[168:169], s[90:91] op_sel_hi:[1,0]
	v_pk_mul_f32 v[166:167], v[166:167], s[90:91] op_sel_hi:[1,0]
	v_exp_f32_e32 v162, v162
	v_exp_f32_e32 v163, v163
	v_exp_f32_e32 v164, v164
	v_exp_f32_e32 v165, v165
	v_exp_f32_e32 v166, v166
	v_exp_f32_e32 v167, v167
	v_exp_f32_e32 v168, v168
	v_exp_f32_e32 v169, v169
	v_pk_add_f32 v[164:165], v[164:165], 1.0 op_sel_hi:[1,0]
	v_pk_add_f32 v[162:163], v[162:163], 1.0 op_sel_hi:[1,0]
	v_pk_add_f32 v[166:167], v[166:167], 1.0 op_sel_hi:[1,0]
	v_pk_add_f32 v[168:169], v[168:169], 1.0 op_sel_hi:[1,0]
	v_rcp_f32_e32 v162, v162
	v_rcp_f32_e32 v163, v163
	v_rcp_f32_e32 v164, v164
	v_rcp_f32_e32 v165, v165
	v_rcp_f32_e32 v166, v166
	v_rcp_f32_e32 v167, v167
	v_rcp_f32_e32 v168, v168
	v_rcp_f32_e32 v169, v169
	s_waitcnt vmcnt(5)
	v_lshlrev_b32_e32 v170, 16, v158
	v_and_b32_e32 v171, 0xffff0000, v158
	v_lshlrev_b32_e32 v158, 16, v159
	v_and_b32_e32 v159, 0xffff0000, v159
	v_lshlrev_b32_e32 v172, 16, v160
	v_and_b32_e32 v173, 0xffff0000, v160
	v_lshlrev_b32_e32 v220, 16, v161
	v_and_b32_e32 v221, 0xffff0000, v161
	v_pk_mul_f32 v[160:161], v[164:165], v[158:159]
	v_pk_mul_f32 v[158:159], v[162:163], v[170:171]
	v_pk_mul_f32 v[164:165], v[168:169], v[220:221]
	v_pk_mul_f32 v[162:163], v[166:167], v[172:173]
	v_pk_fma_f32 v[166:167], v[54:55], v[218:219], v[134:135] op_sel_hi:[1,0,1]
	v_pk_fma_f32 v[168:169], v[56:57], v[218:219], v[136:137] op_sel_hi:[1,0,1]
	v_pk_fma_f32 v[170:171], v[50:51], v[218:219], v[130:131] op_sel_hi:[1,0,1]
	v_pk_fma_f32 v[172:173], v[52:53], v[218:219], v[132:133] op_sel_hi:[1,0,1]
	v_pk_mul_f32 v[168:169], v[168:169], s[90:91] op_sel_hi:[1,0]
	v_pk_mul_f32 v[166:167], v[166:167], s[90:91] op_sel_hi:[1,0]
	v_pk_mul_f32 v[172:173], v[172:173], s[90:91] op_sel_hi:[1,0]
	v_pk_mul_f32 v[170:171], v[170:171], s[90:91] op_sel_hi:[1,0]
	v_exp_f32_e32 v166, v166
	v_exp_f32_e32 v167, v167
	v_exp_f32_e32 v168, v168
	v_exp_f32_e32 v169, v169
	v_exp_f32_e32 v170, v170
	v_exp_f32_e32 v171, v171
	v_exp_f32_e32 v172, v172
	v_exp_f32_e32 v173, v173
	v_pk_add_f32 v[168:169], v[168:169], 1.0 op_sel_hi:[1,0]
	v_pk_add_f32 v[166:167], v[166:167], 1.0 op_sel_hi:[1,0]
	v_pk_add_f32 v[170:171], v[170:171], 1.0 op_sel_hi:[1,0]
	v_pk_add_f32 v[172:173], v[172:173], 1.0 op_sel_hi:[1,0]
	v_rcp_f32_e32 v166, v166
	v_rcp_f32_e32 v167, v167
	v_rcp_f32_e32 v168, v168
	v_rcp_f32_e32 v169, v169
	v_rcp_f32_e32 v170, v170
	v_rcp_f32_e32 v171, v171
	v_rcp_f32_e32 v172, v172
	v_rcp_f32_e32 v173, v173
	s_waitcnt vmcnt(4)
	v_lshlrev_b32_e32 v218, 16, v154
	v_and_b32_e32 v219, 0xffff0000, v154
	v_lshlrev_b32_e32 v154, 16, v155
	v_and_b32_e32 v155, 0xffff0000, v155
	v_lshlrev_b32_e32 v220, 16, v156
	v_and_b32_e32 v221, 0xffff0000, v156
	v_lshlrev_b32_e32 v156, 16, v157
	v_and_b32_e32 v157, 0xffff0000, v157
	v_pk_fma_f32 v[160:161], v[168:169], v[154:155], v[160:161]
	v_pk_fma_f32 v[154:155], v[166:167], v[218:219], v[158:159]
	v_pk_fma_f32 v[158:159], v[172:173], v[156:157], v[164:165]
	v_pk_fma_f32 v[156:157], v[170:171], v[220:221], v[162:163]
	v_cvt_pk_bf16_f32 v154, v154, v155
	v_cvt_pk_bf16_f32 v156, v156, v157
	v_cvt_pk_bf16_f32 v157, v158, v159
	v_lshlrev_b64 v[158:159], 11, v[188:189]
	v_lshl_add_u64 v[158:159], s[12:13], 0, v[158:159]
	v_cvt_pk_bf16_f32 v155, v160, v161
	v_lshl_add_u64 v[158:159], v[158:159], 0, v[216:217]
	global_store_dwordx4 v[158:159], v[154:157], off
	v_pk_fma_f32 v[158:159], v[98:99], v[214:215], v[138:139] op_sel_hi:[1,0,1]
	v_pk_fma_f32 v[160:161], v[100:101], v[214:215], v[140:141] op_sel_hi:[1,0,1]
	v_pk_fma_f32 v[154:155], v[102:103], v[214:215], v[142:143] op_sel_hi:[1,0,1]
	v_pk_fma_f32 v[156:157], v[104:105], v[214:215], v[144:145] op_sel_hi:[1,0,1]
	v_pk_mul_f32 v[154:155], v[154:155], s[90:91] op_sel_hi:[1,0]
	v_pk_mul_f32 v[156:157], v[156:157], s[90:91] op_sel_hi:[1,0]
	v_pk_mul_f32 v[160:161], v[160:161], s[90:91] op_sel_hi:[1,0]
	v_pk_mul_f32 v[158:159], v[158:159], s[90:91] op_sel_hi:[1,0]
	v_exp_f32_e32 v154, v154
	v_exp_f32_e32 v155, v155
	v_exp_f32_e32 v156, v156
	v_exp_f32_e32 v157, v157
	v_exp_f32_e32 v158, v158
	v_exp_f32_e32 v159, v159
	v_exp_f32_e32 v160, v160
	v_exp_f32_e32 v161, v161
	v_pk_add_f32 v[156:157], v[156:157], 1.0 op_sel_hi:[1,0]
	v_pk_add_f32 v[154:155], v[154:155], 1.0 op_sel_hi:[1,0]
	v_pk_add_f32 v[158:159], v[158:159], 1.0 op_sel_hi:[1,0]
	v_pk_add_f32 v[160:161], v[160:161], 1.0 op_sel_hi:[1,0]
	v_rcp_f32_e32 v154, v154
	v_rcp_f32_e32 v155, v155
	v_rcp_f32_e32 v156, v156
	v_rcp_f32_e32 v157, v157
	v_rcp_f32_e32 v158, v158
	v_rcp_f32_e32 v159, v159
	v_rcp_f32_e32 v160, v160
	v_rcp_f32_e32 v161, v161
	s_waitcnt vmcnt(4)
	v_lshlrev_b32_e32 v162, 16, v150
	v_and_b32_e32 v163, 0xffff0000, v150
	v_lshlrev_b32_e32 v150, 16, v151
	v_and_b32_e32 v151, 0xffff0000, v151
	v_lshlrev_b32_e32 v164, 16, v152
	v_and_b32_e32 v165, 0xffff0000, v152
	v_lshlrev_b32_e32 v166, 16, v153
	v_and_b32_e32 v167, 0xffff0000, v153
	v_pk_mul_f32 v[152:153], v[156:157], v[150:151]
	v_pk_mul_f32 v[150:151], v[154:155], v[162:163]
	v_pk_mul_f32 v[156:157], v[160:161], v[166:167]
	v_pk_mul_f32 v[154:155], v[158:159], v[164:165]
	v_pk_fma_f32 v[158:159], v[38:39], v[214:215], v[134:135] op_sel_hi:[1,0,1]
	v_pk_fma_f32 v[160:161], v[40:41], v[214:215], v[136:137] op_sel_hi:[1,0,1]
	v_pk_fma_f32 v[162:163], v[34:35], v[214:215], v[130:131] op_sel_hi:[1,0,1]
	v_pk_fma_f32 v[164:165], v[36:37], v[214:215], v[132:133] op_sel_hi:[1,0,1]
	v_pk_mul_f32 v[160:161], v[160:161], s[90:91] op_sel_hi:[1,0]
	v_pk_mul_f32 v[158:159], v[158:159], s[90:91] op_sel_hi:[1,0]
	v_pk_mul_f32 v[164:165], v[164:165], s[90:91] op_sel_hi:[1,0]
	v_pk_mul_f32 v[162:163], v[162:163], s[90:91] op_sel_hi:[1,0]
	v_exp_f32_e32 v158, v158
	v_exp_f32_e32 v159, v159
	v_exp_f32_e32 v160, v160
	v_exp_f32_e32 v161, v161
	v_exp_f32_e32 v162, v162
	v_exp_f32_e32 v163, v163
	v_exp_f32_e32 v164, v164
	v_exp_f32_e32 v165, v165
	v_pk_add_f32 v[160:161], v[160:161], 1.0 op_sel_hi:[1,0]
	v_pk_add_f32 v[158:159], v[158:159], 1.0 op_sel_hi:[1,0]
	v_pk_add_f32 v[162:163], v[162:163], 1.0 op_sel_hi:[1,0]
	v_pk_add_f32 v[164:165], v[164:165], 1.0 op_sel_hi:[1,0]
	v_rcp_f32_e32 v158, v158
	v_rcp_f32_e32 v159, v159
	v_rcp_f32_e32 v160, v160
	v_rcp_f32_e32 v161, v161
	v_rcp_f32_e32 v162, v162
	v_rcp_f32_e32 v163, v163
	v_rcp_f32_e32 v164, v164
	v_rcp_f32_e32 v165, v165
	s_waitcnt vmcnt(3)
	v_lshlrev_b32_e32 v166, 16, v146
	v_and_b32_e32 v167, 0xffff0000, v146
	v_lshlrev_b32_e32 v146, 16, v147
	v_and_b32_e32 v147, 0xffff0000, v147
	v_lshlrev_b32_e32 v168, 16, v148
	v_and_b32_e32 v169, 0xffff0000, v148
	v_lshlrev_b32_e32 v148, 16, v149
	v_and_b32_e32 v149, 0xffff0000, v149
	v_pk_fma_f32 v[152:153], v[160:161], v[146:147], v[152:153]
	v_pk_fma_f32 v[146:147], v[158:159], v[166:167], v[150:151]
	v_pk_fma_f32 v[150:151], v[164:165], v[148:149], v[156:157]
	v_pk_fma_f32 v[148:149], v[162:163], v[168:169], v[154:155]
	v_cvt_pk_bf16_f32 v146, v146, v147
	v_cvt_pk_bf16_f32 v148, v148, v149
	v_cvt_pk_bf16_f32 v149, v150, v151
	v_lshlrev_b64 v[150:151], 11, v[186:187]
	v_lshl_add_u64 v[150:151], s[12:13], 0, v[150:151]
	v_cvt_pk_bf16_f32 v147, v152, v153
	v_lshl_add_u64 v[150:151], v[150:151], 0, v[216:217]
	global_store_dwordx4 v[150:151], v[146:149], off
	v_pk_fma_f32 v[214:215], v[96:97], v[212:213], v[144:145] op_sel_hi:[1,0,1]
	v_pk_fma_f32 v[224:225], v[90:91], v[212:213], v[138:139] op_sel_hi:[1,0,1]
	v_lshlrev_b64 v[146:147], 10, v[206:207]
	v_lshl_add_u64 v[146:147], v[146:147], 0, v[210:211]
	v_lshlrev_b64 v[146:147], 1, v[146:147]
	v_lshl_add_u64 v[148:149], s[12:13], 0, v[146:147]
	global_load_dwordx4 v[170:173], v[148:149], off
	v_lshl_add_u64 v[146:147], s[14:15], 0, v[146:147]
	global_load_dwordx4 v[218:221], v[146:147], off
	v_lshlrev_b64 v[146:147], 10, v[202:203]
	v_lshl_add_u64 v[146:147], v[146:147], 0, v[210:211]
	v_lshlrev_b64 v[146:147], 1, v[146:147]
	v_lshl_add_u64 v[148:149], s[12:13], 0, v[146:147]
	global_load_dwordx4 v[166:169], v[148:149], off
	v_lshl_add_u64 v[146:147], s[14:15], 0, v[146:147]
	global_load_dwordx4 v[162:165], v[146:147], off
	v_lshlrev_b64 v[146:147], 10, v[198:199]
	v_lshl_add_u64 v[146:147], v[146:147], 0, v[210:211]
	v_lshlrev_b64 v[146:147], 1, v[146:147]
	v_lshl_add_u64 v[148:149], s[12:13], 0, v[146:147]
	global_load_dwordx4 v[158:161], v[148:149], off
	v_lshl_add_u64 v[146:147], s[14:15], 0, v[146:147]
	global_load_dwordx4 v[154:157], v[146:147], off
	v_lshlrev_b64 v[146:147], 10, v[196:197]
	v_lshl_add_u64 v[146:147], v[146:147], 0, v[210:211]
	v_lshlrev_b64 v[146:147], 1, v[146:147]
	v_lshl_add_u64 v[148:149], s[12:13], 0, v[146:147]
	global_load_dwordx4 v[150:153], v[148:149], off
	v_lshl_add_u64 v[146:147], s[14:15], 0, v[146:147]
	global_load_dwordx4 v[146:149], v[146:147], off
	v_pk_fma_f32 v[210:211], v[94:95], v[212:213], v[142:143] op_sel_hi:[1,0,1]
	v_pk_mul_f32 v[214:215], v[214:215], s[90:91] op_sel_hi:[1,0]
	v_pk_mul_f32 v[210:211], v[210:211], s[90:91] op_sel_hi:[1,0]
	v_exp_f32_e32 v214, v214
	v_exp_f32_e32 v210, v210
	v_exp_f32_e32 v211, v211
	v_exp_f32_e32 v215, v215
	v_pk_fma_f32 v[226:227], v[92:93], v[212:213], v[140:141] op_sel_hi:[1,0,1]
	v_pk_mul_f32 v[224:225], v[224:225], s[90:91] op_sel_hi:[1,0]
	v_pk_add_f32 v[210:211], v[210:211], 1.0 op_sel_hi:[1,0]
	v_pk_add_f32 v[214:215], v[214:215], 1.0 op_sel_hi:[1,0]
	v_rcp_f32_e32 v210, v210
	v_rcp_f32_e32 v211, v211
	v_rcp_f32_e32 v214, v214
	v_rcp_f32_e32 v215, v215
	v_pk_mul_f32 v[226:227], v[226:227], s[90:91] op_sel_hi:[1,0]
	v_exp_f32_e32 v224, v224
	v_exp_f32_e32 v225, v225
	v_exp_f32_e32 v226, v226
	v_exp_f32_e32 v227, v227
	v_pk_add_f32 v[224:225], v[224:225], 1.0 op_sel_hi:[1,0]
	v_lshlrev_b64 v[206:207], 11, v[206:207]
	v_pk_add_f32 v[226:227], v[226:227], 1.0 op_sel_hi:[1,0]
	v_rcp_f32_e32 v224, v224
	v_rcp_f32_e32 v225, v225
	v_rcp_f32_e32 v226, v226
	v_rcp_f32_e32 v227, v227
	v_lshl_add_u64 v[206:207], s[12:13], 0, v[206:207]
	v_lshl_add_u64 v[206:207], v[206:207], 0, v[216:217]
	s_waitcnt vmcnt(7)
	v_lshlrev_b32_e32 v232, 16, v170
	v_and_b32_e32 v233, 0xffff0000, v170
	v_lshlrev_b32_e32 v170, 16, v171
	v_and_b32_e32 v171, 0xffff0000, v171
	v_lshlrev_b32_e32 v236, 16, v172
	v_and_b32_e32 v237, 0xffff0000, v172
	v_lshlrev_b32_e32 v242, 16, v173
	v_and_b32_e32 v243, 0xffff0000, v173
	v_pk_mul_f32 v[172:173], v[214:215], v[170:171]
	v_pk_mul_f32 v[170:171], v[210:211], v[232:233]
	v_pk_fma_f32 v[210:211], v[30:31], v[212:213], v[134:135] op_sel_hi:[1,0,1]
	v_pk_fma_f32 v[214:215], v[32:33], v[212:213], v[136:137] op_sel_hi:[1,0,1]
	v_pk_fma_f32 v[232:233], v[26:27], v[212:213], v[130:131] op_sel_hi:[1,0,1]
	v_pk_fma_f32 v[212:213], v[28:29], v[212:213], v[132:133] op_sel_hi:[1,0,1]
	v_pk_mul_f32 v[214:215], v[214:215], s[90:91] op_sel_hi:[1,0]
	v_pk_mul_f32 v[210:211], v[210:211], s[90:91] op_sel_hi:[1,0]
	v_pk_mul_f32 v[212:213], v[212:213], s[90:91] op_sel_hi:[1,0]
	v_pk_mul_f32 v[232:233], v[232:233], s[90:91] op_sel_hi:[1,0]
	v_exp_f32_e32 v210, v210
	v_exp_f32_e32 v211, v211
	v_exp_f32_e32 v214, v214
	v_exp_f32_e32 v215, v215
	v_exp_f32_e32 v232, v232
	v_exp_f32_e32 v233, v233
	v_exp_f32_e32 v212, v212
	v_exp_f32_e32 v213, v213
	v_pk_add_f32 v[214:215], v[214:215], 1.0 op_sel_hi:[1,0]
	v_pk_add_f32 v[210:211], v[210:211], 1.0 op_sel_hi:[1,0]
	v_pk_add_f32 v[232:233], v[232:233], 1.0 op_sel_hi:[1,0]
	v_pk_add_f32 v[212:213], v[212:213], 1.0 op_sel_hi:[1,0]
	v_rcp_f32_e32 v210, v210
	v_rcp_f32_e32 v211, v211
	v_rcp_f32_e32 v214, v214
	v_rcp_f32_e32 v215, v215
	v_rcp_f32_e32 v232, v232
	v_rcp_f32_e32 v233, v233
	v_rcp_f32_e32 v212, v212
	v_rcp_f32_e32 v213, v213
	v_pk_mul_f32 v[226:227], v[226:227], v[242:243]
	v_pk_mul_f32 v[224:225], v[224:225], v[236:237]
	s_waitcnt vmcnt(6)
	v_lshlrev_b32_e32 v236, 16, v218
	v_and_b32_e32 v237, 0xffff0000, v218
	v_lshlrev_b32_e32 v218, 16, v219
	v_and_b32_e32 v219, 0xffff0000, v219
	v_lshlrev_b32_e32 v242, 16, v220
	v_and_b32_e32 v243, 0xffff0000, v220
	v_lshlrev_b32_e32 v220, 16, v221
	v_and_b32_e32 v221, 0xffff0000, v221
	v_pk_fma_f32 v[172:173], v[214:215], v[218:219], v[172:173]
	v_pk_fma_f32 v[170:171], v[210:211], v[236:237], v[170:171]
	v_pk_fma_f32 v[210:211], v[212:213], v[220:221], v[226:227]
	v_pk_fma_f32 v[212:213], v[232:233], v[242:243], v[224:225]
	v_cvt_pk_bf16_f32 v170, v170, v171
	v_cvt_pk_bf16_f32 v171, v172, v173
	v_cvt_pk_bf16_f32 v172, v212, v213
	v_cvt_pk_bf16_f32 v173, v210, v211
	global_store_dwordx4 v[206:207], v[170:173], off
	v_pk_fma_f32 v[206:207], v[78:79], v[208:209], v[138:139] op_sel_hi:[1,0,1]
	v_pk_fma_f32 v[210:211], v[80:81], v[208:209], v[140:141] op_sel_hi:[1,0,1]
	v_pk_fma_f32 v[170:171], v[86:87], v[208:209], v[142:143] op_sel_hi:[1,0,1]
	v_pk_fma_f32 v[172:173], v[88:89], v[208:209], v[144:145] op_sel_hi:[1,0,1]
	v_pk_mul_f32 v[170:171], v[170:171], s[90:91] op_sel_hi:[1,0]
	v_pk_mul_f32 v[172:173], v[172:173], s[90:91] op_sel_hi:[1,0]
	v_pk_mul_f32 v[210:211], v[210:211], s[90:91] op_sel_hi:[1,0]
	v_pk_mul_f32 v[206:207], v[206:207], s[90:91] op_sel_hi:[1,0]
	v_exp_f32_e32 v170, v170
	v_exp_f32_e32 v171, v171
	v_exp_f32_e32 v172, v172
	v_exp_f32_e32 v173, v173
	v_exp_f32_e32 v206, v206
	v_exp_f32_e32 v207, v207
	v_exp_f32_e32 v210, v210
	v_exp_f32_e32 v211, v211
	v_pk_add_f32 v[172:173], v[172:173], 1.0 op_sel_hi:[1,0]
	v_pk_add_f32 v[170:171], v[170:171], 1.0 op_sel_hi:[1,0]
	v_pk_add_f32 v[206:207], v[206:207], 1.0 op_sel_hi:[1,0]
	v_pk_add_f32 v[210:211], v[210:211], 1.0 op_sel_hi:[1,0]
	v_rcp_f32_e32 v170, v170
	v_rcp_f32_e32 v171, v171
	v_rcp_f32_e32 v172, v172
	v_rcp_f32_e32 v173, v173
	v_rcp_f32_e32 v206, v206
	v_rcp_f32_e32 v207, v207
	v_rcp_f32_e32 v210, v210
	v_rcp_f32_e32 v211, v211
	s_waitcnt vmcnt(6)
	v_lshlrev_b32_e32 v212, 16, v166
	v_and_b32_e32 v213, 0xffff0000, v166
	v_lshlrev_b32_e32 v166, 16, v167
	v_and_b32_e32 v167, 0xffff0000, v167
	v_lshlrev_b32_e32 v214, 16, v168
	v_and_b32_e32 v215, 0xffff0000, v168
	v_lshlrev_b32_e32 v218, 16, v169
	v_and_b32_e32 v219, 0xffff0000, v169
	v_pk_mul_f32 v[168:169], v[172:173], v[166:167]
	v_pk_mul_f32 v[166:167], v[170:171], v[212:213]
	v_pk_mul_f32 v[172:173], v[210:211], v[218:219]
	v_pk_mul_f32 v[170:171], v[206:207], v[214:215]
	v_pk_fma_f32 v[206:207], v[22:23], v[208:209], v[134:135] op_sel_hi:[1,0,1]
	v_pk_fma_f32 v[210:211], v[24:25], v[208:209], v[136:137] op_sel_hi:[1,0,1]
	v_pk_fma_f32 v[212:213], v[18:19], v[208:209], v[130:131] op_sel_hi:[1,0,1]
	v_pk_fma_f32 v[214:215], v[20:21], v[208:209], v[132:133] op_sel_hi:[1,0,1]
	v_pk_mul_f32 v[210:211], v[210:211], s[90:91] op_sel_hi:[1,0]
	v_pk_mul_f32 v[206:207], v[206:207], s[90:91] op_sel_hi:[1,0]
	v_pk_mul_f32 v[214:215], v[214:215], s[90:91] op_sel_hi:[1,0]
	v_pk_mul_f32 v[212:213], v[212:213], s[90:91] op_sel_hi:[1,0]
	v_exp_f32_e32 v206, v206
	v_exp_f32_e32 v207, v207
	v_exp_f32_e32 v210, v210
	v_exp_f32_e32 v211, v211
	v_exp_f32_e32 v212, v212
	v_exp_f32_e32 v213, v213
	v_exp_f32_e32 v214, v214
	v_exp_f32_e32 v215, v215
	v_pk_add_f32 v[210:211], v[210:211], 1.0 op_sel_hi:[1,0]
	v_pk_add_f32 v[206:207], v[206:207], 1.0 op_sel_hi:[1,0]
	v_pk_add_f32 v[212:213], v[212:213], 1.0 op_sel_hi:[1,0]
	v_pk_add_f32 v[214:215], v[214:215], 1.0 op_sel_hi:[1,0]
	v_rcp_f32_e32 v206, v206
	v_rcp_f32_e32 v207, v207
	v_rcp_f32_e32 v210, v210
	v_rcp_f32_e32 v211, v211
	v_rcp_f32_e32 v212, v212
	v_rcp_f32_e32 v213, v213
	v_rcp_f32_e32 v214, v214
	v_rcp_f32_e32 v215, v215
	s_waitcnt vmcnt(5)
	v_lshlrev_b32_e32 v218, 16, v162
	v_and_b32_e32 v219, 0xffff0000, v162
	v_lshlrev_b32_e32 v162, 16, v163
	v_and_b32_e32 v163, 0xffff0000, v163
	v_lshlrev_b32_e32 v220, 16, v164
	v_and_b32_e32 v221, 0xffff0000, v164
	v_lshlrev_b32_e32 v164, 16, v165
	v_and_b32_e32 v165, 0xffff0000, v165
	v_pk_fma_f32 v[168:169], v[210:211], v[162:163], v[168:169]
	v_pk_fma_f32 v[162:163], v[206:207], v[218:219], v[166:167]
	v_pk_fma_f32 v[166:167], v[214:215], v[164:165], v[172:173]
	v_pk_fma_f32 v[164:165], v[212:213], v[220:221], v[170:171]
	v_cvt_pk_bf16_f32 v162, v162, v163
	v_cvt_pk_bf16_f32 v164, v164, v165
	v_cvt_pk_bf16_f32 v165, v166, v167
	v_lshlrev_b64 v[166:167], 11, v[202:203]
	v_lshl_add_u64 v[166:167], s[12:13], 0, v[166:167]
	v_cvt_pk_bf16_f32 v163, v168, v169
	v_lshl_add_u64 v[166:167], v[166:167], 0, v[216:217]
	global_store_dwordx4 v[166:167], v[162:165], off
	v_pk_fma_f32 v[166:167], v[58:59], v[204:205], v[138:139] op_sel_hi:[1,0,1]
	v_pk_fma_f32 v[168:169], v[60:61], v[204:205], v[140:141] op_sel_hi:[1,0,1]
	v_pk_fma_f32 v[162:163], v[66:67], v[204:205], v[142:143] op_sel_hi:[1,0,1]
	v_pk_fma_f32 v[164:165], v[68:69], v[204:205], v[144:145] op_sel_hi:[1,0,1]
	v_pk_mul_f32 v[162:163], v[162:163], s[90:91] op_sel_hi:[1,0]
	v_pk_mul_f32 v[164:165], v[164:165], s[90:91] op_sel_hi:[1,0]
	v_pk_mul_f32 v[168:169], v[168:169], s[90:91] op_sel_hi:[1,0]
	v_pk_mul_f32 v[166:167], v[166:167], s[90:91] op_sel_hi:[1,0]
	v_exp_f32_e32 v162, v162
	v_exp_f32_e32 v163, v163
	v_exp_f32_e32 v164, v164
	v_exp_f32_e32 v165, v165
	v_exp_f32_e32 v166, v166
	v_exp_f32_e32 v167, v167
	v_exp_f32_e32 v168, v168
	v_exp_f32_e32 v169, v169
	v_pk_add_f32 v[164:165], v[164:165], 1.0 op_sel_hi:[1,0]
	v_pk_add_f32 v[162:163], v[162:163], 1.0 op_sel_hi:[1,0]
	v_pk_add_f32 v[166:167], v[166:167], 1.0 op_sel_hi:[1,0]
	v_pk_add_f32 v[168:169], v[168:169], 1.0 op_sel_hi:[1,0]
	v_rcp_f32_e32 v162, v162
	v_rcp_f32_e32 v163, v163
	v_rcp_f32_e32 v164, v164
	v_rcp_f32_e32 v165, v165
	v_rcp_f32_e32 v166, v166
	v_rcp_f32_e32 v167, v167
	v_rcp_f32_e32 v168, v168
	v_rcp_f32_e32 v169, v169
	s_waitcnt vmcnt(5)
	v_lshlrev_b32_e32 v170, 16, v158
	v_and_b32_e32 v171, 0xffff0000, v158
	v_lshlrev_b32_e32 v158, 16, v159
	v_and_b32_e32 v159, 0xffff0000, v159
	v_lshlrev_b32_e32 v172, 16, v160
	v_and_b32_e32 v173, 0xffff0000, v160
	v_lshlrev_b32_e32 v202, 16, v161
	v_and_b32_e32 v203, 0xffff0000, v161
	v_pk_mul_f32 v[160:161], v[164:165], v[158:159]
	v_pk_mul_f32 v[158:159], v[162:163], v[170:171]
	v_pk_mul_f32 v[164:165], v[168:169], v[202:203]
	v_pk_mul_f32 v[162:163], v[166:167], v[172:173]
	v_pk_fma_f32 v[166:167], v[14:15], v[204:205], v[134:135] op_sel_hi:[1,0,1]
	v_pk_fma_f32 v[168:169], v[16:17], v[204:205], v[136:137] op_sel_hi:[1,0,1]
	v_pk_fma_f32 v[170:171], v[10:11], v[204:205], v[130:131] op_sel_hi:[1,0,1]
	v_pk_fma_f32 v[172:173], v[12:13], v[204:205], v[132:133] op_sel_hi:[1,0,1]
	v_pk_mul_f32 v[168:169], v[168:169], s[90:91] op_sel_hi:[1,0]
	v_pk_mul_f32 v[166:167], v[166:167], s[90:91] op_sel_hi:[1,0]
	v_pk_mul_f32 v[172:173], v[172:173], s[90:91] op_sel_hi:[1,0]
	v_pk_mul_f32 v[170:171], v[170:171], s[90:91] op_sel_hi:[1,0]
	v_exp_f32_e32 v166, v166
	v_exp_f32_e32 v167, v167
	v_exp_f32_e32 v168, v168
	v_exp_f32_e32 v169, v169
	v_exp_f32_e32 v170, v170
	v_exp_f32_e32 v171, v171
	v_exp_f32_e32 v172, v172
	v_exp_f32_e32 v173, v173
	v_pk_add_f32 v[168:169], v[168:169], 1.0 op_sel_hi:[1,0]
	v_pk_add_f32 v[166:167], v[166:167], 1.0 op_sel_hi:[1,0]
	v_pk_add_f32 v[170:171], v[170:171], 1.0 op_sel_hi:[1,0]
	v_pk_add_f32 v[172:173], v[172:173], 1.0 op_sel_hi:[1,0]
	v_rcp_f32_e32 v166, v166
	v_rcp_f32_e32 v167, v167
	v_rcp_f32_e32 v168, v168
	v_rcp_f32_e32 v169, v169
	v_rcp_f32_e32 v170, v170
	v_rcp_f32_e32 v171, v171
	v_rcp_f32_e32 v172, v172
	v_rcp_f32_e32 v173, v173
	v_pk_fma_f32 v[142:143], v[46:47], v[200:201], v[142:143] op_sel_hi:[1,0,1]
	v_pk_fma_f32 v[144:145], v[48:49], v[200:201], v[144:145] op_sel_hi:[1,0,1]
	v_pk_fma_f32 v[138:139], v[42:43], v[200:201], v[138:139] op_sel_hi:[1,0,1]
	v_pk_fma_f32 v[140:141], v[44:45], v[200:201], v[140:141] op_sel_hi:[1,0,1]
	v_pk_mul_f32 v[144:145], v[144:145], s[90:91] op_sel_hi:[1,0]
	v_pk_mul_f32 v[142:143], v[142:143], s[90:91] op_sel_hi:[1,0]
	v_pk_mul_f32 v[140:141], v[140:141], s[90:91] op_sel_hi:[1,0]
	v_pk_mul_f32 v[138:139], v[138:139], s[90:91] op_sel_hi:[1,0]
	v_pk_fma_f32 v[134:135], v[6:7], v[200:201], v[134:135] op_sel_hi:[1,0,1]
	s_waitcnt vmcnt(4)
	v_lshlrev_b32_e32 v202, 16, v154
	v_and_b32_e32 v203, 0xffff0000, v154
	v_lshlrev_b32_e32 v154, 16, v155
	v_and_b32_e32 v155, 0xffff0000, v155
	v_lshlrev_b32_e32 v206, 16, v156
	v_and_b32_e32 v207, 0xffff0000, v156
	v_lshlrev_b32_e32 v156, 16, v157
	v_and_b32_e32 v157, 0xffff0000, v157
	v_exp_f32_e32 v142, v142
	v_exp_f32_e32 v143, v143
	v_exp_f32_e32 v144, v144
	v_exp_f32_e32 v145, v145
	v_exp_f32_e32 v138, v138
	v_exp_f32_e32 v139, v139
	v_exp_f32_e32 v140, v140
	v_exp_f32_e32 v141, v141
	v_pk_fma_f32 v[130:131], v[2:3], v[200:201], v[130:131] op_sel_hi:[1,0,1]
	v_pk_fma_f32 v[132:133], v[4:5], v[200:201], v[132:133] op_sel_hi:[1,0,1]
	v_pk_mul_f32 v[134:135], v[134:135], s[90:91] op_sel_hi:[1,0]
	v_pk_fma_f32 v[160:161], v[168:169], v[154:155], v[160:161]
	v_pk_fma_f32 v[154:155], v[166:167], v[202:203], v[158:159]
	v_pk_fma_f32 v[158:159], v[172:173], v[156:157], v[164:165]
	v_pk_fma_f32 v[156:157], v[170:171], v[206:207], v[162:163]
	v_pk_fma_f32 v[136:137], v[8:9], v[200:201], v[136:137] op_sel_hi:[1,0,1]
	v_pk_mul_f32 v[132:133], v[132:133], s[90:91] op_sel_hi:[1,0]
	v_pk_mul_f32 v[130:131], v[130:131], s[90:91] op_sel_hi:[1,0]
	v_exp_f32_e32 v134, v134
	v_exp_f32_e32 v135, v135
	v_cvt_pk_bf16_f32 v156, v156, v157
	v_cvt_pk_bf16_f32 v157, v158, v159
	v_lshlrev_b64 v[158:159], 11, v[198:199]
	v_pk_mul_f32 v[136:137], v[136:137], s[90:91] op_sel_hi:[1,0]
	v_exp_f32_e32 v130, v130
	v_exp_f32_e32 v131, v131
	v_exp_f32_e32 v132, v132
	v_exp_f32_e32 v133, v133
	v_lshl_add_u64 v[158:159], s[12:13], 0, v[158:159]
	v_exp_f32_e32 v136, v136
	v_exp_f32_e32 v137, v137
	v_cvt_pk_bf16_f32 v154, v154, v155
	v_cvt_pk_bf16_f32 v155, v160, v161
	v_lshl_add_u64 v[158:159], v[158:159], 0, v[216:217]
	v_pk_add_f32 v[144:145], v[144:145], 1.0 op_sel_hi:[1,0]
	v_pk_add_f32 v[142:143], v[142:143], 1.0 op_sel_hi:[1,0]
	v_pk_add_f32 v[140:141], v[140:141], 1.0 op_sel_hi:[1,0]
	v_pk_add_f32 v[138:139], v[138:139], 1.0 op_sel_hi:[1,0]
	global_store_dwordx4 v[158:159], v[154:157], off
	v_rcp_f32_e32 v142, v142
	v_rcp_f32_e32 v143, v143
	v_rcp_f32_e32 v144, v144
	v_rcp_f32_e32 v145, v145
	v_rcp_f32_e32 v154, v138
	v_rcp_f32_e32 v155, v139
	v_rcp_f32_e32 v156, v140
	v_rcp_f32_e32 v157, v141
	v_pk_add_f32 v[134:135], v[134:135], 1.0 op_sel_hi:[1,0]
	v_pk_add_f32 v[132:133], v[132:133], 1.0 op_sel_hi:[1,0]
	v_pk_add_f32 v[130:131], v[130:131], 1.0 op_sel_hi:[1,0]
	v_rcp_f32_e32 v134, v134
	v_rcp_f32_e32 v135, v135
	v_pk_add_f32 v[136:137], v[136:137], 1.0 op_sel_hi:[1,0]
	v_rcp_f32_e32 v130, v130
	v_rcp_f32_e32 v131, v131
	v_rcp_f32_e32 v132, v132
	v_rcp_f32_e32 v133, v133
	s_waitcnt vmcnt(4)
	v_lshlrev_b32_e32 v138, 16, v150
	v_and_b32_e32 v139, 0xffff0000, v150
	v_lshlrev_b32_e32 v140, 16, v151
	v_and_b32_e32 v141, 0xffff0000, v151
	v_lshlrev_b32_e32 v150, 16, v152
	v_and_b32_e32 v151, 0xffff0000, v152
	v_lshlrev_b32_e32 v152, 16, v153
	v_and_b32_e32 v153, 0xffff0000, v153
	v_rcp_f32_e32 v136, v136
	v_rcp_f32_e32 v137, v137
	v_pk_mul_f32 v[140:141], v[144:145], v[140:141]
	v_pk_mul_f32 v[138:139], v[142:143], v[138:139]
	v_pk_mul_f32 v[144:145], v[156:157], v[152:153]
	v_pk_mul_f32 v[142:143], v[154:155], v[150:151]
	s_waitcnt vmcnt(3)
	v_lshlrev_b32_e32 v150, 16, v146
	v_and_b32_e32 v151, 0xffff0000, v146
	v_lshlrev_b32_e32 v152, 16, v148
	v_and_b32_e32 v153, 0xffff0000, v148
	v_lshlrev_b32_e32 v148, 16, v149
	v_and_b32_e32 v149, 0xffff0000, v149
	v_pk_fma_f32 v[134:135], v[134:135], v[150:151], v[138:139]
	v_lshlrev_b32_e32 v146, 16, v147
	v_and_b32_e32 v147, 0xffff0000, v147
	v_pk_fma_f32 v[138:139], v[132:133], v[148:149], v[144:145]
	v_pk_fma_f32 v[132:133], v[130:131], v[152:153], v[142:143]
	v_cvt_pk_bf16_f32 v130, v134, v135
	v_lshlrev_b64 v[134:135], 11, v[196:197]
	v_pk_fma_f32 v[136:137], v[136:137], v[146:147], v[140:141]
	v_lshl_add_u64 v[134:135], s[12:13], 0, v[134:135]
	v_cvt_pk_bf16_f32 v131, v136, v137
	v_cvt_pk_bf16_f32 v132, v132, v133
	v_cvt_pk_bf16_f32 v133, v138, v139
	v_lshl_add_u64 v[134:135], v[134:135], 0, v[216:217]
	global_store_dwordx4 v[134:135], v[130:133], off
	v_mov_b32_e32 v236, v240
	v_mov_b32_e32 v237, v245
	v_mov_b32_e32 v245, v241
	v_mov_b32_e32 v241, v238
	v_mov_b32_e32 v238, v222
	v_mov_b32_e32 v222, v235
	v_mov_b32_e32 v235, v254
	v_mov_b32_e32 v254, v228
	v_mov_b32_e32 v228, v229
	v_mov_b32_e32 v229, v230
	v_mov_b32_e32 v230, v231
	v_mov_b32_e32 v231, v239
	s_cbranch_execnz .LBB0_468
